# speedup vs baseline: 1.0399x; 1.0121x over previous
; DEV u16 f2bf(float f) { return (u16)(pk2bf(f, 0.f) & 0xffffu); }
; DEV float bf2f(u16 h) { return __uint_as_float(((unsigned)h) << 16); }
; DEV float siluf_(float x) { return x / (1.0f + __expf(-x)); }
; template <int MI>
; DEV void tile_load_t(unsigned char* smem, const u16* src, size_t lds_) {
;   u16* sC = (u16*)smem;
;   const int tid_ = TIDX();
; #pragma unroll
;   for (int i = 0; i < MI * 4; ++i) {
;     const int c = tid_ + 256 * i, row = c >> 4, cc = (c & 15) * 8;
;     *(bf16x8*)(sC + row * LDC + cc) = __builtin_nontemporal_load((const bf16x8*)(src + (size_t)row * lds_ + cc));
;   }
;   __syncthreads();
; }
; template <int MI>
; DEV void p4_tile(const Params& p, int l, int m0, int nt, unsigned char* smem) {
;     ...
;     tile_load_t<MI>(smem, Q + (size_t)m0 * 1536 + nt * 192, 1536);
;     acc_foreach_t<MI>([&](int mi, int ni, int r, int row, int col) __attribute__((always_inline)) {
;       sC[row * LDC + col] = f2bf(bf2f(sC[row * LDC + col]) * siluf_(acc[mi][ni][r]));
;     });
.LBB0_1211:
	s_mul_hi_i32 s1, s0, 0xc00
	s_mulk_i32 s0, 0xc00
	s_add_u32 s0, s19, s0
	s_addc_u32 s1, s36, s1
	s_mul_i32 s6, s37, 0x180
	s_waitcnt vmcnt(8)
	v_mov_b32_e32 v136, v232
	s_barrier
	s_add_u32 s0, s0, s6
	s_addc_u32 s1, s1, 0
	v_lshlrev_b32_e32 v128, 4, v136
	v_and_b32_e32 v224, 0xf0, v128
	v_lshl_add_u64 v[128:129], s[0:1], 0, v[224:225]
	v_ashrrev_i32_e32 v134, 4, v136
	v_mad_i64_i32 v[204:205], s[0:1], v134, s41, v[128:129]
	v_mad_u64_u32 v[206:207], s[0:1], v134, s42, v[224:225]
	s_lshl_b32 s0, s41, 4
	s_mov_b32 s1, 0
	global_load_dwordx4 v[140:143], v[204:205], off nt
	v_lshl_add_u64 v[204:205], v[204:205], 0, s[0:1]
	global_load_dwordx4 v[144:147], v[204:205], off nt
	v_lshl_add_u64 v[204:205], v[204:205], 0, s[0:1]
	global_load_dwordx4 v[148:151], v[204:205], off nt
	v_lshl_add_u64 v[204:205], v[204:205], 0, s[0:1]
	global_load_dwordx4 v[152:155], v[204:205], off nt
	v_lshl_add_u64 v[204:205], v[204:205], 0, s[0:1]
	global_load_dwordx4 v[156:159], v[204:205], off nt
	v_lshl_add_u64 v[204:205], v[204:205], 0, s[0:1]
	global_load_dwordx4 v[160:163], v[204:205], off nt
	v_lshl_add_u64 v[204:205], v[204:205], 0, s[0:1]
	global_load_dwordx4 v[164:167], v[204:205], off nt
	v_lshl_add_u64 v[204:205], v[204:205], 0, s[0:1]
	global_load_dwordx4 v[168:171], v[204:205], off nt
	v_lshl_add_u64 v[204:205], v[204:205], 0, s[0:1]
	global_load_dwordx4 v[172:175], v[204:205], off nt
	v_lshl_add_u64 v[204:205], v[204:205], 0, s[0:1]
	global_load_dwordx4 v[176:179], v[204:205], off nt
	v_lshl_add_u64 v[204:205], v[204:205], 0, s[0:1]
	global_load_dwordx4 v[180:183], v[204:205], off nt
	v_lshl_add_u64 v[204:205], v[204:205], 0, s[0:1]
	global_load_dwordx4 v[184:187], v[204:205], off nt
	v_lshl_add_u64 v[204:205], v[204:205], 0, s[0:1]
	global_load_dwordx4 v[188:191], v[204:205], off nt
	v_lshl_add_u64 v[204:205], v[204:205], 0, s[0:1]
	global_load_dwordx4 v[192:195], v[204:205], off nt
	v_lshl_add_u64 v[204:205], v[204:205], 0, s[0:1]
	global_load_dwordx4 v[196:199], v[204:205], off nt
	v_lshl_add_u64 v[204:205], v[204:205], 0, s[0:1]
	global_load_dwordx4 v[200:203], v[204:205], off nt
	s_waitcnt vmcnt(15)
	ds_write_b128 v206, v[140:143]
	s_waitcnt vmcnt(14)
	ds_write_b128 v206, v[144:147] offset:4352
	s_waitcnt vmcnt(13)
	ds_write_b128 v206, v[148:151] offset:8704
	s_waitcnt vmcnt(12)
	ds_write_b128 v206, v[152:155] offset:13056
	s_waitcnt vmcnt(11)
	ds_write_b128 v206, v[156:159] offset:17408
	s_waitcnt vmcnt(10)
	ds_write_b128 v206, v[160:163] offset:21760
	s_waitcnt vmcnt(9)
	ds_write_b128 v206, v[164:167] offset:26112
	s_waitcnt vmcnt(8)
	ds_write_b128 v206, v[168:171] offset:30464
	s_waitcnt vmcnt(7)
	ds_write_b128 v206, v[172:175] offset:34816
	s_waitcnt vmcnt(6)
	ds_write_b128 v206, v[176:179] offset:39168
	s_waitcnt vmcnt(5)
	ds_write_b128 v206, v[180:183] offset:43520
	s_waitcnt vmcnt(4)
	ds_write_b128 v206, v[184:187] offset:47872
	s_waitcnt vmcnt(3)
	ds_write_b128 v206, v[188:191] offset:52224
	s_waitcnt vmcnt(2)
	ds_write_b128 v206, v[192:195] offset:56576
	s_waitcnt vmcnt(1)
	ds_write_b128 v206, v[196:199] offset:60928
	s_waitcnt vmcnt(0)
	ds_write_b128 v206, v[200:203] offset:65280
	v_mov_b32_e32 v128, v232
	s_waitcnt lgkmcnt(0)
	s_barrier
	s_nop 0
	v_and_b32_e32 v129, 0xfffff80, v128
	v_lshrrev_b32_e32 v130, 3, v128
	v_and_or_b32 v129, v130, 4, v129
	v_mul_f32_e32 v130, 0xbfb8aa3b, v112
	v_exp_f32_e32 v130, v130
	v_and_b32_e32 v128, 0x5f, v128
	v_mul_lo_u32 v129, v129, s42
	v_lshl_add_u32 v128, v128, 1, v129
	v_add_f32_e32 v130, 1.0, v130
	ds_read_u16 v129, v128
	s_waitcnt lgkmcnt(0)
	v_lshlrev_b32_e32 v129, 16, v129
	v_rcp_f32_e32 v131, v130
	s_nop 0
	v_mul_f32_e32 v112, v112, v131
	v_mul_f32_e32 v112, v112, v129
	v_mul_f32_e32 v129, 0xbfb8aa3b, v113
	v_exp_f32_e32 v129, v129
	v_cvt_pk_bf16_f32 v112, v112, s0
	ds_write_b16 v128, v112
	ds_read_u16 v112, v128 offset:272
	v_add_f32_e32 v129, 1.0, v129
	s_waitcnt lgkmcnt(0)
	v_lshlrev_b32_e32 v112, 16, v112
	v_rcp_f32_e32 v130, v129
	s_nop 0
	v_mul_f32_e32 v113, v113, v130
	v_mul_f32_e32 v112, v113, v112
	v_mul_f32_e32 v113, 0xbfb8aa3b, v114
	v_exp_f32_e32 v113, v113
	v_cvt_pk_bf16_f32 v112, v112, s0
	ds_write_b16 v128, v112 offset:272
	ds_read_u16 v112, v128 offset:544
	v_add_f32_e32 v113, 1.0, v113
	s_waitcnt lgkmcnt(0)
	v_lshlrev_b32_e32 v112, 16, v112
	v_rcp_f32_e32 v129, v113
	s_nop 0
	v_mul_f32_e32 v113, v114, v129
	v_mul_f32_e32 v112, v113, v112
	v_mul_f32_e32 v113, 0xbfb8aa3b, v115
	v_exp_f32_e32 v113, v113
	v_cvt_pk_bf16_f32 v112, v112, s0
	ds_write_b16 v128, v112 offset:544
	ds_read_u16 v112, v128 offset:816
	v_add_f32_e32 v113, 1.0, v113
	s_waitcnt lgkmcnt(0)
	v_lshlrev_b32_e32 v112, 16, v112
	v_rcp_f32_e32 v114, v113
	s_nop 0
	v_mul_f32_e32 v113, v115, v114
	v_mul_f32_e32 v112, v113, v112
	v_mul_f32_e32 v113, 0xbfb8aa3b, v116
	v_exp_f32_e32 v113, v113
	v_cvt_pk_bf16_f32 v112, v112, s0
	ds_write_b16 v128, v112 offset:816
	ds_read_u16 v112, v128 offset:2176
	v_add_f32_e32 v113, 1.0, v113
	s_waitcnt lgkmcnt(0)
	v_lshlrev_b32_e32 v112, 16, v112
	v_rcp_f32_e32 v114, v113
	s_nop 0
	v_mul_f32_e32 v113, v116, v114
	v_mul_f32_e32 v112, v113, v112
	v_mul_f32_e32 v113, 0xbfb8aa3b, v117
	v_exp_f32_e32 v113, v113
	v_cvt_pk_bf16_f32 v112, v112, s0
	ds_write_b16 v128, v112 offset:2176
	ds_read_u16 v112, v128 offset:2448
	v_add_f32_e32 v113, 1.0, v113
	s_waitcnt lgkmcnt(0)
	v_lshlrev_b32_e32 v112, 16, v112
	v_rcp_f32_e32 v114, v113
	s_nop 0
	v_mul_f32_e32 v113, v117, v114
	v_mul_f32_e32 v112, v113, v112
	v_mul_f32_e32 v113, 0xbfb8aa3b, v118
	v_exp_f32_e32 v113, v113
	v_cvt_pk_bf16_f32 v112, v112, s0
	ds_write_b16 v128, v112 offset:2448
	ds_read_u16 v112, v128 offset:2720
	v_add_f32_e32 v113, 1.0, v113
	s_waitcnt lgkmcnt(0)
; DEV u16 f2bf(float f) { return (u16)(pk2bf(f, 0.f) & 0xffffu); }
; DEV float bf2f(u16 h) { return __uint_as_float(((unsigned)h) << 16); }
; DEV float siluf_(float x) { return x / (1.0f + __expf(-x)); }
; template <int MI>
; DEV void p4_tile(const Params& p, int l, int m0, int nt, unsigned char* smem) {
;     ...
;     acc_foreach_t<MI>([&](int mi, int ni, int r, int row, int col) __attribute__((always_inline)) {
;       sC[row * LDC + col] = f2bf(bf2f(sC[row * LDC + col]) * siluf_(acc[mi][ni][r]));
;     });
	v_lshlrev_b32_e32 v112, 16, v112
	v_rcp_f32_e32 v114, v113
	s_nop 0
	v_mul_f32_e32 v113, v118, v114
	v_mul_f32_e32 v112, v113, v112
	v_mul_f32_e32 v113, 0xbfb8aa3b, v119
	v_exp_f32_e32 v113, v113
	v_cvt_pk_bf16_f32 v112, v112, s0
	ds_write_b16 v128, v112 offset:2720
	ds_read_u16 v112, v128 offset:2992
	v_add_f32_e32 v113, 1.0, v113
	s_waitcnt lgkmcnt(0)
	v_lshlrev_b32_e32 v112, 16, v112
	v_rcp_f32_e32 v114, v113
	s_nop 0
	v_mul_f32_e32 v113, v119, v114
	v_mul_f32_e32 v112, v113, v112
	v_mul_f32_e32 v113, 0xbfb8aa3b, v120
	v_exp_f32_e32 v113, v113
	v_cvt_pk_bf16_f32 v112, v112, s0
	ds_write_b16 v128, v112 offset:2992
	ds_read_u16 v112, v128 offset:4352
	v_add_f32_e32 v113, 1.0, v113
	s_waitcnt lgkmcnt(0)
	v_lshlrev_b32_e32 v112, 16, v112
	v_rcp_f32_e32 v114, v113
	s_nop 0
	v_mul_f32_e32 v113, v120, v114
	v_mul_f32_e32 v112, v113, v112
	v_mul_f32_e32 v113, 0xbfb8aa3b, v121
	v_exp_f32_e32 v113, v113
	v_cvt_pk_bf16_f32 v112, v112, s0
	ds_write_b16 v128, v112 offset:4352
	ds_read_u16 v112, v128 offset:4624
	v_add_f32_e32 v113, 1.0, v113
	s_waitcnt lgkmcnt(0)
	v_lshlrev_b32_e32 v112, 16, v112
	v_rcp_f32_e32 v114, v113
	s_nop 0
	v_mul_f32_e32 v113, v121, v114
	v_mul_f32_e32 v112, v113, v112
	v_mul_f32_e32 v113, 0xbfb8aa3b, v122
	v_exp_f32_e32 v113, v113
	v_cvt_pk_bf16_f32 v112, v112, s0
	ds_write_b16 v128, v112 offset:4624
	ds_read_u16 v112, v128 offset:4896
	v_add_f32_e32 v113, 1.0, v113
	s_waitcnt lgkmcnt(0)
	v_lshlrev_b32_e32 v112, 16, v112
	v_rcp_f32_e32 v114, v113
	s_nop 0
	v_mul_f32_e32 v113, v122, v114
	v_mul_f32_e32 v112, v113, v112
	v_mul_f32_e32 v113, 0xbfb8aa3b, v123
	v_exp_f32_e32 v113, v113
	v_cvt_pk_bf16_f32 v112, v112, s0
	ds_write_b16 v128, v112 offset:4896
	ds_read_u16 v112, v128 offset:5168
	v_add_f32_e32 v113, 1.0, v113
	s_waitcnt lgkmcnt(0)
	v_lshlrev_b32_e32 v112, 16, v112
	v_rcp_f32_e32 v114, v113
	s_nop 0
	v_mul_f32_e32 v113, v123, v114
	v_mul_f32_e32 v112, v113, v112
	v_mul_f32_e32 v113, 0xbfb8aa3b, v124
	v_exp_f32_e32 v113, v113
	v_cvt_pk_bf16_f32 v112, v112, s0
	ds_write_b16 v128, v112 offset:5168
	ds_read_u16 v112, v128 offset:6528
	v_add_f32_e32 v113, 1.0, v113
	s_waitcnt lgkmcnt(0)
	v_lshlrev_b32_e32 v112, 16, v112
	v_rcp_f32_e32 v114, v113
	s_nop 0
	v_mul_f32_e32 v113, v124, v114
	v_mul_f32_e32 v112, v113, v112
	v_mul_f32_e32 v113, 0xbfb8aa3b, v125
	v_exp_f32_e32 v113, v113
	v_cvt_pk_bf16_f32 v112, v112, s0
	ds_write_b16 v128, v112 offset:6528
	ds_read_u16 v112, v128 offset:6800
	v_add_f32_e32 v113, 1.0, v113
	s_waitcnt lgkmcnt(0)
	v_lshlrev_b32_e32 v112, 16, v112
	v_rcp_f32_e32 v114, v113
	s_nop 0
	v_mul_f32_e32 v113, v125, v114
	v_mul_f32_e32 v112, v113, v112
	v_mul_f32_e32 v113, 0xbfb8aa3b, v126
	v_exp_f32_e32 v113, v113
	v_cvt_pk_bf16_f32 v112, v112, s0
	ds_write_b16 v128, v112 offset:6800
	ds_read_u16 v112, v128 offset:7072
	v_add_f32_e32 v113, 1.0, v113
	s_waitcnt lgkmcnt(0)
	v_lshlrev_b32_e32 v112, 16, v112
	v_rcp_f32_e32 v114, v113
	s_nop 0
	v_mul_f32_e32 v113, v126, v114
	v_mul_f32_e32 v112, v113, v112
	v_mul_f32_e32 v113, 0xbfb8aa3b, v127
	v_exp_f32_e32 v113, v113
	v_cvt_pk_bf16_f32 v112, v112, s0
	ds_write_b16 v128, v112 offset:7072
	ds_read_u16 v112, v128 offset:7344
	v_add_f32_e32 v113, 1.0, v113
	s_waitcnt lgkmcnt(0)
	v_lshlrev_b32_e32 v112, 16, v112
	v_rcp_f32_e32 v114, v113
	s_nop 0
	v_mul_f32_e32 v113, v127, v114
	v_mul_f32_e32 v112, v113, v112
	v_mul_f32_e32 v113, 0xbfb8aa3b, v96
	v_exp_f32_e32 v113, v113
	v_cvt_pk_bf16_f32 v112, v112, s0
	ds_write_b16 v128, v112 offset:7344
	ds_read_u16 v112, v128 offset:64
	v_add_f32_e32 v113, 1.0, v113
	s_waitcnt lgkmcnt(0)
	v_lshlrev_b32_e32 v112, 16, v112
	v_rcp_f32_e32 v114, v113
	s_nop 0
	v_mul_f32_e32 v96, v96, v114
	v_mul_f32_e32 v96, v96, v112
	v_mul_f32_e32 v112, 0xbfb8aa3b, v97
	v_exp_f32_e32 v112, v112
	v_cvt_pk_bf16_f32 v96, v96, s0
	ds_write_b16 v128, v96 offset:64
	ds_read_u16 v96, v128 offset:336
	v_add_f32_e32 v112, 1.0, v112
	s_waitcnt lgkmcnt(0)
	v_lshlrev_b32_e32 v96, 16, v96
	v_rcp_f32_e32 v113, v112
	s_nop 0
	v_mul_f32_e32 v97, v97, v113
	v_mul_f32_e32 v96, v97, v96
	v_mul_f32_e32 v97, 0xbfb8aa3b, v98
	v_exp_f32_e32 v97, v97
	v_cvt_pk_bf16_f32 v96, v96, s0
	ds_write_b16 v128, v96 offset:336
	ds_read_u16 v96, v128 offset:608
	v_add_f32_e32 v97, 1.0, v97
	s_waitcnt lgkmcnt(0)
	v_lshlrev_b32_e32 v96, 16, v96
	v_rcp_f32_e32 v112, v97
	s_nop 0
	v_mul_f32_e32 v97, v98, v112
	v_mul_f32_e32 v96, v97, v96
	v_mul_f32_e32 v97, 0xbfb8aa3b, v99
	v_exp_f32_e32 v97, v97
	v_cvt_pk_bf16_f32 v96, v96, s0
	ds_write_b16 v128, v96 offset:608
	ds_read_u16 v96, v128 offset:880
	v_add_f32_e32 v97, 1.0, v97
	s_waitcnt lgkmcnt(0)
	v_lshlrev_b32_e32 v96, 16, v96
	v_rcp_f32_e32 v98, v97
	s_nop 0
	v_mul_f32_e32 v97, v99, v98
	v_mul_f32_e32 v96, v97, v96
	v_mul_f32_e32 v97, 0xbfb8aa3b, v100
	v_exp_f32_e32 v97, v97
	v_cvt_pk_bf16_f32 v96, v96, s0
	ds_write_b16 v128, v96 offset:880
	ds_read_u16 v96, v128 offset:2240
	v_add_f32_e32 v97, 1.0, v97
	s_waitcnt lgkmcnt(0)
	v_lshlrev_b32_e32 v96, 16, v96
	v_rcp_f32_e32 v98, v97
	s_nop 0
	v_mul_f32_e32 v97, v100, v98
	v_mul_f32_e32 v96, v97, v96
	v_mul_f32_e32 v97, 0xbfb8aa3b, v101
	v_exp_f32_e32 v97, v97
	v_cvt_pk_bf16_f32 v96, v96, s0
	ds_write_b16 v128, v96 offset:2240
	ds_read_u16 v96, v128 offset:2512
	v_add_f32_e32 v97, 1.0, v97
	s_waitcnt lgkmcnt(0)
	v_lshlrev_b32_e32 v96, 16, v96
	v_rcp_f32_e32 v98, v97
	s_nop 0
	v_mul_f32_e32 v97, v101, v98
	v_mul_f32_e32 v96, v97, v96
	v_mul_f32_e32 v97, 0xbfb8aa3b, v102
	v_exp_f32_e32 v97, v97
	v_cvt_pk_bf16_f32 v96, v96, s0
	ds_write_b16 v128, v96 offset:2512
	ds_read_u16 v96, v128 offset:2784
	v_add_f32_e32 v97, 1.0, v97
	s_waitcnt lgkmcnt(0)
; DEV u16 f2bf(float f) { return (u16)(pk2bf(f, 0.f) & 0xffffu); }
; DEV float bf2f(u16 h) { return __uint_as_float(((unsigned)h) << 16); }
; DEV float siluf_(float x) { return x / (1.0f + __expf(-x)); }
; template <int MI>
; DEV void p4_tile(const Params& p, int l, int m0, int nt, unsigned char* smem) {
;     ...
;     acc_foreach_t<MI>([&](int mi, int ni, int r, int row, int col) __attribute__((always_inline)) {
;       sC[row * LDC + col] = f2bf(bf2f(sC[row * LDC + col]) * siluf_(acc[mi][ni][r]));
;     });
	v_lshlrev_b32_e32 v96, 16, v96
	v_rcp_f32_e32 v98, v97
	s_nop 0
	v_mul_f32_e32 v97, v102, v98
	v_mul_f32_e32 v96, v97, v96
	v_mul_f32_e32 v97, 0xbfb8aa3b, v103
	v_exp_f32_e32 v97, v97
	v_cvt_pk_bf16_f32 v96, v96, s0
	ds_write_b16 v128, v96 offset:2784
	ds_read_u16 v96, v128 offset:3056
	v_add_f32_e32 v97, 1.0, v97
	s_waitcnt lgkmcnt(0)
	v_lshlrev_b32_e32 v96, 16, v96
	v_rcp_f32_e32 v98, v97
	s_nop 0
	v_mul_f32_e32 v97, v103, v98
	v_mul_f32_e32 v96, v97, v96
	v_mul_f32_e32 v97, 0xbfb8aa3b, v104
	v_exp_f32_e32 v97, v97
	v_cvt_pk_bf16_f32 v96, v96, s0
	ds_write_b16 v128, v96 offset:3056
	ds_read_u16 v96, v128 offset:4416
	v_add_f32_e32 v97, 1.0, v97
	s_waitcnt lgkmcnt(0)
	v_lshlrev_b32_e32 v96, 16, v96
	v_rcp_f32_e32 v98, v97
	s_nop 0
	v_mul_f32_e32 v97, v104, v98
	v_mul_f32_e32 v96, v97, v96
	v_mul_f32_e32 v97, 0xbfb8aa3b, v105
	v_exp_f32_e32 v97, v97
	v_cvt_pk_bf16_f32 v96, v96, s0
	ds_write_b16 v128, v96 offset:4416
	ds_read_u16 v96, v128 offset:4688
	v_add_f32_e32 v97, 1.0, v97
	s_waitcnt lgkmcnt(0)
	v_lshlrev_b32_e32 v96, 16, v96
	v_rcp_f32_e32 v98, v97
	s_nop 0
	v_mul_f32_e32 v97, v105, v98
	v_mul_f32_e32 v96, v97, v96
	v_mul_f32_e32 v97, 0xbfb8aa3b, v106
	v_exp_f32_e32 v97, v97
	v_cvt_pk_bf16_f32 v96, v96, s0
	ds_write_b16 v128, v96 offset:4688
	ds_read_u16 v96, v128 offset:4960
	v_add_f32_e32 v97, 1.0, v97
	s_waitcnt lgkmcnt(0)
	v_lshlrev_b32_e32 v96, 16, v96
	v_rcp_f32_e32 v98, v97
	s_nop 0
	v_mul_f32_e32 v97, v106, v98
	v_mul_f32_e32 v96, v97, v96
	v_mul_f32_e32 v97, 0xbfb8aa3b, v107
	v_exp_f32_e32 v97, v97
	v_cvt_pk_bf16_f32 v96, v96, s0
	ds_write_b16 v128, v96 offset:4960
	ds_read_u16 v96, v128 offset:5232
	v_add_f32_e32 v97, 1.0, v97
	s_waitcnt lgkmcnt(0)
	v_lshlrev_b32_e32 v96, 16, v96
	v_rcp_f32_e32 v98, v97
	s_nop 0
	v_mul_f32_e32 v97, v107, v98
	v_mul_f32_e32 v96, v97, v96
	v_mul_f32_e32 v97, 0xbfb8aa3b, v108
	v_exp_f32_e32 v97, v97
	v_cvt_pk_bf16_f32 v96, v96, s0
	ds_write_b16 v128, v96 offset:5232
	ds_read_u16 v96, v128 offset:6592
	v_add_f32_e32 v97, 1.0, v97
	s_waitcnt lgkmcnt(0)
	v_lshlrev_b32_e32 v96, 16, v96
	v_rcp_f32_e32 v98, v97
	s_nop 0
	v_mul_f32_e32 v97, v108, v98
	v_mul_f32_e32 v96, v97, v96
	v_mul_f32_e32 v97, 0xbfb8aa3b, v109
	v_exp_f32_e32 v97, v97
	v_cvt_pk_bf16_f32 v96, v96, s0
	ds_write_b16 v128, v96 offset:6592
	ds_read_u16 v96, v128 offset:6864
	v_add_f32_e32 v97, 1.0, v97
	s_waitcnt lgkmcnt(0)
	v_lshlrev_b32_e32 v96, 16, v96
	v_rcp_f32_e32 v98, v97
	s_nop 0
	v_mul_f32_e32 v97, v109, v98
	v_mul_f32_e32 v96, v97, v96
	v_mul_f32_e32 v97, 0xbfb8aa3b, v110
	v_exp_f32_e32 v97, v97
	v_cvt_pk_bf16_f32 v96, v96, s0
	ds_write_b16 v128, v96 offset:6864
	ds_read_u16 v96, v128 offset:7136
	v_add_f32_e32 v97, 1.0, v97
	s_waitcnt lgkmcnt(0)
	v_lshlrev_b32_e32 v96, 16, v96
	v_rcp_f32_e32 v98, v97
	s_nop 0
	v_mul_f32_e32 v97, v110, v98
	v_mul_f32_e32 v96, v97, v96
	v_mul_f32_e32 v97, 0xbfb8aa3b, v111
	v_exp_f32_e32 v97, v97
	v_cvt_pk_bf16_f32 v96, v96, s0
	ds_write_b16 v128, v96 offset:7136
	ds_read_u16 v96, v128 offset:7408
	v_add_f32_e32 v97, 1.0, v97
	s_waitcnt lgkmcnt(0)
	v_lshlrev_b32_e32 v96, 16, v96
	v_rcp_f32_e32 v98, v97
	s_nop 0
	v_mul_f32_e32 v97, v111, v98
	v_mul_f32_e32 v96, v97, v96
	v_mul_f32_e32 v97, 0xbfb8aa3b, v80
	v_exp_f32_e32 v97, v97
	v_cvt_pk_bf16_f32 v96, v96, s0
	ds_write_b16 v128, v96 offset:7408
	ds_read_u16 v96, v128 offset:8704
	v_add_f32_e32 v97, 1.0, v97
	s_waitcnt lgkmcnt(0)
	v_lshlrev_b32_e32 v96, 16, v96
	v_rcp_f32_e32 v98, v97
	s_nop 0
	v_mul_f32_e32 v80, v80, v98
	v_mul_f32_e32 v80, v80, v96
	v_mul_f32_e32 v96, 0xbfb8aa3b, v81
	v_exp_f32_e32 v96, v96
	v_cvt_pk_bf16_f32 v80, v80, s0
	ds_write_b16 v128, v80 offset:8704
	ds_read_u16 v80, v128 offset:8976
	v_add_f32_e32 v96, 1.0, v96
	s_waitcnt lgkmcnt(0)
	v_lshlrev_b32_e32 v80, 16, v80
	v_rcp_f32_e32 v97, v96
	s_nop 0
	v_mul_f32_e32 v81, v81, v97
	v_mul_f32_e32 v80, v81, v80
	v_mul_f32_e32 v81, 0xbfb8aa3b, v82
	v_exp_f32_e32 v81, v81
	v_cvt_pk_bf16_f32 v80, v80, s0
	ds_write_b16 v128, v80 offset:8976
	ds_read_u16 v80, v128 offset:9248
	v_add_f32_e32 v81, 1.0, v81
	s_waitcnt lgkmcnt(0)
	v_lshlrev_b32_e32 v80, 16, v80
	v_rcp_f32_e32 v96, v81
	s_nop 0
	v_mul_f32_e32 v81, v82, v96
	v_mul_f32_e32 v80, v81, v80
	v_mul_f32_e32 v81, 0xbfb8aa3b, v83
	v_exp_f32_e32 v81, v81
	v_cvt_pk_bf16_f32 v80, v80, s0
	ds_write_b16 v128, v80 offset:9248
	ds_read_u16 v80, v128 offset:9520
	v_add_f32_e32 v81, 1.0, v81
	s_waitcnt lgkmcnt(0)
	v_lshlrev_b32_e32 v80, 16, v80
	v_rcp_f32_e32 v82, v81
	s_nop 0
	v_mul_f32_e32 v81, v83, v82
	v_mul_f32_e32 v80, v81, v80
	v_mul_f32_e32 v81, 0xbfb8aa3b, v84
	v_exp_f32_e32 v81, v81
	v_cvt_pk_bf16_f32 v80, v80, s0
	ds_write_b16 v128, v80 offset:9520
	ds_read_u16 v80, v128 offset:10880
	v_add_f32_e32 v81, 1.0, v81
	s_waitcnt lgkmcnt(0)
	v_lshlrev_b32_e32 v80, 16, v80
	v_rcp_f32_e32 v82, v81
	s_nop 0
	v_mul_f32_e32 v81, v84, v82
	v_mul_f32_e32 v80, v81, v80
	v_mul_f32_e32 v81, 0xbfb8aa3b, v85
	v_exp_f32_e32 v81, v81
	v_cvt_pk_bf16_f32 v80, v80, s0
	ds_write_b16 v128, v80 offset:10880
	ds_read_u16 v80, v128 offset:11152
	v_add_f32_e32 v81, 1.0, v81
	s_waitcnt lgkmcnt(0)
	v_lshlrev_b32_e32 v80, 16, v80
	v_rcp_f32_e32 v82, v81
	s_nop 0
	v_mul_f32_e32 v81, v85, v82
	v_mul_f32_e32 v80, v81, v80
	v_mul_f32_e32 v81, 0xbfb8aa3b, v86
	v_exp_f32_e32 v81, v81
	v_cvt_pk_bf16_f32 v80, v80, s0
	ds_write_b16 v128, v80 offset:11152
	ds_read_u16 v80, v128 offset:11424
	v_add_f32_e32 v81, 1.0, v81
	s_waitcnt lgkmcnt(0)
	v_lshlrev_b32_e32 v80, 16, v80
	v_rcp_f32_e32 v82, v81
	s_nop 0
	v_mul_f32_e32 v81, v86, v82
	v_mul_f32_e32 v80, v81, v80
	v_mul_f32_e32 v81, 0xbfb8aa3b, v87
	v_exp_f32_e32 v81, v81
	v_cvt_pk_bf16_f32 v80, v80, s0
	ds_write_b16 v128, v80 offset:11424
	ds_read_u16 v80, v128 offset:11696
	v_add_f32_e32 v81, 1.0, v81
	s_waitcnt lgkmcnt(0)
; DEV u16 f2bf(float f) { return (u16)(pk2bf(f, 0.f) & 0xffffu); }
; DEV float bf2f(u16 h) { return __uint_as_float(((unsigned)h) << 16); }
; DEV float siluf_(float x) { return x / (1.0f + __expf(-x)); }
; template <int MI>
; DEV void p4_tile(const Params& p, int l, int m0, int nt, unsigned char* smem) {
;     ...
;     acc_foreach_t<MI>([&](int mi, int ni, int r, int row, int col) __attribute__((always_inline)) {
;       sC[row * LDC + col] = f2bf(bf2f(sC[row * LDC + col]) * siluf_(acc[mi][ni][r]));
;     });
	v_lshlrev_b32_e32 v80, 16, v80
	v_rcp_f32_e32 v82, v81
	s_nop 0
	v_mul_f32_e32 v81, v87, v82
	v_mul_f32_e32 v80, v81, v80
	v_mul_f32_e32 v81, 0xbfb8aa3b, v88
	v_exp_f32_e32 v81, v81
	v_cvt_pk_bf16_f32 v80, v80, s0
	ds_write_b16 v128, v80 offset:11696
	ds_read_u16 v80, v128 offset:13056
	v_add_f32_e32 v81, 1.0, v81
	s_waitcnt lgkmcnt(0)
	v_lshlrev_b32_e32 v80, 16, v80
	v_rcp_f32_e32 v82, v81
	s_nop 0
	v_mul_f32_e32 v81, v88, v82
	v_mul_f32_e32 v80, v81, v80
	v_mul_f32_e32 v81, 0xbfb8aa3b, v89
	v_exp_f32_e32 v81, v81
	v_cvt_pk_bf16_f32 v80, v80, s0
	ds_write_b16 v128, v80 offset:13056
	ds_read_u16 v80, v128 offset:13328
	v_add_f32_e32 v81, 1.0, v81
	s_waitcnt lgkmcnt(0)
	v_lshlrev_b32_e32 v80, 16, v80
	v_rcp_f32_e32 v82, v81
	s_nop 0
	v_mul_f32_e32 v81, v89, v82
	v_mul_f32_e32 v80, v81, v80
	v_mul_f32_e32 v81, 0xbfb8aa3b, v90
	v_exp_f32_e32 v81, v81
	v_cvt_pk_bf16_f32 v80, v80, s0
	ds_write_b16 v128, v80 offset:13328
	ds_read_u16 v80, v128 offset:13600
	v_add_f32_e32 v81, 1.0, v81
	s_waitcnt lgkmcnt(0)
	v_lshlrev_b32_e32 v80, 16, v80
	v_rcp_f32_e32 v82, v81
	s_nop 0
	v_mul_f32_e32 v81, v90, v82
	v_mul_f32_e32 v80, v81, v80
	v_mul_f32_e32 v81, 0xbfb8aa3b, v91
	v_exp_f32_e32 v81, v81
	v_cvt_pk_bf16_f32 v80, v80, s0
	ds_write_b16 v128, v80 offset:13600
	ds_read_u16 v80, v128 offset:13872
	v_add_f32_e32 v81, 1.0, v81
	s_waitcnt lgkmcnt(0)
	v_lshlrev_b32_e32 v80, 16, v80
	v_rcp_f32_e32 v82, v81
	s_nop 0
	v_mul_f32_e32 v81, v91, v82
	v_mul_f32_e32 v80, v81, v80
	v_mul_f32_e32 v81, 0xbfb8aa3b, v92
	v_exp_f32_e32 v81, v81
	v_cvt_pk_bf16_f32 v80, v80, s0
	ds_write_b16 v128, v80 offset:13872
	ds_read_u16 v80, v128 offset:15232
	v_add_f32_e32 v81, 1.0, v81
	s_waitcnt lgkmcnt(0)
	v_lshlrev_b32_e32 v80, 16, v80
	v_rcp_f32_e32 v82, v81
	s_nop 0
	v_mul_f32_e32 v81, v92, v82
	v_mul_f32_e32 v80, v81, v80
	v_mul_f32_e32 v81, 0xbfb8aa3b, v93
	v_exp_f32_e32 v81, v81
	v_cvt_pk_bf16_f32 v80, v80, s0
	ds_write_b16 v128, v80 offset:15232
	ds_read_u16 v80, v128 offset:15504
	v_add_f32_e32 v81, 1.0, v81
	s_waitcnt lgkmcnt(0)
	v_lshlrev_b32_e32 v80, 16, v80
	v_rcp_f32_e32 v82, v81
	s_nop 0
	v_mul_f32_e32 v81, v93, v82
	v_mul_f32_e32 v80, v81, v80
	v_mul_f32_e32 v81, 0xbfb8aa3b, v94
	v_exp_f32_e32 v81, v81
	v_cvt_pk_bf16_f32 v80, v80, s0
	ds_write_b16 v128, v80 offset:15504
	ds_read_u16 v80, v128 offset:15776
	v_add_f32_e32 v81, 1.0, v81
	s_waitcnt lgkmcnt(0)
	v_lshlrev_b32_e32 v80, 16, v80
	v_rcp_f32_e32 v82, v81
	s_nop 0
	v_mul_f32_e32 v81, v94, v82
	v_mul_f32_e32 v80, v81, v80
	v_mul_f32_e32 v81, 0xbfb8aa3b, v95
	v_exp_f32_e32 v81, v81
	v_cvt_pk_bf16_f32 v80, v80, s0
	ds_write_b16 v128, v80 offset:15776
	ds_read_u16 v80, v128 offset:16048
	v_add_f32_e32 v81, 1.0, v81
	s_waitcnt lgkmcnt(0)
	v_lshlrev_b32_e32 v80, 16, v80
	v_rcp_f32_e32 v82, v81
	s_nop 0
	v_mul_f32_e32 v81, v95, v82
	v_mul_f32_e32 v80, v81, v80
	v_mul_f32_e32 v81, 0xbfb8aa3b, v64
	v_exp_f32_e32 v81, v81
	v_cvt_pk_bf16_f32 v80, v80, s0
	ds_write_b16 v128, v80 offset:16048
	ds_read_u16 v80, v128 offset:8768
	v_add_f32_e32 v81, 1.0, v81
	s_waitcnt lgkmcnt(0)
	v_lshlrev_b32_e32 v80, 16, v80
	v_rcp_f32_e32 v82, v81
	s_nop 0
	v_mul_f32_e32 v64, v64, v82
	v_mul_f32_e32 v64, v64, v80
	v_mul_f32_e32 v80, 0xbfb8aa3b, v65
	v_exp_f32_e32 v80, v80
	v_cvt_pk_bf16_f32 v64, v64, s0
	ds_write_b16 v128, v64 offset:8768
	ds_read_u16 v64, v128 offset:9040
	v_add_f32_e32 v80, 1.0, v80
	s_waitcnt lgkmcnt(0)
	v_lshlrev_b32_e32 v64, 16, v64
	v_rcp_f32_e32 v81, v80
	s_nop 0
	v_mul_f32_e32 v65, v65, v81
	v_mul_f32_e32 v64, v65, v64
	v_mul_f32_e32 v65, 0xbfb8aa3b, v66
	v_exp_f32_e32 v65, v65
	v_cvt_pk_bf16_f32 v64, v64, s0
	ds_write_b16 v128, v64 offset:9040
	ds_read_u16 v64, v128 offset:9312
	v_add_f32_e32 v65, 1.0, v65
	s_waitcnt lgkmcnt(0)
	v_lshlrev_b32_e32 v64, 16, v64
	v_rcp_f32_e32 v80, v65
	s_nop 0
	v_mul_f32_e32 v65, v66, v80
	v_mul_f32_e32 v64, v65, v64
	v_mul_f32_e32 v65, 0xbfb8aa3b, v67
	v_exp_f32_e32 v65, v65
	v_cvt_pk_bf16_f32 v64, v64, s0
	ds_write_b16 v128, v64 offset:9312
	ds_read_u16 v64, v128 offset:9584
	v_add_f32_e32 v65, 1.0, v65
	s_waitcnt lgkmcnt(0)
	v_lshlrev_b32_e32 v64, 16, v64
	v_rcp_f32_e32 v66, v65
	s_nop 0
	v_mul_f32_e32 v65, v67, v66
	v_mul_f32_e32 v64, v65, v64
	v_mul_f32_e32 v65, 0xbfb8aa3b, v68
	v_exp_f32_e32 v65, v65
	v_cvt_pk_bf16_f32 v64, v64, s0
	ds_write_b16 v128, v64 offset:9584
	ds_read_u16 v64, v128 offset:10944
	v_add_f32_e32 v65, 1.0, v65
	s_waitcnt lgkmcnt(0)
	v_lshlrev_b32_e32 v64, 16, v64
	v_rcp_f32_e32 v66, v65
	s_nop 0
	v_mul_f32_e32 v65, v68, v66
	v_mul_f32_e32 v64, v65, v64
	v_mul_f32_e32 v65, 0xbfb8aa3b, v69
	v_exp_f32_e32 v65, v65
	v_cvt_pk_bf16_f32 v64, v64, s0
	ds_write_b16 v128, v64 offset:10944
	ds_read_u16 v64, v128 offset:11216
	v_add_f32_e32 v65, 1.0, v65
	s_waitcnt lgkmcnt(0)
	v_lshlrev_b32_e32 v64, 16, v64
	v_rcp_f32_e32 v66, v65
	s_nop 0
	v_mul_f32_e32 v65, v69, v66
	v_mul_f32_e32 v64, v65, v64
	v_mul_f32_e32 v65, 0xbfb8aa3b, v70
	v_exp_f32_e32 v65, v65
	v_cvt_pk_bf16_f32 v64, v64, s0
	ds_write_b16 v128, v64 offset:11216
	ds_read_u16 v64, v128 offset:11488
	v_add_f32_e32 v65, 1.0, v65
	s_waitcnt lgkmcnt(0)
	v_lshlrev_b32_e32 v64, 16, v64
	v_rcp_f32_e32 v66, v65
	s_nop 0
	v_mul_f32_e32 v65, v70, v66
	v_mul_f32_e32 v64, v65, v64
	v_mul_f32_e32 v65, 0xbfb8aa3b, v71
	v_exp_f32_e32 v65, v65
	v_cvt_pk_bf16_f32 v64, v64, s0
	ds_write_b16 v128, v64 offset:11488
	ds_read_u16 v64, v128 offset:11760
	v_add_f32_e32 v65, 1.0, v65
	s_waitcnt lgkmcnt(0)
	v_lshlrev_b32_e32 v64, 16, v64
	v_rcp_f32_e32 v66, v65
	s_nop 0
	v_mul_f32_e32 v65, v71, v66
	v_mul_f32_e32 v64, v65, v64
	v_mul_f32_e32 v65, 0xbfb8aa3b, v72
	v_exp_f32_e32 v65, v65
	v_cvt_pk_bf16_f32 v64, v64, s0
	ds_write_b16 v128, v64 offset:11760
	ds_read_u16 v64, v128 offset:13120
	v_add_f32_e32 v65, 1.0, v65
	s_waitcnt lgkmcnt(0)
; DEV u16 f2bf(float f) { return (u16)(pk2bf(f, 0.f) & 0xffffu); }
; DEV float bf2f(u16 h) { return __uint_as_float(((unsigned)h) << 16); }
; DEV float siluf_(float x) { return x / (1.0f + __expf(-x)); }
; template <int MI>
; DEV void p4_tile(const Params& p, int l, int m0, int nt, unsigned char* smem) {
;     ...
;     acc_foreach_t<MI>([&](int mi, int ni, int r, int row, int col) __attribute__((always_inline)) {
;       sC[row * LDC + col] = f2bf(bf2f(sC[row * LDC + col]) * siluf_(acc[mi][ni][r]));
;     });
	v_lshlrev_b32_e32 v64, 16, v64
	v_rcp_f32_e32 v66, v65
	s_nop 0
	v_mul_f32_e32 v65, v72, v66
	v_mul_f32_e32 v64, v65, v64
	v_mul_f32_e32 v65, 0xbfb8aa3b, v73
	v_exp_f32_e32 v65, v65
	v_cvt_pk_bf16_f32 v64, v64, s0
	ds_write_b16 v128, v64 offset:13120
	ds_read_u16 v64, v128 offset:13392
	v_add_f32_e32 v65, 1.0, v65
	s_waitcnt lgkmcnt(0)
	v_lshlrev_b32_e32 v64, 16, v64
	v_rcp_f32_e32 v66, v65
	s_nop 0
	v_mul_f32_e32 v65, v73, v66
	v_mul_f32_e32 v64, v65, v64
	v_mul_f32_e32 v65, 0xbfb8aa3b, v74
	v_exp_f32_e32 v65, v65
	v_cvt_pk_bf16_f32 v64, v64, s0
	ds_write_b16 v128, v64 offset:13392
	ds_read_u16 v64, v128 offset:13664
	v_add_f32_e32 v65, 1.0, v65
	s_waitcnt lgkmcnt(0)
	v_lshlrev_b32_e32 v64, 16, v64
	v_rcp_f32_e32 v66, v65
	s_nop 0
	v_mul_f32_e32 v65, v74, v66
	v_mul_f32_e32 v64, v65, v64
	v_mul_f32_e32 v65, 0xbfb8aa3b, v75
	v_exp_f32_e32 v65, v65
	v_cvt_pk_bf16_f32 v64, v64, s0
	ds_write_b16 v128, v64 offset:13664
	ds_read_u16 v64, v128 offset:13936
	v_add_f32_e32 v65, 1.0, v65
	s_waitcnt lgkmcnt(0)
	v_lshlrev_b32_e32 v64, 16, v64
	v_rcp_f32_e32 v66, v65
	s_nop 0
	v_mul_f32_e32 v65, v75, v66
	v_mul_f32_e32 v64, v65, v64
	v_mul_f32_e32 v65, 0xbfb8aa3b, v76
	v_exp_f32_e32 v65, v65
	v_cvt_pk_bf16_f32 v64, v64, s0
	ds_write_b16 v128, v64 offset:13936
	ds_read_u16 v64, v128 offset:15296
	v_add_f32_e32 v65, 1.0, v65
	s_waitcnt lgkmcnt(0)
	v_lshlrev_b32_e32 v64, 16, v64
	v_rcp_f32_e32 v66, v65
	s_nop 0
	v_mul_f32_e32 v65, v76, v66
	v_mul_f32_e32 v64, v65, v64
	v_mul_f32_e32 v65, 0xbfb8aa3b, v77
	v_exp_f32_e32 v65, v65
	v_cvt_pk_bf16_f32 v64, v64, s0
	ds_write_b16 v128, v64 offset:15296
	ds_read_u16 v64, v128 offset:15568
	v_add_f32_e32 v65, 1.0, v65
	s_waitcnt lgkmcnt(0)
	v_lshlrev_b32_e32 v64, 16, v64
	v_rcp_f32_e32 v66, v65
	s_nop 0
	v_mul_f32_e32 v65, v77, v66
	v_mul_f32_e32 v64, v65, v64
	v_mul_f32_e32 v65, 0xbfb8aa3b, v78
	v_exp_f32_e32 v65, v65
	v_cvt_pk_bf16_f32 v64, v64, s0
	ds_write_b16 v128, v64 offset:15568
	ds_read_u16 v64, v128 offset:15840
	v_add_f32_e32 v65, 1.0, v65
	s_waitcnt lgkmcnt(0)
	v_lshlrev_b32_e32 v64, 16, v64
	v_rcp_f32_e32 v66, v65
	s_nop 0
	v_mul_f32_e32 v65, v78, v66
	v_mul_f32_e32 v64, v65, v64
	v_mul_f32_e32 v65, 0xbfb8aa3b, v79
	v_exp_f32_e32 v65, v65
	v_cvt_pk_bf16_f32 v64, v64, s0
	ds_write_b16 v128, v64 offset:15840
	ds_read_u16 v64, v128 offset:16112
	v_add_f32_e32 v65, 1.0, v65
	s_waitcnt lgkmcnt(0)
	v_lshlrev_b32_e32 v64, 16, v64
	v_rcp_f32_e32 v66, v65
	s_nop 0
	v_mul_f32_e32 v65, v79, v66
	v_mul_f32_e32 v64, v65, v64
	v_mul_f32_e32 v65, 0xbfb8aa3b, v48
	v_exp_f32_e32 v65, v65
	v_cvt_pk_bf16_f32 v64, v64, s0
	ds_write_b16 v128, v64 offset:16112
	ds_read_u16 v64, v128 offset:17408
	v_add_f32_e32 v65, 1.0, v65
	s_waitcnt lgkmcnt(0)
	v_lshlrev_b32_e32 v64, 16, v64
	v_rcp_f32_e32 v66, v65
	s_nop 0
	v_mul_f32_e32 v48, v48, v66
	v_mul_f32_e32 v48, v48, v64
	v_mul_f32_e32 v64, 0xbfb8aa3b, v49
	v_exp_f32_e32 v64, v64
	v_cvt_pk_bf16_f32 v48, v48, s0
	ds_write_b16 v128, v48 offset:17408
	ds_read_u16 v48, v128 offset:17680
	v_add_f32_e32 v64, 1.0, v64
	s_waitcnt lgkmcnt(0)
	v_lshlrev_b32_e32 v48, 16, v48
	v_rcp_f32_e32 v65, v64
	s_nop 0
	v_mul_f32_e32 v49, v49, v65
	v_mul_f32_e32 v48, v49, v48
	v_mul_f32_e32 v49, 0xbfb8aa3b, v50
	v_exp_f32_e32 v49, v49
	v_cvt_pk_bf16_f32 v48, v48, s0
	ds_write_b16 v128, v48 offset:17680
	ds_read_u16 v48, v128 offset:17952
	v_add_f32_e32 v49, 1.0, v49
	s_waitcnt lgkmcnt(0)
	v_lshlrev_b32_e32 v48, 16, v48
	v_rcp_f32_e32 v64, v49
	s_nop 0
	v_mul_f32_e32 v49, v50, v64
	v_mul_f32_e32 v48, v49, v48
	v_mul_f32_e32 v49, 0xbfb8aa3b, v51
	v_exp_f32_e32 v49, v49
	v_cvt_pk_bf16_f32 v48, v48, s0
	ds_write_b16 v128, v48 offset:17952
	ds_read_u16 v48, v128 offset:18224
	v_add_f32_e32 v49, 1.0, v49
	s_waitcnt lgkmcnt(0)
	v_lshlrev_b32_e32 v48, 16, v48
	v_rcp_f32_e32 v50, v49
	s_nop 0
	v_mul_f32_e32 v49, v51, v50
	v_mul_f32_e32 v48, v49, v48
	v_mul_f32_e32 v49, 0xbfb8aa3b, v52
	v_exp_f32_e32 v49, v49
	v_cvt_pk_bf16_f32 v48, v48, s0
	ds_write_b16 v128, v48 offset:18224
	ds_read_u16 v48, v128 offset:19584
	v_add_f32_e32 v49, 1.0, v49
	s_waitcnt lgkmcnt(0)
	v_lshlrev_b32_e32 v48, 16, v48
	v_rcp_f32_e32 v50, v49
	s_nop 0
	v_mul_f32_e32 v49, v52, v50
	v_mul_f32_e32 v48, v49, v48
	v_mul_f32_e32 v49, 0xbfb8aa3b, v53
	v_exp_f32_e32 v49, v49
	v_cvt_pk_bf16_f32 v48, v48, s0
	ds_write_b16 v128, v48 offset:19584
	ds_read_u16 v48, v128 offset:19856
	v_add_f32_e32 v49, 1.0, v49
	s_waitcnt lgkmcnt(0)
	v_lshlrev_b32_e32 v48, 16, v48
	v_rcp_f32_e32 v50, v49
	s_nop 0
	v_mul_f32_e32 v49, v53, v50
	v_mul_f32_e32 v48, v49, v48
	v_mul_f32_e32 v49, 0xbfb8aa3b, v54
	v_exp_f32_e32 v49, v49
	v_cvt_pk_bf16_f32 v48, v48, s0
	ds_write_b16 v128, v48 offset:19856
	ds_read_u16 v48, v128 offset:20128
	v_add_f32_e32 v49, 1.0, v49
	s_waitcnt lgkmcnt(0)
	v_lshlrev_b32_e32 v48, 16, v48
	v_rcp_f32_e32 v50, v49
	s_nop 0
	v_mul_f32_e32 v49, v54, v50
	v_mul_f32_e32 v48, v49, v48
	v_mul_f32_e32 v49, 0xbfb8aa3b, v55
	v_exp_f32_e32 v49, v49
	v_cvt_pk_bf16_f32 v48, v48, s0
	ds_write_b16 v128, v48 offset:20128
	ds_read_u16 v48, v128 offset:20400
	v_add_f32_e32 v49, 1.0, v49
	s_waitcnt lgkmcnt(0)
	v_lshlrev_b32_e32 v48, 16, v48
	v_rcp_f32_e32 v50, v49
	s_nop 0
	v_mul_f32_e32 v49, v55, v50
	v_mul_f32_e32 v48, v49, v48
	v_mul_f32_e32 v49, 0xbfb8aa3b, v56
	v_exp_f32_e32 v49, v49
	v_cvt_pk_bf16_f32 v48, v48, s0
	ds_write_b16 v128, v48 offset:20400
	ds_read_u16 v48, v128 offset:21760
	v_add_f32_e32 v49, 1.0, v49
	s_waitcnt lgkmcnt(0)
	v_lshlrev_b32_e32 v48, 16, v48
	v_rcp_f32_e32 v50, v49
	s_nop 0
	v_mul_f32_e32 v49, v56, v50
	v_mul_f32_e32 v48, v49, v48
	v_mul_f32_e32 v49, 0xbfb8aa3b, v57
	v_exp_f32_e32 v49, v49
	v_cvt_pk_bf16_f32 v48, v48, s0
	ds_write_b16 v128, v48 offset:21760
	ds_read_u16 v48, v128 offset:22032
	v_add_f32_e32 v49, 1.0, v49
	s_waitcnt lgkmcnt(0)
; DEV u16 f2bf(float f) { return (u16)(pk2bf(f, 0.f) & 0xffffu); }
; DEV float bf2f(u16 h) { return __uint_as_float(((unsigned)h) << 16); }
; DEV float siluf_(float x) { return x / (1.0f + __expf(-x)); }
; template <int MI>
; DEV void p4_tile(const Params& p, int l, int m0, int nt, unsigned char* smem) {
;     ...
;     acc_foreach_t<MI>([&](int mi, int ni, int r, int row, int col) __attribute__((always_inline)) {
;       sC[row * LDC + col] = f2bf(bf2f(sC[row * LDC + col]) * siluf_(acc[mi][ni][r]));
;     });
	v_lshlrev_b32_e32 v48, 16, v48
	v_rcp_f32_e32 v50, v49
	s_nop 0
	v_mul_f32_e32 v49, v57, v50
	v_mul_f32_e32 v48, v49, v48
	v_mul_f32_e32 v49, 0xbfb8aa3b, v58
	v_exp_f32_e32 v49, v49
	v_cvt_pk_bf16_f32 v48, v48, s0
	ds_write_b16 v128, v48 offset:22032
	ds_read_u16 v48, v128 offset:22304
	v_add_f32_e32 v49, 1.0, v49
	s_waitcnt lgkmcnt(0)
	v_lshlrev_b32_e32 v48, 16, v48
	v_rcp_f32_e32 v50, v49
	s_nop 0
	v_mul_f32_e32 v49, v58, v50
	v_mul_f32_e32 v48, v49, v48
	v_mul_f32_e32 v49, 0xbfb8aa3b, v59
	v_exp_f32_e32 v49, v49
	v_cvt_pk_bf16_f32 v48, v48, s0
	ds_write_b16 v128, v48 offset:22304
	ds_read_u16 v48, v128 offset:22576
	v_add_f32_e32 v49, 1.0, v49
	s_waitcnt lgkmcnt(0)
	v_lshlrev_b32_e32 v48, 16, v48
	v_rcp_f32_e32 v50, v49
	s_nop 0
	v_mul_f32_e32 v49, v59, v50
	v_mul_f32_e32 v48, v49, v48
	v_mul_f32_e32 v49, 0xbfb8aa3b, v60
	v_exp_f32_e32 v49, v49
	v_cvt_pk_bf16_f32 v48, v48, s0
	ds_write_b16 v128, v48 offset:22576
	ds_read_u16 v48, v128 offset:23936
	v_add_f32_e32 v49, 1.0, v49
	s_waitcnt lgkmcnt(0)
	v_lshlrev_b32_e32 v48, 16, v48
	v_rcp_f32_e32 v50, v49
	s_nop 0
	v_mul_f32_e32 v49, v60, v50
	v_mul_f32_e32 v48, v49, v48
	v_mul_f32_e32 v49, 0xbfb8aa3b, v61
	v_exp_f32_e32 v49, v49
	v_cvt_pk_bf16_f32 v48, v48, s0
	ds_write_b16 v128, v48 offset:23936
	ds_read_u16 v48, v128 offset:24208
	v_add_f32_e32 v49, 1.0, v49
	s_waitcnt lgkmcnt(0)
	v_lshlrev_b32_e32 v48, 16, v48
	v_rcp_f32_e32 v50, v49
	s_nop 0
	v_mul_f32_e32 v49, v61, v50
	v_mul_f32_e32 v48, v49, v48
	v_mul_f32_e32 v49, 0xbfb8aa3b, v62
	v_exp_f32_e32 v49, v49
	v_cvt_pk_bf16_f32 v48, v48, s0
	ds_write_b16 v128, v48 offset:24208
	ds_read_u16 v48, v128 offset:24480
	v_add_f32_e32 v49, 1.0, v49
	s_waitcnt lgkmcnt(0)
	v_lshlrev_b32_e32 v48, 16, v48
	v_rcp_f32_e32 v50, v49
	s_nop 0
	v_mul_f32_e32 v49, v62, v50
	v_mul_f32_e32 v48, v49, v48
	v_mul_f32_e32 v49, 0xbfb8aa3b, v63
	v_exp_f32_e32 v49, v49
	v_cvt_pk_bf16_f32 v48, v48, s0
	ds_write_b16 v128, v48 offset:24480
	ds_read_u16 v48, v128 offset:24752
	v_add_f32_e32 v49, 1.0, v49
	s_waitcnt lgkmcnt(0)
	v_lshlrev_b32_e32 v48, 16, v48
	v_rcp_f32_e32 v50, v49
	s_nop 0
	v_mul_f32_e32 v49, v63, v50
	v_mul_f32_e32 v48, v49, v48
	v_mul_f32_e32 v49, 0xbfb8aa3b, v32
	v_exp_f32_e32 v49, v49
	v_cvt_pk_bf16_f32 v48, v48, s0
	ds_write_b16 v128, v48 offset:24752
	ds_read_u16 v48, v128 offset:17472
	v_add_f32_e32 v49, 1.0, v49
	s_waitcnt lgkmcnt(0)
	v_lshlrev_b32_e32 v48, 16, v48
	v_rcp_f32_e32 v50, v49
	s_nop 0
	v_mul_f32_e32 v32, v32, v50
	v_mul_f32_e32 v32, v32, v48
	v_mul_f32_e32 v48, 0xbfb8aa3b, v33
	v_exp_f32_e32 v48, v48
	v_cvt_pk_bf16_f32 v32, v32, s0
	ds_write_b16 v128, v32 offset:17472
	ds_read_u16 v32, v128 offset:17744
	v_add_f32_e32 v48, 1.0, v48
	s_waitcnt lgkmcnt(0)
	v_lshlrev_b32_e32 v32, 16, v32
	v_rcp_f32_e32 v49, v48
	s_nop 0
	v_mul_f32_e32 v33, v33, v49
	v_mul_f32_e32 v32, v33, v32
	v_mul_f32_e32 v33, 0xbfb8aa3b, v34
	v_exp_f32_e32 v33, v33
	v_cvt_pk_bf16_f32 v32, v32, s0
	ds_write_b16 v128, v32 offset:17744
	ds_read_u16 v32, v128 offset:18016
	v_add_f32_e32 v33, 1.0, v33
	s_waitcnt lgkmcnt(0)
	v_lshlrev_b32_e32 v32, 16, v32
	v_rcp_f32_e32 v48, v33
	s_nop 0
	v_mul_f32_e32 v33, v34, v48
	v_mul_f32_e32 v32, v33, v32
	v_mul_f32_e32 v33, 0xbfb8aa3b, v35
	v_exp_f32_e32 v33, v33
	v_cvt_pk_bf16_f32 v32, v32, s0
	ds_write_b16 v128, v32 offset:18016
	ds_read_u16 v32, v128 offset:18288
	v_add_f32_e32 v33, 1.0, v33
	s_waitcnt lgkmcnt(0)
	v_lshlrev_b32_e32 v32, 16, v32
	v_rcp_f32_e32 v34, v33
	s_nop 0
	v_mul_f32_e32 v33, v35, v34
	v_mul_f32_e32 v32, v33, v32
	v_mul_f32_e32 v33, 0xbfb8aa3b, v36
	v_exp_f32_e32 v33, v33
	v_cvt_pk_bf16_f32 v32, v32, s0
	ds_write_b16 v128, v32 offset:18288
	ds_read_u16 v32, v128 offset:19648
	v_add_f32_e32 v33, 1.0, v33
	s_waitcnt lgkmcnt(0)
	v_lshlrev_b32_e32 v32, 16, v32
	v_rcp_f32_e32 v34, v33
	s_nop 0
	v_mul_f32_e32 v33, v36, v34
	v_mul_f32_e32 v32, v33, v32
	v_mul_f32_e32 v33, 0xbfb8aa3b, v37
	v_exp_f32_e32 v33, v33
	v_cvt_pk_bf16_f32 v32, v32, s0
	ds_write_b16 v128, v32 offset:19648
	ds_read_u16 v32, v128 offset:19920
	v_add_f32_e32 v33, 1.0, v33
	s_waitcnt lgkmcnt(0)
	v_lshlrev_b32_e32 v32, 16, v32
	v_rcp_f32_e32 v34, v33
	s_nop 0
	v_mul_f32_e32 v33, v37, v34
	v_mul_f32_e32 v32, v33, v32
	v_mul_f32_e32 v33, 0xbfb8aa3b, v38
	v_exp_f32_e32 v33, v33
	v_cvt_pk_bf16_f32 v32, v32, s0
	ds_write_b16 v128, v32 offset:19920
	ds_read_u16 v32, v128 offset:20192
	v_add_f32_e32 v33, 1.0, v33
	s_waitcnt lgkmcnt(0)
	v_lshlrev_b32_e32 v32, 16, v32
	v_rcp_f32_e32 v34, v33
	s_nop 0
	v_mul_f32_e32 v33, v38, v34
	v_mul_f32_e32 v32, v33, v32
	v_mul_f32_e32 v33, 0xbfb8aa3b, v39
	v_exp_f32_e32 v33, v33
	v_cvt_pk_bf16_f32 v32, v32, s0
	ds_write_b16 v128, v32 offset:20192
	ds_read_u16 v32, v128 offset:20464
	v_add_f32_e32 v33, 1.0, v33
	s_waitcnt lgkmcnt(0)
	v_lshlrev_b32_e32 v32, 16, v32
	v_rcp_f32_e32 v34, v33
	s_nop 0
	v_mul_f32_e32 v33, v39, v34
	v_mul_f32_e32 v32, v33, v32
	v_mul_f32_e32 v33, 0xbfb8aa3b, v40
	v_exp_f32_e32 v33, v33
	v_cvt_pk_bf16_f32 v32, v32, s0
	ds_write_b16 v128, v32 offset:20464
	ds_read_u16 v32, v128 offset:21824
	v_add_f32_e32 v33, 1.0, v33
	s_waitcnt lgkmcnt(0)
	v_lshlrev_b32_e32 v32, 16, v32
	v_rcp_f32_e32 v34, v33
	s_nop 0
	v_mul_f32_e32 v33, v40, v34
	v_mul_f32_e32 v32, v33, v32
	v_mul_f32_e32 v33, 0xbfb8aa3b, v41
	v_exp_f32_e32 v33, v33
	v_cvt_pk_bf16_f32 v32, v32, s0
	ds_write_b16 v128, v32 offset:21824
	ds_read_u16 v32, v128 offset:22096
	v_add_f32_e32 v33, 1.0, v33
	s_waitcnt lgkmcnt(0)
	v_lshlrev_b32_e32 v32, 16, v32
	v_rcp_f32_e32 v34, v33
	s_nop 0
	v_mul_f32_e32 v33, v41, v34
	v_mul_f32_e32 v32, v33, v32
	v_mul_f32_e32 v33, 0xbfb8aa3b, v42
	v_exp_f32_e32 v33, v33
	v_cvt_pk_bf16_f32 v32, v32, s0
	ds_write_b16 v128, v32 offset:22096
	ds_read_u16 v32, v128 offset:22368
	v_add_f32_e32 v33, 1.0, v33
	s_waitcnt lgkmcnt(0)
; DEV u16 f2bf(float f) { return (u16)(pk2bf(f, 0.f) & 0xffffu); }
; DEV float bf2f(u16 h) { return __uint_as_float(((unsigned)h) << 16); }
; DEV float siluf_(float x) { return x / (1.0f + __expf(-x)); }
; template <int MI>
; DEV void p4_tile(const Params& p, int l, int m0, int nt, unsigned char* smem) {
;     ...
;     acc_foreach_t<MI>([&](int mi, int ni, int r, int row, int col) __attribute__((always_inline)) {
;       sC[row * LDC + col] = f2bf(bf2f(sC[row * LDC + col]) * siluf_(acc[mi][ni][r]));
;     });
	v_lshlrev_b32_e32 v32, 16, v32
	v_rcp_f32_e32 v34, v33
	s_nop 0
	v_mul_f32_e32 v33, v42, v34
	v_mul_f32_e32 v32, v33, v32
	v_mul_f32_e32 v33, 0xbfb8aa3b, v43
	v_exp_f32_e32 v33, v33
	v_cvt_pk_bf16_f32 v32, v32, s0
	ds_write_b16 v128, v32 offset:22368
	ds_read_u16 v32, v128 offset:22640
	v_add_f32_e32 v33, 1.0, v33
	s_waitcnt lgkmcnt(0)
	v_lshlrev_b32_e32 v32, 16, v32
	v_rcp_f32_e32 v34, v33
	s_nop 0
	v_mul_f32_e32 v33, v43, v34
	v_mul_f32_e32 v32, v33, v32
	v_mul_f32_e32 v33, 0xbfb8aa3b, v44
	v_exp_f32_e32 v33, v33
	v_cvt_pk_bf16_f32 v32, v32, s0
	ds_write_b16 v128, v32 offset:22640
	ds_read_u16 v32, v128 offset:24000
	v_add_f32_e32 v33, 1.0, v33
	s_waitcnt lgkmcnt(0)
	v_lshlrev_b32_e32 v32, 16, v32
	v_rcp_f32_e32 v34, v33
	s_nop 0
	v_mul_f32_e32 v33, v44, v34
	v_mul_f32_e32 v32, v33, v32
	v_mul_f32_e32 v33, 0xbfb8aa3b, v45
	v_exp_f32_e32 v33, v33
	v_cvt_pk_bf16_f32 v32, v32, s0
	ds_write_b16 v128, v32 offset:24000
	ds_read_u16 v32, v128 offset:24272
	v_add_f32_e32 v33, 1.0, v33
	s_waitcnt lgkmcnt(0)
	v_lshlrev_b32_e32 v32, 16, v32
	v_rcp_f32_e32 v34, v33
	s_nop 0
	v_mul_f32_e32 v33, v45, v34
	v_mul_f32_e32 v32, v33, v32
	v_mul_f32_e32 v33, 0xbfb8aa3b, v46
	v_exp_f32_e32 v33, v33
	v_cvt_pk_bf16_f32 v32, v32, s0
	ds_write_b16 v128, v32 offset:24272
	ds_read_u16 v32, v128 offset:24544
	v_add_f32_e32 v33, 1.0, v33
	s_waitcnt lgkmcnt(0)
	v_lshlrev_b32_e32 v32, 16, v32
	v_rcp_f32_e32 v34, v33
	s_nop 0
	v_mul_f32_e32 v33, v46, v34
	v_mul_f32_e32 v32, v33, v32
	v_mul_f32_e32 v33, 0xbfb8aa3b, v47
	v_exp_f32_e32 v33, v33
	v_cvt_pk_bf16_f32 v32, v32, s0
	ds_write_b16 v128, v32 offset:24544
	ds_read_u16 v32, v128 offset:24816
	v_add_f32_e32 v33, 1.0, v33
	s_waitcnt lgkmcnt(0)
	v_lshlrev_b32_e32 v32, 16, v32
	v_rcp_f32_e32 v34, v33
	s_nop 0
	v_mul_f32_e32 v33, v47, v34
	v_mul_f32_e32 v32, v33, v32
	v_mul_f32_e32 v33, 0xbfb8aa3b, v16
	v_exp_f32_e32 v33, v33
	v_cvt_pk_bf16_f32 v32, v32, s0
	ds_write_b16 v128, v32 offset:24816
	ds_read_u16 v32, v128 offset:26112
	v_add_f32_e32 v33, 1.0, v33
	s_waitcnt lgkmcnt(0)
	v_lshlrev_b32_e32 v32, 16, v32
	v_rcp_f32_e32 v34, v33
	s_nop 0
	v_mul_f32_e32 v16, v16, v34
	v_mul_f32_e32 v16, v16, v32
	v_mul_f32_e32 v32, 0xbfb8aa3b, v17
	v_exp_f32_e32 v32, v32
	v_cvt_pk_bf16_f32 v16, v16, s0
	ds_write_b16 v128, v16 offset:26112
	ds_read_u16 v16, v128 offset:26384
	v_add_f32_e32 v32, 1.0, v32
	s_waitcnt lgkmcnt(0)
	v_lshlrev_b32_e32 v16, 16, v16
	v_rcp_f32_e32 v33, v32
	s_nop 0
	v_mul_f32_e32 v17, v17, v33
	v_mul_f32_e32 v16, v17, v16
	v_mul_f32_e32 v17, 0xbfb8aa3b, v18
	v_exp_f32_e32 v17, v17
	v_cvt_pk_bf16_f32 v16, v16, s0
	ds_write_b16 v128, v16 offset:26384
	ds_read_u16 v16, v128 offset:26656
	v_add_f32_e32 v17, 1.0, v17
	s_waitcnt lgkmcnt(0)
	v_lshlrev_b32_e32 v16, 16, v16
	v_rcp_f32_e32 v32, v17
	s_nop 0
	v_mul_f32_e32 v17, v18, v32
	v_mul_f32_e32 v16, v17, v16
	v_mul_f32_e32 v17, 0xbfb8aa3b, v19
	v_exp_f32_e32 v17, v17
	v_cvt_pk_bf16_f32 v16, v16, s0
	ds_write_b16 v128, v16 offset:26656
	ds_read_u16 v16, v128 offset:26928
	v_add_f32_e32 v17, 1.0, v17
	s_waitcnt lgkmcnt(0)
	v_lshlrev_b32_e32 v16, 16, v16
	v_rcp_f32_e32 v18, v17
	s_nop 0
	v_mul_f32_e32 v17, v19, v18
	v_mul_f32_e32 v16, v17, v16
	v_mul_f32_e32 v17, 0xbfb8aa3b, v20
	v_exp_f32_e32 v17, v17
	v_cvt_pk_bf16_f32 v16, v16, s0
	ds_write_b16 v128, v16 offset:26928
	ds_read_u16 v16, v128 offset:28288
	v_add_f32_e32 v17, 1.0, v17
	s_waitcnt lgkmcnt(0)
	v_lshlrev_b32_e32 v16, 16, v16
	v_rcp_f32_e32 v18, v17
	s_nop 0
	v_mul_f32_e32 v17, v20, v18
	v_mul_f32_e32 v16, v17, v16
	v_mul_f32_e32 v17, 0xbfb8aa3b, v21
	v_exp_f32_e32 v17, v17
	v_cvt_pk_bf16_f32 v16, v16, s0
	ds_write_b16 v128, v16 offset:28288
	ds_read_u16 v16, v128 offset:28560
	v_add_f32_e32 v17, 1.0, v17
	s_waitcnt lgkmcnt(0)
	v_lshlrev_b32_e32 v16, 16, v16
	v_rcp_f32_e32 v18, v17
	s_nop 0
	v_mul_f32_e32 v17, v21, v18
	v_mul_f32_e32 v16, v17, v16
	v_mul_f32_e32 v17, 0xbfb8aa3b, v22
	v_exp_f32_e32 v17, v17
	v_cvt_pk_bf16_f32 v16, v16, s0
	ds_write_b16 v128, v16 offset:28560
	ds_read_u16 v16, v128 offset:28832
	v_add_f32_e32 v17, 1.0, v17
	s_waitcnt lgkmcnt(0)
	v_lshlrev_b32_e32 v16, 16, v16
	v_rcp_f32_e32 v18, v17
	s_nop 0
	v_mul_f32_e32 v17, v22, v18
	v_mul_f32_e32 v16, v17, v16
	v_mul_f32_e32 v17, 0xbfb8aa3b, v23
	v_exp_f32_e32 v17, v17
	v_cvt_pk_bf16_f32 v16, v16, s0
	ds_write_b16 v128, v16 offset:28832
	ds_read_u16 v16, v128 offset:29104
	v_add_f32_e32 v17, 1.0, v17
	s_waitcnt lgkmcnt(0)
	v_lshlrev_b32_e32 v16, 16, v16
	v_rcp_f32_e32 v18, v17
	s_nop 0
	v_mul_f32_e32 v17, v23, v18
	v_mul_f32_e32 v16, v17, v16
	v_mul_f32_e32 v17, 0xbfb8aa3b, v24
	v_exp_f32_e32 v17, v17
	v_cvt_pk_bf16_f32 v16, v16, s0
	ds_write_b16 v128, v16 offset:29104
	ds_read_u16 v16, v128 offset:30464
	v_add_f32_e32 v17, 1.0, v17
	s_waitcnt lgkmcnt(0)
	v_lshlrev_b32_e32 v16, 16, v16
	v_rcp_f32_e32 v18, v17
	s_nop 0
	v_mul_f32_e32 v17, v24, v18
	v_mul_f32_e32 v16, v17, v16
	v_mul_f32_e32 v17, 0xbfb8aa3b, v25
	v_exp_f32_e32 v17, v17
	v_cvt_pk_bf16_f32 v16, v16, s0
	ds_write_b16 v128, v16 offset:30464
	ds_read_u16 v16, v128 offset:30736
	v_add_f32_e32 v17, 1.0, v17
	s_waitcnt lgkmcnt(0)
	v_lshlrev_b32_e32 v16, 16, v16
	v_rcp_f32_e32 v18, v17
	s_nop 0
	v_mul_f32_e32 v17, v25, v18
	v_mul_f32_e32 v16, v17, v16
	v_mul_f32_e32 v17, 0xbfb8aa3b, v26
	v_exp_f32_e32 v17, v17
	v_cvt_pk_bf16_f32 v16, v16, s0
	ds_write_b16 v128, v16 offset:30736
	ds_read_u16 v16, v128 offset:31008
	v_add_f32_e32 v17, 1.0, v17
	s_waitcnt lgkmcnt(0)
	v_lshlrev_b32_e32 v16, 16, v16
	v_rcp_f32_e32 v18, v17
	s_nop 0
	v_mul_f32_e32 v17, v26, v18
	v_mul_f32_e32 v16, v17, v16
	v_mul_f32_e32 v17, 0xbfb8aa3b, v27
	v_exp_f32_e32 v17, v17
	v_cvt_pk_bf16_f32 v16, v16, s0
	ds_write_b16 v128, v16 offset:31008
	ds_read_u16 v16, v128 offset:31280
	v_add_f32_e32 v17, 1.0, v17
	s_waitcnt lgkmcnt(0)
; DEV u16 f2bf(float f) { return (u16)(pk2bf(f, 0.f) & 0xffffu); }
; DEV float bf2f(u16 h) { return __uint_as_float(((unsigned)h) << 16); }
; DEV float siluf_(float x) { return x / (1.0f + __expf(-x)); }
; template <int MI>
; DEV void tile_store_t(unsigned char* smem, u16* dst, size_t ldd) {
;   const u16* sC = (const u16*)smem;
;   __syncthreads();
; template <int MI>
; DEV void p4_tile(const Params& p, int l, int m0, int nt, unsigned char* smem) {
;     ...
;     acc_foreach_t<MI>([&](int mi, int ni, int r, int row, int col) __attribute__((always_inline)) {
;       sC[row * LDC + col] = f2bf(bf2f(sC[row * LDC + col]) * siluf_(acc[mi][ni][r]));
;     });
;     tile_store_t<MI>(smem, YB + (size_t)m0 * 1024 + nt * 128, 1024);
	v_lshlrev_b32_e32 v16, 16, v16
	v_rcp_f32_e32 v18, v17
	s_nop 0
	v_mul_f32_e32 v17, v27, v18
	v_mul_f32_e32 v16, v17, v16
	v_mul_f32_e32 v17, 0xbfb8aa3b, v28
	v_exp_f32_e32 v17, v17
	v_cvt_pk_bf16_f32 v16, v16, s0
	ds_write_b16 v128, v16 offset:31280
	ds_read_u16 v16, v128 offset:32640
	v_add_f32_e32 v17, 1.0, v17
	s_waitcnt lgkmcnt(0)
	v_lshlrev_b32_e32 v16, 16, v16
	v_rcp_f32_e32 v18, v17
	s_nop 0
	v_mul_f32_e32 v17, v28, v18
	v_mul_f32_e32 v16, v17, v16
	v_mul_f32_e32 v17, 0xbfb8aa3b, v29
	v_exp_f32_e32 v17, v17
	v_cvt_pk_bf16_f32 v16, v16, s0
	ds_write_b16 v128, v16 offset:32640
	ds_read_u16 v16, v128 offset:32912
	v_add_f32_e32 v17, 1.0, v17
	s_waitcnt lgkmcnt(0)
	v_lshlrev_b32_e32 v16, 16, v16
	v_rcp_f32_e32 v18, v17
	s_nop 0
	v_mul_f32_e32 v17, v29, v18
	v_mul_f32_e32 v16, v17, v16
	v_mul_f32_e32 v17, 0xbfb8aa3b, v30
	v_exp_f32_e32 v17, v17
	v_cvt_pk_bf16_f32 v16, v16, s0
	ds_write_b16 v128, v16 offset:32912
	ds_read_u16 v16, v128 offset:33184
	v_add_f32_e32 v17, 1.0, v17
	s_waitcnt lgkmcnt(0)
	v_lshlrev_b32_e32 v16, 16, v16
	v_rcp_f32_e32 v18, v17
	s_nop 0
	v_mul_f32_e32 v17, v30, v18
	v_mul_f32_e32 v16, v17, v16
	v_mul_f32_e32 v17, 0xbfb8aa3b, v31
	v_exp_f32_e32 v17, v17
	v_cvt_pk_bf16_f32 v16, v16, s0
	ds_write_b16 v128, v16 offset:33184
	ds_read_u16 v16, v128 offset:33456
	v_add_f32_e32 v17, 1.0, v17
	s_waitcnt lgkmcnt(0)
	v_lshlrev_b32_e32 v16, 16, v16
	v_rcp_f32_e32 v18, v17
	s_nop 0
	v_mul_f32_e32 v17, v31, v18
	v_mul_f32_e32 v16, v17, v16
	v_mul_f32_e32 v17, 0xbfb8aa3b, v0
	v_exp_f32_e32 v17, v17
	v_cvt_pk_bf16_f32 v16, v16, s0
	ds_write_b16 v128, v16 offset:33456
	ds_read_u16 v16, v128 offset:26176
	v_add_f32_e32 v17, 1.0, v17
	s_waitcnt lgkmcnt(0)
	v_lshlrev_b32_e32 v16, 16, v16
	v_rcp_f32_e32 v18, v17
	s_nop 0
	v_mul_f32_e32 v0, v0, v18
	v_mul_f32_e32 v0, v0, v16
	v_mul_f32_e32 v16, 0xbfb8aa3b, v1
	v_exp_f32_e32 v16, v16
	v_cvt_pk_bf16_f32 v0, v0, s0
	ds_write_b16 v128, v0 offset:26176
	ds_read_u16 v0, v128 offset:26448
	v_add_f32_e32 v16, 1.0, v16
	s_waitcnt lgkmcnt(0)
	v_lshlrev_b32_e32 v0, 16, v0
	v_rcp_f32_e32 v17, v16
	s_nop 0
	v_mul_f32_e32 v1, v1, v17
	v_mul_f32_e32 v0, v1, v0
	v_mul_f32_e32 v1, 0xbfb8aa3b, v2
	v_exp_f32_e32 v1, v1
	v_cvt_pk_bf16_f32 v0, v0, s0
	ds_write_b16 v128, v0 offset:26448
	ds_read_u16 v0, v128 offset:26720
	v_add_f32_e32 v1, 1.0, v1
	s_waitcnt lgkmcnt(0)
	v_lshlrev_b32_e32 v0, 16, v0
	v_rcp_f32_e32 v16, v1
	s_nop 0
	v_mul_f32_e32 v1, v2, v16
	v_mul_f32_e32 v0, v1, v0
	v_mul_f32_e32 v1, 0xbfb8aa3b, v3
	v_exp_f32_e32 v1, v1
	v_cvt_pk_bf16_f32 v0, v0, s0
	ds_write_b16 v128, v0 offset:26720
	ds_read_u16 v0, v128 offset:26992
	v_add_f32_e32 v1, 1.0, v1
	s_waitcnt lgkmcnt(0)
	v_lshlrev_b32_e32 v0, 16, v0
	v_rcp_f32_e32 v2, v1
	s_nop 0
	v_mul_f32_e32 v1, v3, v2
	v_mul_f32_e32 v0, v1, v0
	v_mul_f32_e32 v1, 0xbfb8aa3b, v4
	v_exp_f32_e32 v1, v1
	v_cvt_pk_bf16_f32 v0, v0, s0
	ds_write_b16 v128, v0 offset:26992
	ds_read_u16 v0, v128 offset:28352
	v_add_f32_e32 v1, 1.0, v1
	s_waitcnt lgkmcnt(0)
	v_lshlrev_b32_e32 v0, 16, v0
	v_rcp_f32_e32 v2, v1
	s_nop 0
	v_mul_f32_e32 v1, v4, v2
	v_mul_f32_e32 v0, v1, v0
	v_mul_f32_e32 v1, 0xbfb8aa3b, v5
	v_exp_f32_e32 v1, v1
	v_cvt_pk_bf16_f32 v0, v0, s0
	ds_write_b16 v128, v0 offset:28352
	ds_read_u16 v0, v128 offset:28624
	v_add_f32_e32 v1, 1.0, v1
	s_waitcnt lgkmcnt(0)
	v_lshlrev_b32_e32 v0, 16, v0
	v_rcp_f32_e32 v2, v1
	s_nop 0
	v_mul_f32_e32 v1, v5, v2
	v_mul_f32_e32 v0, v1, v0
	v_mul_f32_e32 v1, 0xbfb8aa3b, v6
	v_exp_f32_e32 v1, v1
	v_cvt_pk_bf16_f32 v0, v0, s0
	ds_write_b16 v128, v0 offset:28624
	ds_read_u16 v0, v128 offset:28896
	v_add_f32_e32 v1, 1.0, v1
	s_waitcnt lgkmcnt(0)
	v_lshlrev_b32_e32 v0, 16, v0
	v_rcp_f32_e32 v2, v1
	s_nop 0
	v_mul_f32_e32 v1, v6, v2
	v_mul_f32_e32 v0, v1, v0
	v_mul_f32_e32 v1, 0xbfb8aa3b, v7
	v_exp_f32_e32 v1, v1
	v_cvt_pk_bf16_f32 v0, v0, s0
	ds_write_b16 v128, v0 offset:28896
	ds_read_u16 v0, v128 offset:29168
	v_add_f32_e32 v1, 1.0, v1
	s_waitcnt lgkmcnt(0)
	v_lshlrev_b32_e32 v0, 16, v0
	v_rcp_f32_e32 v2, v1
	s_nop 0
	v_mul_f32_e32 v1, v7, v2
	v_mul_f32_e32 v0, v1, v0
	v_mul_f32_e32 v1, 0xbfb8aa3b, v8
	v_exp_f32_e32 v1, v1
	v_cvt_pk_bf16_f32 v0, v0, s0
	ds_write_b16 v128, v0 offset:29168
	ds_read_u16 v0, v128 offset:30528
	v_add_f32_e32 v1, 1.0, v1
	s_waitcnt lgkmcnt(0)
	v_lshlrev_b32_e32 v0, 16, v0
	v_rcp_f32_e32 v2, v1
	s_nop 0
	v_mul_f32_e32 v1, v8, v2
	v_mul_f32_e32 v0, v1, v0
	v_mul_f32_e32 v1, 0xbfb8aa3b, v9
	v_exp_f32_e32 v1, v1
	v_cvt_pk_bf16_f32 v0, v0, s0
	ds_write_b16 v128, v0 offset:30528
	ds_read_u16 v0, v128 offset:30800
	v_add_f32_e32 v1, 1.0, v1
	s_waitcnt lgkmcnt(0)
	v_lshlrev_b32_e32 v0, 16, v0
	v_rcp_f32_e32 v2, v1
	s_nop 0
	v_mul_f32_e32 v1, v9, v2
	v_mul_f32_e32 v0, v1, v0
	v_mul_f32_e32 v1, 0xbfb8aa3b, v10
	v_exp_f32_e32 v1, v1
	v_cvt_pk_bf16_f32 v0, v0, s0
	ds_write_b16 v128, v0 offset:30800
	ds_read_u16 v0, v128 offset:31072
	v_add_f32_e32 v1, 1.0, v1
	s_waitcnt lgkmcnt(0)
	v_lshlrev_b32_e32 v0, 16, v0
	v_rcp_f32_e32 v2, v1
	s_nop 0
	v_mul_f32_e32 v1, v10, v2
	v_mul_f32_e32 v0, v1, v0
	v_mul_f32_e32 v1, 0xbfb8aa3b, v11
	v_exp_f32_e32 v1, v1
	v_cvt_pk_bf16_f32 v0, v0, s0
	ds_write_b16 v128, v0 offset:31072
	ds_read_u16 v0, v128 offset:31344
	v_add_f32_e32 v1, 1.0, v1
	s_waitcnt lgkmcnt(0)
	v_lshlrev_b32_e32 v0, 16, v0
	v_rcp_f32_e32 v2, v1
	s_nop 0
	v_mul_f32_e32 v1, v11, v2
	v_mul_f32_e32 v0, v1, v0
	v_mul_f32_e32 v1, 0xbfb8aa3b, v12
	v_exp_f32_e32 v1, v1
	v_cvt_pk_bf16_f32 v0, v0, s0
	ds_write_b16 v128, v0 offset:31344
	ds_read_u16 v0, v128 offset:32704
	v_add_f32_e32 v1, 1.0, v1
	s_waitcnt lgkmcnt(0)
	v_lshlrev_b32_e32 v0, 16, v0
	v_rcp_f32_e32 v2, v1
	s_nop 0
	v_mul_f32_e32 v1, v12, v2
	v_mul_f32_e32 v0, v1, v0
	v_mul_f32_e32 v1, 0xbfb8aa3b, v13
	v_exp_f32_e32 v1, v1
	v_cvt_pk_bf16_f32 v0, v0, s0
	ds_write_b16 v128, v0 offset:32704
	ds_read_u16 v0, v128 offset:32976
	v_add_f32_e32 v1, 1.0, v1
	s_waitcnt lgkmcnt(0)
	v_lshlrev_b32_e32 v0, 16, v0
	v_rcp_f32_e32 v2, v1
	s_nop 0
	v_mul_f32_e32 v1, v13, v2
	v_mul_f32_e32 v0, v1, v0
	v_mul_f32_e32 v1, 0xbfb8aa3b, v14
	v_exp_f32_e32 v1, v1
	v_cvt_pk_bf16_f32 v0, v0, s0
	ds_write_b16 v128, v0 offset:32976
	ds_read_u16 v0, v128 offset:33248
	v_add_f32_e32 v1, 1.0, v1
	s_waitcnt lgkmcnt(0)
	v_lshlrev_b32_e32 v0, 16, v0
	v_rcp_f32_e32 v2, v1
	s_nop 0
	v_mul_f32_e32 v1, v14, v2
	v_mul_f32_e32 v0, v1, v0
	v_mul_f32_e32 v1, 0xbfb8aa3b, v15
	v_exp_f32_e32 v1, v1
	v_cvt_pk_bf16_f32 v0, v0, s0
	ds_write_b16 v128, v0 offset:33248
	ds_read_u16 v0, v128 offset:33520
	v_add_f32_e32 v1, 1.0, v1
	s_waitcnt lgkmcnt(0)
	v_lshlrev_b32_e32 v0, 16, v0
	v_rcp_f32_e32 v2, v1
	s_nop 0
	v_mul_f32_e32 v1, v15, v2
	v_mul_f32_e32 v0, v1, v0
	v_cvt_pk_bf16_f32 v0, v0, s0
	s_lshl_b64 s[0:1], s[4:5], 1
	s_add_u32 s0, s17, s0
	s_addc_u32 s1, s18, s1
	s_lshl_b32 s4, s37, 8
	s_add_u32 s4, s0, s4
	ds_write_b16 v128, v0 offset:33520
	s_addc_u32 s5, s1, 0
	v_mov_b32_e32 v0, v232
	s_waitcnt lgkmcnt(0)
	s_barrier

; DEV u16 f2bf(float f) { return (u16)(pk2bf(f, 0.f) & 0xffffu); }
; DEV float bf2f(u16 h) { return __uint_as_float(((unsigned)h) << 16); }
; DEV float siluf_(float x) { return x / (1.0f + __expf(-x)); }
; template <int MI>
; DEV void tile_load_t(unsigned char* smem, const u16* src, size_t lds_) {
;   u16* sC = (u16*)smem;
;   const int tid_ = TIDX();
; #pragma unroll
;   for (int i = 0; i < MI * 4; ++i) {
;     const int c = tid_ + 256 * i, row = c >> 4, cc = (c & 15) * 8;
;     *(bf16x8*)(sC + row * LDC + cc) = __builtin_nontemporal_load((const bf16x8*)(src + (size_t)row * lds_ + cc));
;   }
;   __syncthreads();
; template <int MI>
; DEV void p4_tile(const Params& p, int l, int m0, int nt, unsigned char* smem) {
;     ...
;     tile_load_t<MI>(smem, YA + (size_t)m0 * 1024 + n0, 1024);
;     acc_foreach_t<MI>([&](int mi, int ni, int r, int row, int col) __attribute__((always_inline)) {
;       sC[row * LDC + col] = f2bf(bf2f(sC[row * LDC + col]) * siluf_(acc[mi][ni][r]));
;     });
.LBB0_1218:
	s_lshl_b64 s[4:5], s[4:5], 1
	s_add_u32 s1, s15, s4
	s_addc_u32 s6, s16, s5
	s_lshl_b64 s[4:5], s[96:97], 1
	s_waitcnt vmcnt(11)
	v_mov_b32_e32 v136, v232
	s_barrier
	s_add_u32 s4, s1, s4
	s_addc_u32 s5, s6, s5
	s_waitcnt vmcnt(10)
	v_lshlrev_b32_e32 v128, 4, v136
	s_waitcnt vmcnt(9)
	v_ashrrev_i32_e32 v134, 4, v136
	v_and_b32_e32 v224, 0xf0, v128
	v_ashrrev_i32_e32 v135, 31, v134
	v_lshl_add_u64 v[128:129], s[4:5], 0, v[224:225]
	v_lshlrev_b64 v[204:205], 11, v[134:135]
	v_lshl_add_u64 v[204:205], v[128:129], 0, v[204:205]
	v_mad_u64_u32 v[206:207], s[6:7], v134, s42, v[224:225]
	s_mov_b32 s6, 0x8000
	s_mov_b32 s7, 0
	global_load_dwordx4 v[140:143], v[204:205], off nt
	v_lshl_add_u64 v[204:205], v[204:205], 0, s[6:7]
	global_load_dwordx4 v[144:147], v[204:205], off nt
	v_lshl_add_u64 v[204:205], v[204:205], 0, s[6:7]
	global_load_dwordx4 v[148:151], v[204:205], off nt
	v_lshl_add_u64 v[204:205], v[204:205], 0, s[6:7]
	global_load_dwordx4 v[152:155], v[204:205], off nt
	v_lshl_add_u64 v[204:205], v[204:205], 0, s[6:7]
	global_load_dwordx4 v[156:159], v[204:205], off nt
	v_lshl_add_u64 v[204:205], v[204:205], 0, s[6:7]
	global_load_dwordx4 v[160:163], v[204:205], off nt
	v_lshl_add_u64 v[204:205], v[204:205], 0, s[6:7]
	global_load_dwordx4 v[164:167], v[204:205], off nt
	v_lshl_add_u64 v[204:205], v[204:205], 0, s[6:7]
	global_load_dwordx4 v[168:171], v[204:205], off nt
	v_lshl_add_u64 v[204:205], v[204:205], 0, s[6:7]
	global_load_dwordx4 v[172:175], v[204:205], off nt
	v_lshl_add_u64 v[204:205], v[204:205], 0, s[6:7]
	global_load_dwordx4 v[176:179], v[204:205], off nt
	v_lshl_add_u64 v[204:205], v[204:205], 0, s[6:7]
	global_load_dwordx4 v[180:183], v[204:205], off nt
	v_lshl_add_u64 v[204:205], v[204:205], 0, s[6:7]
	global_load_dwordx4 v[184:187], v[204:205], off nt
	v_lshl_add_u64 v[204:205], v[204:205], 0, s[6:7]
	global_load_dwordx4 v[188:191], v[204:205], off nt
	v_lshl_add_u64 v[204:205], v[204:205], 0, s[6:7]
	global_load_dwordx4 v[192:195], v[204:205], off nt
	v_lshl_add_u64 v[204:205], v[204:205], 0, s[6:7]
	global_load_dwordx4 v[196:199], v[204:205], off nt
	v_lshl_add_u64 v[204:205], v[204:205], 0, s[6:7]
	global_load_dwordx4 v[200:203], v[204:205], off nt
	s_waitcnt vmcnt(15)
	ds_write_b128 v206, v[140:143]
	s_waitcnt vmcnt(14)
	ds_write_b128 v206, v[144:147] offset:4352
	s_waitcnt vmcnt(13)
	ds_write_b128 v206, v[148:151] offset:8704
	s_waitcnt vmcnt(12)
	ds_write_b128 v206, v[152:155] offset:13056
	s_waitcnt vmcnt(11)
	ds_write_b128 v206, v[156:159] offset:17408
	s_waitcnt vmcnt(10)
	ds_write_b128 v206, v[160:163] offset:21760
	s_waitcnt vmcnt(9)
	ds_write_b128 v206, v[164:167] offset:26112
	s_waitcnt vmcnt(8)
	ds_write_b128 v206, v[168:171] offset:30464
	s_waitcnt vmcnt(7)
	ds_write_b128 v206, v[172:175] offset:34816
	s_waitcnt vmcnt(6)
	ds_write_b128 v206, v[176:179] offset:39168
	s_waitcnt vmcnt(5)
	ds_write_b128 v206, v[180:183] offset:43520
	s_waitcnt vmcnt(4)
	ds_write_b128 v206, v[184:187] offset:47872
	s_waitcnt vmcnt(3)
	ds_write_b128 v206, v[188:191] offset:52224
	s_waitcnt vmcnt(2)
	ds_write_b128 v206, v[192:195] offset:56576
	s_waitcnt vmcnt(1)
	ds_write_b128 v206, v[196:199] offset:60928
	s_waitcnt vmcnt(0)
	ds_write_b128 v206, v[200:203] offset:65280
	v_mov_b32_e32 v128, v232
	s_waitcnt lgkmcnt(0)
	s_barrier
	s_nop 0
	v_and_b32_e32 v129, 0xfffff80, v128
	v_lshrrev_b32_e32 v130, 3, v128
	v_and_or_b32 v129, v130, 4, v129
	v_mul_f32_e32 v130, 0xbfb8aa3b, v112
	v_exp_f32_e32 v130, v130
	v_and_b32_e32 v128, 0x5f, v128
	v_mul_lo_u32 v129, v129, s42
	v_lshl_add_u32 v128, v128, 1, v129
	v_add_f32_e32 v130, 1.0, v130
	ds_read_u16 v129, v128
	s_waitcnt lgkmcnt(0)
	v_lshlrev_b32_e32 v129, 16, v129
	v_rcp_f32_e32 v131, v130
	s_nop 0
	v_mul_f32_e32 v112, v112, v131
	v_mul_f32_e32 v112, v112, v129
	v_mul_f32_e32 v129, 0xbfb8aa3b, v113
	v_exp_f32_e32 v129, v129
	v_cvt_pk_bf16_f32 v112, v112, s0
	ds_write_b16 v128, v112
	ds_read_u16 v112, v128 offset:272
	v_add_f32_e32 v129, 1.0, v129
	s_waitcnt lgkmcnt(0)
	v_lshlrev_b32_e32 v112, 16, v112
	v_rcp_f32_e32 v130, v129
	s_nop 0
	v_mul_f32_e32 v113, v113, v130
	v_mul_f32_e32 v112, v113, v112
	v_mul_f32_e32 v113, 0xbfb8aa3b, v114
	v_exp_f32_e32 v113, v113
	v_cvt_pk_bf16_f32 v112, v112, s0
	ds_write_b16 v128, v112 offset:272
	ds_read_u16 v112, v128 offset:544
	v_add_f32_e32 v113, 1.0, v113
	s_waitcnt lgkmcnt(0)
	v_lshlrev_b32_e32 v112, 16, v112
	v_rcp_f32_e32 v129, v113
	s_nop 0
	v_mul_f32_e32 v113, v114, v129
	v_mul_f32_e32 v112, v113, v112
	v_mul_f32_e32 v113, 0xbfb8aa3b, v115
	v_exp_f32_e32 v113, v113
	v_cvt_pk_bf16_f32 v112, v112, s0
	ds_write_b16 v128, v112 offset:544
	ds_read_u16 v112, v128 offset:816
	v_add_f32_e32 v113, 1.0, v113
	s_waitcnt lgkmcnt(0)
	v_lshlrev_b32_e32 v112, 16, v112
	v_rcp_f32_e32 v114, v113
	s_nop 0
	v_mul_f32_e32 v113, v115, v114
	v_mul_f32_e32 v112, v113, v112
	v_mul_f32_e32 v113, 0xbfb8aa3b, v116
	v_exp_f32_e32 v113, v113
	v_cvt_pk_bf16_f32 v112, v112, s0
	ds_write_b16 v128, v112 offset:816
	ds_read_u16 v112, v128 offset:2176
	v_add_f32_e32 v113, 1.0, v113
	s_waitcnt lgkmcnt(0)
	v_lshlrev_b32_e32 v112, 16, v112
	v_rcp_f32_e32 v114, v113
	s_nop 0
	v_mul_f32_e32 v113, v116, v114
	v_mul_f32_e32 v112, v113, v112
	v_mul_f32_e32 v113, 0xbfb8aa3b, v117
	v_exp_f32_e32 v113, v113
	v_cvt_pk_bf16_f32 v112, v112, s0
	ds_write_b16 v128, v112 offset:2176
	ds_read_u16 v112, v128 offset:2448
	v_add_f32_e32 v113, 1.0, v113
	s_waitcnt lgkmcnt(0)
	v_lshlrev_b32_e32 v112, 16, v112
	v_rcp_f32_e32 v114, v113
	s_nop 0
	v_mul_f32_e32 v113, v117, v114
	v_mul_f32_e32 v112, v113, v112
	v_mul_f32_e32 v113, 0xbfb8aa3b, v118
	v_exp_f32_e32 v113, v113
	v_cvt_pk_bf16_f32 v112, v112, s0
	ds_write_b16 v128, v112 offset:2448
	ds_read_u16 v112, v128 offset:2720
	v_add_f32_e32 v113, 1.0, v113
	s_waitcnt lgkmcnt(0)
; DEV u16 f2bf(float f) { return (u16)(pk2bf(f, 0.f) & 0xffffu); }
; DEV float bf2f(u16 h) { return __uint_as_float(((unsigned)h) << 16); }
; DEV float siluf_(float x) { return x / (1.0f + __expf(-x)); }
; template <int MI>
; DEV void p4_tile(const Params& p, int l, int m0, int nt, unsigned char* smem) {
;     ...
;     acc_foreach_t<MI>([&](int mi, int ni, int r, int row, int col) __attribute__((always_inline)) {
;       sC[row * LDC + col] = f2bf(bf2f(sC[row * LDC + col]) * siluf_(acc[mi][ni][r]));
;     });
	v_lshlrev_b32_e32 v112, 16, v112
	v_rcp_f32_e32 v114, v113
	s_nop 0
	v_mul_f32_e32 v113, v118, v114
	v_mul_f32_e32 v112, v113, v112
	v_mul_f32_e32 v113, 0xbfb8aa3b, v119
	v_exp_f32_e32 v113, v113
	v_cvt_pk_bf16_f32 v112, v112, s0
	ds_write_b16 v128, v112 offset:2720
	ds_read_u16 v112, v128 offset:2992
	v_add_f32_e32 v113, 1.0, v113
	s_waitcnt lgkmcnt(0)
	v_lshlrev_b32_e32 v112, 16, v112
	v_rcp_f32_e32 v114, v113
	s_nop 0
	v_mul_f32_e32 v113, v119, v114
	v_mul_f32_e32 v112, v113, v112
	v_mul_f32_e32 v113, 0xbfb8aa3b, v120
	v_exp_f32_e32 v113, v113
	v_cvt_pk_bf16_f32 v112, v112, s0
	ds_write_b16 v128, v112 offset:2992
	ds_read_u16 v112, v128 offset:4352
	v_add_f32_e32 v113, 1.0, v113
	s_waitcnt lgkmcnt(0)
	v_lshlrev_b32_e32 v112, 16, v112
	v_rcp_f32_e32 v114, v113
	s_nop 0
	v_mul_f32_e32 v113, v120, v114
	v_mul_f32_e32 v112, v113, v112
	v_mul_f32_e32 v113, 0xbfb8aa3b, v121
	v_exp_f32_e32 v113, v113
	v_cvt_pk_bf16_f32 v112, v112, s0
	ds_write_b16 v128, v112 offset:4352
	ds_read_u16 v112, v128 offset:4624
	v_add_f32_e32 v113, 1.0, v113
	s_waitcnt lgkmcnt(0)
	v_lshlrev_b32_e32 v112, 16, v112
	v_rcp_f32_e32 v114, v113
	s_nop 0
	v_mul_f32_e32 v113, v121, v114
	v_mul_f32_e32 v112, v113, v112
	v_mul_f32_e32 v113, 0xbfb8aa3b, v122
	v_exp_f32_e32 v113, v113
	v_cvt_pk_bf16_f32 v112, v112, s0
	ds_write_b16 v128, v112 offset:4624
	ds_read_u16 v112, v128 offset:4896
	v_add_f32_e32 v113, 1.0, v113
	s_waitcnt lgkmcnt(0)
	v_lshlrev_b32_e32 v112, 16, v112
	v_rcp_f32_e32 v114, v113
	s_nop 0
	v_mul_f32_e32 v113, v122, v114
	v_mul_f32_e32 v112, v113, v112
	v_mul_f32_e32 v113, 0xbfb8aa3b, v123
	v_exp_f32_e32 v113, v113
	v_cvt_pk_bf16_f32 v112, v112, s0
	ds_write_b16 v128, v112 offset:4896
	ds_read_u16 v112, v128 offset:5168
	v_add_f32_e32 v113, 1.0, v113
	s_waitcnt lgkmcnt(0)
	v_lshlrev_b32_e32 v112, 16, v112
	v_rcp_f32_e32 v114, v113
	s_nop 0
	v_mul_f32_e32 v113, v123, v114
	v_mul_f32_e32 v112, v113, v112
	v_mul_f32_e32 v113, 0xbfb8aa3b, v124
	v_exp_f32_e32 v113, v113
	v_cvt_pk_bf16_f32 v112, v112, s0
	ds_write_b16 v128, v112 offset:5168
	ds_read_u16 v112, v128 offset:6528
	v_add_f32_e32 v113, 1.0, v113
	s_waitcnt lgkmcnt(0)
	v_lshlrev_b32_e32 v112, 16, v112
	v_rcp_f32_e32 v114, v113
	s_nop 0
	v_mul_f32_e32 v113, v124, v114
	v_mul_f32_e32 v112, v113, v112
	v_mul_f32_e32 v113, 0xbfb8aa3b, v125
	v_exp_f32_e32 v113, v113
	v_cvt_pk_bf16_f32 v112, v112, s0
	ds_write_b16 v128, v112 offset:6528
	ds_read_u16 v112, v128 offset:6800
	v_add_f32_e32 v113, 1.0, v113
	s_waitcnt lgkmcnt(0)
	v_lshlrev_b32_e32 v112, 16, v112
	v_rcp_f32_e32 v114, v113
	s_nop 0
	v_mul_f32_e32 v113, v125, v114
	v_mul_f32_e32 v112, v113, v112
	v_mul_f32_e32 v113, 0xbfb8aa3b, v126
	v_exp_f32_e32 v113, v113
	v_cvt_pk_bf16_f32 v112, v112, s0
	ds_write_b16 v128, v112 offset:6800
	ds_read_u16 v112, v128 offset:7072
	v_add_f32_e32 v113, 1.0, v113
	s_waitcnt lgkmcnt(0)
	v_lshlrev_b32_e32 v112, 16, v112
	v_rcp_f32_e32 v114, v113
	s_nop 0
	v_mul_f32_e32 v113, v126, v114
	v_mul_f32_e32 v112, v113, v112
	v_mul_f32_e32 v113, 0xbfb8aa3b, v127
	v_exp_f32_e32 v113, v113
	v_cvt_pk_bf16_f32 v112, v112, s0
	ds_write_b16 v128, v112 offset:7072
	ds_read_u16 v112, v128 offset:7344
	v_add_f32_e32 v113, 1.0, v113
	s_waitcnt lgkmcnt(0)
	v_lshlrev_b32_e32 v112, 16, v112
	v_rcp_f32_e32 v114, v113
	s_nop 0
	v_mul_f32_e32 v113, v127, v114
	v_mul_f32_e32 v112, v113, v112
	v_mul_f32_e32 v113, 0xbfb8aa3b, v96
	v_exp_f32_e32 v113, v113
	v_cvt_pk_bf16_f32 v112, v112, s0
	ds_write_b16 v128, v112 offset:7344
	ds_read_u16 v112, v128 offset:64
	v_add_f32_e32 v113, 1.0, v113
	s_waitcnt lgkmcnt(0)
	v_lshlrev_b32_e32 v112, 16, v112
	v_rcp_f32_e32 v114, v113
	s_nop 0
	v_mul_f32_e32 v96, v96, v114
	v_mul_f32_e32 v96, v96, v112
	v_mul_f32_e32 v112, 0xbfb8aa3b, v97
	v_exp_f32_e32 v112, v112
	v_cvt_pk_bf16_f32 v96, v96, s0
	ds_write_b16 v128, v96 offset:64
	ds_read_u16 v96, v128 offset:336
	v_add_f32_e32 v112, 1.0, v112
	s_waitcnt lgkmcnt(0)
	v_lshlrev_b32_e32 v96, 16, v96
	v_rcp_f32_e32 v113, v112
	s_nop 0
	v_mul_f32_e32 v97, v97, v113
	v_mul_f32_e32 v96, v97, v96
	v_mul_f32_e32 v97, 0xbfb8aa3b, v98
	v_exp_f32_e32 v97, v97
	v_cvt_pk_bf16_f32 v96, v96, s0
	ds_write_b16 v128, v96 offset:336
	ds_read_u16 v96, v128 offset:608
	v_add_f32_e32 v97, 1.0, v97
	s_waitcnt lgkmcnt(0)
	v_lshlrev_b32_e32 v96, 16, v96
	v_rcp_f32_e32 v112, v97
	s_nop 0
	v_mul_f32_e32 v97, v98, v112
	v_mul_f32_e32 v96, v97, v96
	v_mul_f32_e32 v97, 0xbfb8aa3b, v99
	v_exp_f32_e32 v97, v97
	v_cvt_pk_bf16_f32 v96, v96, s0
	ds_write_b16 v128, v96 offset:608
	ds_read_u16 v96, v128 offset:880
	v_add_f32_e32 v97, 1.0, v97
	s_waitcnt lgkmcnt(0)
	v_lshlrev_b32_e32 v96, 16, v96
	v_rcp_f32_e32 v98, v97
	s_nop 0
	v_mul_f32_e32 v97, v99, v98
	v_mul_f32_e32 v96, v97, v96
	v_mul_f32_e32 v97, 0xbfb8aa3b, v100
	v_exp_f32_e32 v97, v97
	v_cvt_pk_bf16_f32 v96, v96, s0
	ds_write_b16 v128, v96 offset:880
	ds_read_u16 v96, v128 offset:2240
	v_add_f32_e32 v97, 1.0, v97
	s_waitcnt lgkmcnt(0)
	v_lshlrev_b32_e32 v96, 16, v96
	v_rcp_f32_e32 v98, v97
	s_nop 0
	v_mul_f32_e32 v97, v100, v98
	v_mul_f32_e32 v96, v97, v96
	v_mul_f32_e32 v97, 0xbfb8aa3b, v101
	v_exp_f32_e32 v97, v97
	v_cvt_pk_bf16_f32 v96, v96, s0
	ds_write_b16 v128, v96 offset:2240
	ds_read_u16 v96, v128 offset:2512
	v_add_f32_e32 v97, 1.0, v97
	s_waitcnt lgkmcnt(0)
	v_lshlrev_b32_e32 v96, 16, v96
	v_rcp_f32_e32 v98, v97
	s_nop 0
	v_mul_f32_e32 v97, v101, v98
	v_mul_f32_e32 v96, v97, v96
	v_mul_f32_e32 v97, 0xbfb8aa3b, v102
	v_exp_f32_e32 v97, v97
	v_cvt_pk_bf16_f32 v96, v96, s0
	ds_write_b16 v128, v96 offset:2512
	ds_read_u16 v96, v128 offset:2784
	v_add_f32_e32 v97, 1.0, v97
	s_waitcnt lgkmcnt(0)
; DEV u16 f2bf(float f) { return (u16)(pk2bf(f, 0.f) & 0xffffu); }
; DEV float bf2f(u16 h) { return __uint_as_float(((unsigned)h) << 16); }
; DEV float siluf_(float x) { return x / (1.0f + __expf(-x)); }
; template <int MI>
; DEV void p4_tile(const Params& p, int l, int m0, int nt, unsigned char* smem) {
;     ...
;     acc_foreach_t<MI>([&](int mi, int ni, int r, int row, int col) __attribute__((always_inline)) {
;       sC[row * LDC + col] = f2bf(bf2f(sC[row * LDC + col]) * siluf_(acc[mi][ni][r]));
;     });
	v_lshlrev_b32_e32 v96, 16, v96
	v_rcp_f32_e32 v98, v97
	s_nop 0
	v_mul_f32_e32 v97, v102, v98
	v_mul_f32_e32 v96, v97, v96
	v_mul_f32_e32 v97, 0xbfb8aa3b, v103
	v_exp_f32_e32 v97, v97
	v_cvt_pk_bf16_f32 v96, v96, s0
	ds_write_b16 v128, v96 offset:2784
	ds_read_u16 v96, v128 offset:3056
	v_add_f32_e32 v97, 1.0, v97
	s_waitcnt lgkmcnt(0)
	v_lshlrev_b32_e32 v96, 16, v96
	v_rcp_f32_e32 v98, v97
	s_nop 0
	v_mul_f32_e32 v97, v103, v98
	v_mul_f32_e32 v96, v97, v96
	v_mul_f32_e32 v97, 0xbfb8aa3b, v104
	v_exp_f32_e32 v97, v97
	v_cvt_pk_bf16_f32 v96, v96, s0
	ds_write_b16 v128, v96 offset:3056
	ds_read_u16 v96, v128 offset:4416
	v_add_f32_e32 v97, 1.0, v97
	s_waitcnt lgkmcnt(0)
	v_lshlrev_b32_e32 v96, 16, v96
	v_rcp_f32_e32 v98, v97
	s_nop 0
	v_mul_f32_e32 v97, v104, v98
	v_mul_f32_e32 v96, v97, v96
	v_mul_f32_e32 v97, 0xbfb8aa3b, v105
	v_exp_f32_e32 v97, v97
	v_cvt_pk_bf16_f32 v96, v96, s0
	ds_write_b16 v128, v96 offset:4416
	ds_read_u16 v96, v128 offset:4688
	v_add_f32_e32 v97, 1.0, v97
	s_waitcnt lgkmcnt(0)
	v_lshlrev_b32_e32 v96, 16, v96
	v_rcp_f32_e32 v98, v97
	s_nop 0
	v_mul_f32_e32 v97, v105, v98
	v_mul_f32_e32 v96, v97, v96
	v_mul_f32_e32 v97, 0xbfb8aa3b, v106
	v_exp_f32_e32 v97, v97
	v_cvt_pk_bf16_f32 v96, v96, s0
	ds_write_b16 v128, v96 offset:4688
	ds_read_u16 v96, v128 offset:4960
	v_add_f32_e32 v97, 1.0, v97
	s_waitcnt lgkmcnt(0)
	v_lshlrev_b32_e32 v96, 16, v96
	v_rcp_f32_e32 v98, v97
	s_nop 0
	v_mul_f32_e32 v97, v106, v98
	v_mul_f32_e32 v96, v97, v96
	v_mul_f32_e32 v97, 0xbfb8aa3b, v107
	v_exp_f32_e32 v97, v97
	v_cvt_pk_bf16_f32 v96, v96, s0
	ds_write_b16 v128, v96 offset:4960
	ds_read_u16 v96, v128 offset:5232
	v_add_f32_e32 v97, 1.0, v97
	s_waitcnt lgkmcnt(0)
	v_lshlrev_b32_e32 v96, 16, v96
	v_rcp_f32_e32 v98, v97
	s_nop 0
	v_mul_f32_e32 v97, v107, v98
	v_mul_f32_e32 v96, v97, v96
	v_mul_f32_e32 v97, 0xbfb8aa3b, v108
	v_exp_f32_e32 v97, v97
	v_cvt_pk_bf16_f32 v96, v96, s0
	ds_write_b16 v128, v96 offset:5232
	ds_read_u16 v96, v128 offset:6592
	v_add_f32_e32 v97, 1.0, v97
	s_waitcnt lgkmcnt(0)
	v_lshlrev_b32_e32 v96, 16, v96
	v_rcp_f32_e32 v98, v97
	s_nop 0
	v_mul_f32_e32 v97, v108, v98
	v_mul_f32_e32 v96, v97, v96
	v_mul_f32_e32 v97, 0xbfb8aa3b, v109
	v_exp_f32_e32 v97, v97
	v_cvt_pk_bf16_f32 v96, v96, s0
	ds_write_b16 v128, v96 offset:6592
	ds_read_u16 v96, v128 offset:6864
	v_add_f32_e32 v97, 1.0, v97
	s_waitcnt lgkmcnt(0)
	v_lshlrev_b32_e32 v96, 16, v96
	v_rcp_f32_e32 v98, v97
	s_nop 0
	v_mul_f32_e32 v97, v109, v98
	v_mul_f32_e32 v96, v97, v96
	v_mul_f32_e32 v97, 0xbfb8aa3b, v110
	v_exp_f32_e32 v97, v97
	v_cvt_pk_bf16_f32 v96, v96, s0
	ds_write_b16 v128, v96 offset:6864
	ds_read_u16 v96, v128 offset:7136
	v_add_f32_e32 v97, 1.0, v97
	s_waitcnt lgkmcnt(0)
	v_lshlrev_b32_e32 v96, 16, v96
	v_rcp_f32_e32 v98, v97
	s_nop 0
	v_mul_f32_e32 v97, v110, v98
	v_mul_f32_e32 v96, v97, v96
	v_mul_f32_e32 v97, 0xbfb8aa3b, v111
	v_exp_f32_e32 v97, v97
	v_cvt_pk_bf16_f32 v96, v96, s0
	ds_write_b16 v128, v96 offset:7136
	ds_read_u16 v96, v128 offset:7408
	v_add_f32_e32 v97, 1.0, v97
	s_waitcnt lgkmcnt(0)
	v_lshlrev_b32_e32 v96, 16, v96
	v_rcp_f32_e32 v98, v97
	s_nop 0
	v_mul_f32_e32 v97, v111, v98
	v_mul_f32_e32 v96, v97, v96
	v_mul_f32_e32 v97, 0xbfb8aa3b, v80
	v_exp_f32_e32 v97, v97
	v_cvt_pk_bf16_f32 v96, v96, s0
	ds_write_b16 v128, v96 offset:7408
	ds_read_u16 v96, v128 offset:8704
	v_add_f32_e32 v97, 1.0, v97
	s_waitcnt lgkmcnt(0)
	v_lshlrev_b32_e32 v96, 16, v96
	v_rcp_f32_e32 v98, v97
	s_nop 0
	v_mul_f32_e32 v80, v80, v98
	v_mul_f32_e32 v80, v80, v96
	v_mul_f32_e32 v96, 0xbfb8aa3b, v81
	v_exp_f32_e32 v96, v96
	v_cvt_pk_bf16_f32 v80, v80, s0
	ds_write_b16 v128, v80 offset:8704
	ds_read_u16 v80, v128 offset:8976
	v_add_f32_e32 v96, 1.0, v96
	s_waitcnt lgkmcnt(0)
	v_lshlrev_b32_e32 v80, 16, v80
	v_rcp_f32_e32 v97, v96
	s_nop 0
	v_mul_f32_e32 v81, v81, v97
	v_mul_f32_e32 v80, v81, v80
	v_mul_f32_e32 v81, 0xbfb8aa3b, v82
	v_exp_f32_e32 v81, v81
	v_cvt_pk_bf16_f32 v80, v80, s0
	ds_write_b16 v128, v80 offset:8976
	ds_read_u16 v80, v128 offset:9248
	v_add_f32_e32 v81, 1.0, v81
	s_waitcnt lgkmcnt(0)
	v_lshlrev_b32_e32 v80, 16, v80
	v_rcp_f32_e32 v96, v81
	s_nop 0
	v_mul_f32_e32 v81, v82, v96
	v_mul_f32_e32 v80, v81, v80
	v_mul_f32_e32 v81, 0xbfb8aa3b, v83
	v_exp_f32_e32 v81, v81
	v_cvt_pk_bf16_f32 v80, v80, s0
	ds_write_b16 v128, v80 offset:9248
	ds_read_u16 v80, v128 offset:9520
	v_add_f32_e32 v81, 1.0, v81
	s_waitcnt lgkmcnt(0)
	v_lshlrev_b32_e32 v80, 16, v80
	v_rcp_f32_e32 v82, v81
	s_nop 0
	v_mul_f32_e32 v81, v83, v82
	v_mul_f32_e32 v80, v81, v80
	v_mul_f32_e32 v81, 0xbfb8aa3b, v84
	v_exp_f32_e32 v81, v81
	v_cvt_pk_bf16_f32 v80, v80, s0
	ds_write_b16 v128, v80 offset:9520
	ds_read_u16 v80, v128 offset:10880
	v_add_f32_e32 v81, 1.0, v81
	s_waitcnt lgkmcnt(0)
	v_lshlrev_b32_e32 v80, 16, v80
	v_rcp_f32_e32 v82, v81
	s_nop 0
	v_mul_f32_e32 v81, v84, v82
	v_mul_f32_e32 v80, v81, v80
	v_mul_f32_e32 v81, 0xbfb8aa3b, v85
	v_exp_f32_e32 v81, v81
	v_cvt_pk_bf16_f32 v80, v80, s0
	ds_write_b16 v128, v80 offset:10880
	ds_read_u16 v80, v128 offset:11152
	v_add_f32_e32 v81, 1.0, v81
	s_waitcnt lgkmcnt(0)
	v_lshlrev_b32_e32 v80, 16, v80
	v_rcp_f32_e32 v82, v81
	s_nop 0
	v_mul_f32_e32 v81, v85, v82
	v_mul_f32_e32 v80, v81, v80
	v_mul_f32_e32 v81, 0xbfb8aa3b, v86
	v_exp_f32_e32 v81, v81
	v_cvt_pk_bf16_f32 v80, v80, s0
	ds_write_b16 v128, v80 offset:11152
	ds_read_u16 v80, v128 offset:11424
	v_add_f32_e32 v81, 1.0, v81
	s_waitcnt lgkmcnt(0)
	v_lshlrev_b32_e32 v80, 16, v80
	v_rcp_f32_e32 v82, v81
	s_nop 0
	v_mul_f32_e32 v81, v86, v82
	v_mul_f32_e32 v80, v81, v80
	v_mul_f32_e32 v81, 0xbfb8aa3b, v87
	v_exp_f32_e32 v81, v81
	v_cvt_pk_bf16_f32 v80, v80, s0
	ds_write_b16 v128, v80 offset:11424
	ds_read_u16 v80, v128 offset:11696
	v_add_f32_e32 v81, 1.0, v81
	s_waitcnt lgkmcnt(0)
; DEV u16 f2bf(float f) { return (u16)(pk2bf(f, 0.f) & 0xffffu); }
; DEV float bf2f(u16 h) { return __uint_as_float(((unsigned)h) << 16); }
; DEV float siluf_(float x) { return x / (1.0f + __expf(-x)); }
; template <int MI>
; DEV void p4_tile(const Params& p, int l, int m0, int nt, unsigned char* smem) {
;     ...
;     acc_foreach_t<MI>([&](int mi, int ni, int r, int row, int col) __attribute__((always_inline)) {
;       sC[row * LDC + col] = f2bf(bf2f(sC[row * LDC + col]) * siluf_(acc[mi][ni][r]));
;     });
	v_lshlrev_b32_e32 v80, 16, v80
	v_rcp_f32_e32 v82, v81
	s_nop 0
	v_mul_f32_e32 v81, v87, v82
	v_mul_f32_e32 v80, v81, v80
	v_mul_f32_e32 v81, 0xbfb8aa3b, v88
	v_exp_f32_e32 v81, v81
	v_cvt_pk_bf16_f32 v80, v80, s0
	ds_write_b16 v128, v80 offset:11696
	ds_read_u16 v80, v128 offset:13056
	v_add_f32_e32 v81, 1.0, v81
	s_waitcnt lgkmcnt(0)
	v_lshlrev_b32_e32 v80, 16, v80
	v_rcp_f32_e32 v82, v81
	s_nop 0
	v_mul_f32_e32 v81, v88, v82
	v_mul_f32_e32 v80, v81, v80
	v_mul_f32_e32 v81, 0xbfb8aa3b, v89
	v_exp_f32_e32 v81, v81
	v_cvt_pk_bf16_f32 v80, v80, s0
	ds_write_b16 v128, v80 offset:13056
	ds_read_u16 v80, v128 offset:13328
	v_add_f32_e32 v81, 1.0, v81
	s_waitcnt lgkmcnt(0)
	v_lshlrev_b32_e32 v80, 16, v80
	v_rcp_f32_e32 v82, v81
	s_nop 0
	v_mul_f32_e32 v81, v89, v82
	v_mul_f32_e32 v80, v81, v80
	v_mul_f32_e32 v81, 0xbfb8aa3b, v90
	v_exp_f32_e32 v81, v81
	v_cvt_pk_bf16_f32 v80, v80, s0
	ds_write_b16 v128, v80 offset:13328
	ds_read_u16 v80, v128 offset:13600
	v_add_f32_e32 v81, 1.0, v81
	s_waitcnt lgkmcnt(0)
	v_lshlrev_b32_e32 v80, 16, v80
	v_rcp_f32_e32 v82, v81
	s_nop 0
	v_mul_f32_e32 v81, v90, v82
	v_mul_f32_e32 v80, v81, v80
	v_mul_f32_e32 v81, 0xbfb8aa3b, v91
	v_exp_f32_e32 v81, v81
	v_cvt_pk_bf16_f32 v80, v80, s0
	ds_write_b16 v128, v80 offset:13600
	ds_read_u16 v80, v128 offset:13872
	v_add_f32_e32 v81, 1.0, v81
	s_waitcnt lgkmcnt(0)
	v_lshlrev_b32_e32 v80, 16, v80
	v_rcp_f32_e32 v82, v81
	s_nop 0
	v_mul_f32_e32 v81, v91, v82
	v_mul_f32_e32 v80, v81, v80
	v_mul_f32_e32 v81, 0xbfb8aa3b, v92
	v_exp_f32_e32 v81, v81
	v_cvt_pk_bf16_f32 v80, v80, s0
	ds_write_b16 v128, v80 offset:13872
	ds_read_u16 v80, v128 offset:15232
	v_add_f32_e32 v81, 1.0, v81
	s_waitcnt lgkmcnt(0)
	v_lshlrev_b32_e32 v80, 16, v80
	v_rcp_f32_e32 v82, v81
	s_nop 0
	v_mul_f32_e32 v81, v92, v82
	v_mul_f32_e32 v80, v81, v80
	v_mul_f32_e32 v81, 0xbfb8aa3b, v93
	v_exp_f32_e32 v81, v81
	v_cvt_pk_bf16_f32 v80, v80, s0
	ds_write_b16 v128, v80 offset:15232
	ds_read_u16 v80, v128 offset:15504
	v_add_f32_e32 v81, 1.0, v81
	s_waitcnt lgkmcnt(0)
	v_lshlrev_b32_e32 v80, 16, v80
	v_rcp_f32_e32 v82, v81
	s_nop 0
	v_mul_f32_e32 v81, v93, v82
	v_mul_f32_e32 v80, v81, v80
	v_mul_f32_e32 v81, 0xbfb8aa3b, v94
	v_exp_f32_e32 v81, v81
	v_cvt_pk_bf16_f32 v80, v80, s0
	ds_write_b16 v128, v80 offset:15504
	ds_read_u16 v80, v128 offset:15776
	v_add_f32_e32 v81, 1.0, v81
	s_waitcnt lgkmcnt(0)
	v_lshlrev_b32_e32 v80, 16, v80
	v_rcp_f32_e32 v82, v81
	s_nop 0
	v_mul_f32_e32 v81, v94, v82
	v_mul_f32_e32 v80, v81, v80
	v_mul_f32_e32 v81, 0xbfb8aa3b, v95
	v_exp_f32_e32 v81, v81
	v_cvt_pk_bf16_f32 v80, v80, s0
	ds_write_b16 v128, v80 offset:15776
	ds_read_u16 v80, v128 offset:16048
	v_add_f32_e32 v81, 1.0, v81
	s_waitcnt lgkmcnt(0)
	v_lshlrev_b32_e32 v80, 16, v80
	v_rcp_f32_e32 v82, v81
	s_nop 0
	v_mul_f32_e32 v81, v95, v82
	v_mul_f32_e32 v80, v81, v80
	v_mul_f32_e32 v81, 0xbfb8aa3b, v64
	v_exp_f32_e32 v81, v81
	v_cvt_pk_bf16_f32 v80, v80, s0
	ds_write_b16 v128, v80 offset:16048
	ds_read_u16 v80, v128 offset:8768
	v_add_f32_e32 v81, 1.0, v81
	s_waitcnt lgkmcnt(0)
	v_lshlrev_b32_e32 v80, 16, v80
	v_rcp_f32_e32 v82, v81
	s_nop 0
	v_mul_f32_e32 v64, v64, v82
	v_mul_f32_e32 v64, v64, v80
	v_mul_f32_e32 v80, 0xbfb8aa3b, v65
	v_exp_f32_e32 v80, v80
	v_cvt_pk_bf16_f32 v64, v64, s0
	ds_write_b16 v128, v64 offset:8768
	ds_read_u16 v64, v128 offset:9040
	v_add_f32_e32 v80, 1.0, v80
	s_waitcnt lgkmcnt(0)
	v_lshlrev_b32_e32 v64, 16, v64
	v_rcp_f32_e32 v81, v80
	s_nop 0
	v_mul_f32_e32 v65, v65, v81
	v_mul_f32_e32 v64, v65, v64
	v_mul_f32_e32 v65, 0xbfb8aa3b, v66
	v_exp_f32_e32 v65, v65
	v_cvt_pk_bf16_f32 v64, v64, s0
	ds_write_b16 v128, v64 offset:9040
	ds_read_u16 v64, v128 offset:9312
	v_add_f32_e32 v65, 1.0, v65
	s_waitcnt lgkmcnt(0)
	v_lshlrev_b32_e32 v64, 16, v64
	v_rcp_f32_e32 v80, v65
	s_nop 0
	v_mul_f32_e32 v65, v66, v80
	v_mul_f32_e32 v64, v65, v64
	v_mul_f32_e32 v65, 0xbfb8aa3b, v67
	v_exp_f32_e32 v65, v65
	v_cvt_pk_bf16_f32 v64, v64, s0
	ds_write_b16 v128, v64 offset:9312
	ds_read_u16 v64, v128 offset:9584
	v_add_f32_e32 v65, 1.0, v65
	s_waitcnt lgkmcnt(0)
	v_lshlrev_b32_e32 v64, 16, v64
	v_rcp_f32_e32 v66, v65
	s_nop 0
	v_mul_f32_e32 v65, v67, v66
	v_mul_f32_e32 v64, v65, v64
	v_mul_f32_e32 v65, 0xbfb8aa3b, v68
	v_exp_f32_e32 v65, v65
	v_cvt_pk_bf16_f32 v64, v64, s0
	ds_write_b16 v128, v64 offset:9584
	ds_read_u16 v64, v128 offset:10944
	v_add_f32_e32 v65, 1.0, v65
	s_waitcnt lgkmcnt(0)
	v_lshlrev_b32_e32 v64, 16, v64
	v_rcp_f32_e32 v66, v65
	s_nop 0
	v_mul_f32_e32 v65, v68, v66
	v_mul_f32_e32 v64, v65, v64
	v_mul_f32_e32 v65, 0xbfb8aa3b, v69
	v_exp_f32_e32 v65, v65
	v_cvt_pk_bf16_f32 v64, v64, s0
	ds_write_b16 v128, v64 offset:10944
	ds_read_u16 v64, v128 offset:11216
	v_add_f32_e32 v65, 1.0, v65
	s_waitcnt lgkmcnt(0)
	v_lshlrev_b32_e32 v64, 16, v64
	v_rcp_f32_e32 v66, v65
	s_nop 0
	v_mul_f32_e32 v65, v69, v66
	v_mul_f32_e32 v64, v65, v64
	v_mul_f32_e32 v65, 0xbfb8aa3b, v70
	v_exp_f32_e32 v65, v65
	v_cvt_pk_bf16_f32 v64, v64, s0
	ds_write_b16 v128, v64 offset:11216
	ds_read_u16 v64, v128 offset:11488
	v_add_f32_e32 v65, 1.0, v65
	s_waitcnt lgkmcnt(0)
	v_lshlrev_b32_e32 v64, 16, v64
	v_rcp_f32_e32 v66, v65
	s_nop 0
	v_mul_f32_e32 v65, v70, v66
	v_mul_f32_e32 v64, v65, v64
	v_mul_f32_e32 v65, 0xbfb8aa3b, v71
	v_exp_f32_e32 v65, v65
	v_cvt_pk_bf16_f32 v64, v64, s0
	ds_write_b16 v128, v64 offset:11488
	ds_read_u16 v64, v128 offset:11760
	v_add_f32_e32 v65, 1.0, v65
	s_waitcnt lgkmcnt(0)
	v_lshlrev_b32_e32 v64, 16, v64
	v_rcp_f32_e32 v66, v65
	s_nop 0
	v_mul_f32_e32 v65, v71, v66
	v_mul_f32_e32 v64, v65, v64
	v_mul_f32_e32 v65, 0xbfb8aa3b, v72
	v_exp_f32_e32 v65, v65
	v_cvt_pk_bf16_f32 v64, v64, s0
	ds_write_b16 v128, v64 offset:11760
	ds_read_u16 v64, v128 offset:13120
	v_add_f32_e32 v65, 1.0, v65
	s_waitcnt lgkmcnt(0)
; DEV u16 f2bf(float f) { return (u16)(pk2bf(f, 0.f) & 0xffffu); }
; DEV float bf2f(u16 h) { return __uint_as_float(((unsigned)h) << 16); }
; DEV float siluf_(float x) { return x / (1.0f + __expf(-x)); }
; template <int MI>
; DEV void p4_tile(const Params& p, int l, int m0, int nt, unsigned char* smem) {
;     ...
;     acc_foreach_t<MI>([&](int mi, int ni, int r, int row, int col) __attribute__((always_inline)) {
;       sC[row * LDC + col] = f2bf(bf2f(sC[row * LDC + col]) * siluf_(acc[mi][ni][r]));
;     });
	v_lshlrev_b32_e32 v64, 16, v64
	v_rcp_f32_e32 v66, v65
	s_nop 0
	v_mul_f32_e32 v65, v72, v66
	v_mul_f32_e32 v64, v65, v64
	v_mul_f32_e32 v65, 0xbfb8aa3b, v73
	v_exp_f32_e32 v65, v65
	v_cvt_pk_bf16_f32 v64, v64, s0
	ds_write_b16 v128, v64 offset:13120
	ds_read_u16 v64, v128 offset:13392
	v_add_f32_e32 v65, 1.0, v65
	s_waitcnt lgkmcnt(0)
	v_lshlrev_b32_e32 v64, 16, v64
	v_rcp_f32_e32 v66, v65
	s_nop 0
	v_mul_f32_e32 v65, v73, v66
	v_mul_f32_e32 v64, v65, v64
	v_mul_f32_e32 v65, 0xbfb8aa3b, v74
	v_exp_f32_e32 v65, v65
	v_cvt_pk_bf16_f32 v64, v64, s0
	ds_write_b16 v128, v64 offset:13392
	ds_read_u16 v64, v128 offset:13664
	v_add_f32_e32 v65, 1.0, v65
	s_waitcnt lgkmcnt(0)
	v_lshlrev_b32_e32 v64, 16, v64
	v_rcp_f32_e32 v66, v65
	s_nop 0
	v_mul_f32_e32 v65, v74, v66
	v_mul_f32_e32 v64, v65, v64
	v_mul_f32_e32 v65, 0xbfb8aa3b, v75
	v_exp_f32_e32 v65, v65
	v_cvt_pk_bf16_f32 v64, v64, s0
	ds_write_b16 v128, v64 offset:13664
	ds_read_u16 v64, v128 offset:13936
	v_add_f32_e32 v65, 1.0, v65
	s_waitcnt lgkmcnt(0)
	v_lshlrev_b32_e32 v64, 16, v64
	v_rcp_f32_e32 v66, v65
	s_nop 0
	v_mul_f32_e32 v65, v75, v66
	v_mul_f32_e32 v64, v65, v64
	v_mul_f32_e32 v65, 0xbfb8aa3b, v76
	v_exp_f32_e32 v65, v65
	v_cvt_pk_bf16_f32 v64, v64, s0
	ds_write_b16 v128, v64 offset:13936
	ds_read_u16 v64, v128 offset:15296
	v_add_f32_e32 v65, 1.0, v65
	s_waitcnt lgkmcnt(0)
	v_lshlrev_b32_e32 v64, 16, v64
	v_rcp_f32_e32 v66, v65
	s_nop 0
	v_mul_f32_e32 v65, v76, v66
	v_mul_f32_e32 v64, v65, v64
	v_mul_f32_e32 v65, 0xbfb8aa3b, v77
	v_exp_f32_e32 v65, v65
	v_cvt_pk_bf16_f32 v64, v64, s0
	ds_write_b16 v128, v64 offset:15296
	ds_read_u16 v64, v128 offset:15568
	v_add_f32_e32 v65, 1.0, v65
	s_waitcnt lgkmcnt(0)
	v_lshlrev_b32_e32 v64, 16, v64
	v_rcp_f32_e32 v66, v65
	s_nop 0
	v_mul_f32_e32 v65, v77, v66
	v_mul_f32_e32 v64, v65, v64
	v_mul_f32_e32 v65, 0xbfb8aa3b, v78
	v_exp_f32_e32 v65, v65
	v_cvt_pk_bf16_f32 v64, v64, s0
	ds_write_b16 v128, v64 offset:15568
	ds_read_u16 v64, v128 offset:15840
	v_add_f32_e32 v65, 1.0, v65
	s_waitcnt lgkmcnt(0)
	v_lshlrev_b32_e32 v64, 16, v64
	v_rcp_f32_e32 v66, v65
	s_nop 0
	v_mul_f32_e32 v65, v78, v66
	v_mul_f32_e32 v64, v65, v64
	v_mul_f32_e32 v65, 0xbfb8aa3b, v79
	v_exp_f32_e32 v65, v65
	v_cvt_pk_bf16_f32 v64, v64, s0
	ds_write_b16 v128, v64 offset:15840
	ds_read_u16 v64, v128 offset:16112
	v_add_f32_e32 v65, 1.0, v65
	s_waitcnt lgkmcnt(0)
	v_lshlrev_b32_e32 v64, 16, v64
	v_rcp_f32_e32 v66, v65
	s_nop 0
	v_mul_f32_e32 v65, v79, v66
	v_mul_f32_e32 v64, v65, v64
	v_mul_f32_e32 v65, 0xbfb8aa3b, v48
	v_exp_f32_e32 v65, v65
	v_cvt_pk_bf16_f32 v64, v64, s0
	ds_write_b16 v128, v64 offset:16112
	ds_read_u16 v64, v128 offset:17408
	v_add_f32_e32 v65, 1.0, v65
	s_waitcnt lgkmcnt(0)
	v_lshlrev_b32_e32 v64, 16, v64
	v_rcp_f32_e32 v66, v65
	s_nop 0
	v_mul_f32_e32 v48, v48, v66
	v_mul_f32_e32 v48, v48, v64
	v_mul_f32_e32 v64, 0xbfb8aa3b, v49
	v_exp_f32_e32 v64, v64
	v_cvt_pk_bf16_f32 v48, v48, s0
	ds_write_b16 v128, v48 offset:17408
	ds_read_u16 v48, v128 offset:17680
	v_add_f32_e32 v64, 1.0, v64
	s_waitcnt lgkmcnt(0)
	v_lshlrev_b32_e32 v48, 16, v48
	v_rcp_f32_e32 v65, v64
	s_nop 0
	v_mul_f32_e32 v49, v49, v65
	v_mul_f32_e32 v48, v49, v48
	v_mul_f32_e32 v49, 0xbfb8aa3b, v50
	v_exp_f32_e32 v49, v49
	v_cvt_pk_bf16_f32 v48, v48, s0
	ds_write_b16 v128, v48 offset:17680
	ds_read_u16 v48, v128 offset:17952
	v_add_f32_e32 v49, 1.0, v49
	s_waitcnt lgkmcnt(0)
	v_lshlrev_b32_e32 v48, 16, v48
	v_rcp_f32_e32 v64, v49
	s_nop 0
	v_mul_f32_e32 v49, v50, v64
	v_mul_f32_e32 v48, v49, v48
	v_mul_f32_e32 v49, 0xbfb8aa3b, v51
	v_exp_f32_e32 v49, v49
	v_cvt_pk_bf16_f32 v48, v48, s0
	ds_write_b16 v128, v48 offset:17952
	ds_read_u16 v48, v128 offset:18224
	v_add_f32_e32 v49, 1.0, v49
	s_waitcnt lgkmcnt(0)
	v_lshlrev_b32_e32 v48, 16, v48
	v_rcp_f32_e32 v50, v49
	s_nop 0
	v_mul_f32_e32 v49, v51, v50
	v_mul_f32_e32 v48, v49, v48
	v_mul_f32_e32 v49, 0xbfb8aa3b, v52
	v_exp_f32_e32 v49, v49
	v_cvt_pk_bf16_f32 v48, v48, s0
	ds_write_b16 v128, v48 offset:18224
	ds_read_u16 v48, v128 offset:19584
	v_add_f32_e32 v49, 1.0, v49
	s_waitcnt lgkmcnt(0)
	v_lshlrev_b32_e32 v48, 16, v48
	v_rcp_f32_e32 v50, v49
	s_nop 0
	v_mul_f32_e32 v49, v52, v50
	v_mul_f32_e32 v48, v49, v48
	v_mul_f32_e32 v49, 0xbfb8aa3b, v53
	v_exp_f32_e32 v49, v49
	v_cvt_pk_bf16_f32 v48, v48, s0
	ds_write_b16 v128, v48 offset:19584
	ds_read_u16 v48, v128 offset:19856
	v_add_f32_e32 v49, 1.0, v49
	s_waitcnt lgkmcnt(0)
	v_lshlrev_b32_e32 v48, 16, v48
	v_rcp_f32_e32 v50, v49
	s_nop 0
	v_mul_f32_e32 v49, v53, v50
	v_mul_f32_e32 v48, v49, v48
	v_mul_f32_e32 v49, 0xbfb8aa3b, v54
	v_exp_f32_e32 v49, v49
	v_cvt_pk_bf16_f32 v48, v48, s0
	ds_write_b16 v128, v48 offset:19856
	ds_read_u16 v48, v128 offset:20128
	v_add_f32_e32 v49, 1.0, v49
	s_waitcnt lgkmcnt(0)
	v_lshlrev_b32_e32 v48, 16, v48
	v_rcp_f32_e32 v50, v49
	s_nop 0
	v_mul_f32_e32 v49, v54, v50
	v_mul_f32_e32 v48, v49, v48
	v_mul_f32_e32 v49, 0xbfb8aa3b, v55
	v_exp_f32_e32 v49, v49
	v_cvt_pk_bf16_f32 v48, v48, s0
	ds_write_b16 v128, v48 offset:20128
	ds_read_u16 v48, v128 offset:20400
	v_add_f32_e32 v49, 1.0, v49
	s_waitcnt lgkmcnt(0)
	v_lshlrev_b32_e32 v48, 16, v48
	v_rcp_f32_e32 v50, v49
	s_nop 0
	v_mul_f32_e32 v49, v55, v50
	v_mul_f32_e32 v48, v49, v48
	v_mul_f32_e32 v49, 0xbfb8aa3b, v56
	v_exp_f32_e32 v49, v49
	v_cvt_pk_bf16_f32 v48, v48, s0
	ds_write_b16 v128, v48 offset:20400
	ds_read_u16 v48, v128 offset:21760
	v_add_f32_e32 v49, 1.0, v49
	s_waitcnt lgkmcnt(0)
	v_lshlrev_b32_e32 v48, 16, v48
	v_rcp_f32_e32 v50, v49
	s_nop 0
	v_mul_f32_e32 v49, v56, v50
	v_mul_f32_e32 v48, v49, v48
	v_mul_f32_e32 v49, 0xbfb8aa3b, v57
	v_exp_f32_e32 v49, v49
	v_cvt_pk_bf16_f32 v48, v48, s0
	ds_write_b16 v128, v48 offset:21760
	ds_read_u16 v48, v128 offset:22032
	v_add_f32_e32 v49, 1.0, v49
	s_waitcnt lgkmcnt(0)
; DEV u16 f2bf(float f) { return (u16)(pk2bf(f, 0.f) & 0xffffu); }
; DEV float bf2f(u16 h) { return __uint_as_float(((unsigned)h) << 16); }
; DEV float siluf_(float x) { return x / (1.0f + __expf(-x)); }
; template <int MI>
; DEV void p4_tile(const Params& p, int l, int m0, int nt, unsigned char* smem) {
;     ...
;     zero_acc_t<MI>(acc);
;     gemm_mm<MI>(acc, H + (size_t)m0 * 1024, 1024, WL + WO_G + (size_t)(1024 + nt * 128) * 1024, 1024, 1024, smem);
;     tile_load_t<MI>(smem, Q + (size_t)m0 * 1536 + nt * 192, 1536);
;     acc_foreach_t<MI>([&](int mi, int ni, int r, int row, int col) __attribute__((always_inline)) {
;       sC[row * LDC + col] = f2bf(bf2f(sC[row * LDC + col]) * siluf_(acc[mi][ni][r]));
;     });
;     tile_store_t<MI>(smem, YB + (size_t)m0 * 1024 + nt * 128, 1024);
;   } else {
;     const int n0 = (nt - 8) * 128;
;     zero_acc_t<MI>(acc);
;     gemm_mm<MI>(acc, H + (size_t)m0 * 1024, 1024, WL + WO_G + (size_t)n0 * 1024, 1024, 1024, smem);
;     tile_load_t<MI>(smem, YA + (size_t)m0 * 1024 + n0, 1024);
;     acc_foreach_t<MI>([&](int mi, int ni, int r, int row, int col) __attribute__((always_inline)) {
;       sC[row * LDC + col] = f2bf(bf2f(sC[row * LDC + col]) * siluf_(acc[mi][ni][r]));
;     });
	v_lshlrev_b32_e32 v48, 16, v48
	v_rcp_f32_e32 v50, v49
	s_nop 0
	v_mul_f32_e32 v49, v57, v50
	v_mul_f32_e32 v48, v49, v48
	v_mul_f32_e32 v49, 0xbfb8aa3b, v58
	v_exp_f32_e32 v49, v49
	v_cvt_pk_bf16_f32 v48, v48, s0
	ds_write_b16 v128, v48 offset:22032
	ds_read_u16 v48, v128 offset:22304
	v_add_f32_e32 v49, 1.0, v49
	s_waitcnt lgkmcnt(0)
	v_lshlrev_b32_e32 v48, 16, v48
	v_rcp_f32_e32 v50, v49
	s_nop 0
	v_mul_f32_e32 v49, v58, v50
	v_mul_f32_e32 v48, v49, v48
	v_mul_f32_e32 v49, 0xbfb8aa3b, v59
	v_exp_f32_e32 v49, v49
	v_cvt_pk_bf16_f32 v48, v48, s0
	ds_write_b16 v128, v48 offset:22304
	ds_read_u16 v48, v128 offset:22576
	v_add_f32_e32 v49, 1.0, v49
	s_waitcnt lgkmcnt(0)
	v_lshlrev_b32_e32 v48, 16, v48
	v_rcp_f32_e32 v50, v49
	s_nop 0
	v_mul_f32_e32 v49, v59, v50
	v_mul_f32_e32 v48, v49, v48
	v_mul_f32_e32 v49, 0xbfb8aa3b, v60
	v_exp_f32_e32 v49, v49
	v_cvt_pk_bf16_f32 v48, v48, s0
	ds_write_b16 v128, v48 offset:22576
	ds_read_u16 v48, v128 offset:23936
	v_add_f32_e32 v49, 1.0, v49
	s_waitcnt lgkmcnt(0)
	v_lshlrev_b32_e32 v48, 16, v48
	v_rcp_f32_e32 v50, v49
	s_nop 0
	v_mul_f32_e32 v49, v60, v50
	v_mul_f32_e32 v48, v49, v48
	v_mul_f32_e32 v49, 0xbfb8aa3b, v61
	v_exp_f32_e32 v49, v49
	v_cvt_pk_bf16_f32 v48, v48, s0
	ds_write_b16 v128, v48 offset:23936
	ds_read_u16 v48, v128 offset:24208
	v_add_f32_e32 v49, 1.0, v49
	s_waitcnt lgkmcnt(0)
	v_lshlrev_b32_e32 v48, 16, v48
	v_rcp_f32_e32 v50, v49
	s_nop 0
	v_mul_f32_e32 v49, v61, v50
	v_mul_f32_e32 v48, v49, v48
	v_mul_f32_e32 v49, 0xbfb8aa3b, v62
	v_exp_f32_e32 v49, v49
	v_cvt_pk_bf16_f32 v48, v48, s0
	ds_write_b16 v128, v48 offset:24208
	ds_read_u16 v48, v128 offset:24480
	v_add_f32_e32 v49, 1.0, v49
	s_waitcnt lgkmcnt(0)
	v_lshlrev_b32_e32 v48, 16, v48
	v_rcp_f32_e32 v50, v49
	s_nop 0
	v_mul_f32_e32 v49, v62, v50
	v_mul_f32_e32 v48, v49, v48
	v_mul_f32_e32 v49, 0xbfb8aa3b, v63
	v_exp_f32_e32 v49, v49
	v_cvt_pk_bf16_f32 v48, v48, s0
	ds_write_b16 v128, v48 offset:24480
	ds_read_u16 v48, v128 offset:24752
	v_add_f32_e32 v49, 1.0, v49
	s_waitcnt lgkmcnt(0)
	v_lshlrev_b32_e32 v48, 16, v48
	v_rcp_f32_e32 v50, v49
	s_nop 0
	v_mul_f32_e32 v49, v63, v50
	v_mul_f32_e32 v48, v49, v48
	v_mul_f32_e32 v49, 0xbfb8aa3b, v32
	v_exp_f32_e32 v49, v49
	v_cvt_pk_bf16_f32 v48, v48, s0
	ds_write_b16 v128, v48 offset:24752
	ds_read_u16 v48, v128 offset:17472
	v_add_f32_e32 v49, 1.0, v49
	s_waitcnt lgkmcnt(0)
	v_lshlrev_b32_e32 v48, 16, v48
	v_rcp_f32_e32 v50, v49
	s_nop 0
	v_mul_f32_e32 v32, v32, v50
	v_mul_f32_e32 v32, v32, v48
	v_mul_f32_e32 v48, 0xbfb8aa3b, v33
	v_exp_f32_e32 v48, v48
	v_cvt_pk_bf16_f32 v32, v32, s0
	ds_write_b16 v128, v32 offset:17472
	ds_read_u16 v32, v128 offset:17744
	v_add_f32_e32 v48, 1.0, v48
	s_waitcnt lgkmcnt(0)
	v_lshlrev_b32_e32 v32, 16, v32
	v_rcp_f32_e32 v49, v48
	s_nop 0
	v_mul_f32_e32 v33, v33, v49
	v_mul_f32_e32 v32, v33, v32
	v_mul_f32_e32 v33, 0xbfb8aa3b, v34
	v_exp_f32_e32 v33, v33
	v_cvt_pk_bf16_f32 v32, v32, s0
	ds_write_b16 v128, v32 offset:17744
	ds_read_u16 v32, v128 offset:18016
	v_add_f32_e32 v33, 1.0, v33
	s_waitcnt lgkmcnt(0)
	v_lshlrev_b32_e32 v32, 16, v32
	v_rcp_f32_e32 v48, v33
	s_nop 0
	v_mul_f32_e32 v33, v34, v48
	v_mul_f32_e32 v32, v33, v32
	v_mul_f32_e32 v33, 0xbfb8aa3b, v35
	v_exp_f32_e32 v33, v33
	v_cvt_pk_bf16_f32 v32, v32, s0
	ds_write_b16 v128, v32 offset:18016
	ds_read_u16 v32, v128 offset:18288
	v_add_f32_e32 v33, 1.0, v33
	s_waitcnt lgkmcnt(0)
	v_lshlrev_b32_e32 v32, 16, v32
	v_rcp_f32_e32 v34, v33
	s_nop 0
	v_mul_f32_e32 v33, v35, v34
	v_mul_f32_e32 v32, v33, v32
	v_mul_f32_e32 v33, 0xbfb8aa3b, v36
	v_exp_f32_e32 v33, v33
	v_cvt_pk_bf16_f32 v32, v32, s0
	ds_write_b16 v128, v32 offset:18288
	ds_read_u16 v32, v128 offset:19648
	v_add_f32_e32 v33, 1.0, v33
	s_waitcnt lgkmcnt(0)
	v_lshlrev_b32_e32 v32, 16, v32
	v_rcp_f32_e32 v34, v33
	s_nop 0
	v_mul_f32_e32 v33, v36, v34
	v_mul_f32_e32 v32, v33, v32
	v_mul_f32_e32 v33, 0xbfb8aa3b, v37
	v_exp_f32_e32 v33, v33
	v_cvt_pk_bf16_f32 v32, v32, s0
	ds_write_b16 v128, v32 offset:19648
	ds_read_u16 v32, v128 offset:19920
	v_add_f32_e32 v33, 1.0, v33
	s_waitcnt lgkmcnt(0)
	v_lshlrev_b32_e32 v32, 16, v32
	v_rcp_f32_e32 v34, v33
	s_nop 0
	v_mul_f32_e32 v33, v37, v34
	v_mul_f32_e32 v32, v33, v32
	v_mul_f32_e32 v33, 0xbfb8aa3b, v38
	v_exp_f32_e32 v33, v33
	v_cvt_pk_bf16_f32 v32, v32, s0
	ds_write_b16 v128, v32 offset:19920
	ds_read_u16 v32, v128 offset:20192
	v_add_f32_e32 v33, 1.0, v33
	s_waitcnt lgkmcnt(0)
	v_lshlrev_b32_e32 v32, 16, v32
	v_rcp_f32_e32 v34, v33
	s_nop 0
	v_mul_f32_e32 v33, v38, v34
	v_mul_f32_e32 v32, v33, v32
	v_mul_f32_e32 v33, 0xbfb8aa3b, v39
	v_exp_f32_e32 v33, v33
	v_cvt_pk_bf16_f32 v32, v32, s0
	ds_write_b16 v128, v32 offset:20192
	ds_read_u16 v32, v128 offset:20464
	v_add_f32_e32 v33, 1.0, v33
	s_waitcnt lgkmcnt(0)
	v_lshlrev_b32_e32 v32, 16, v32
	v_rcp_f32_e32 v34, v33
	s_nop 0
	v_mul_f32_e32 v33, v39, v34
	v_mul_f32_e32 v32, v33, v32
	v_mul_f32_e32 v33, 0xbfb8aa3b, v40
	v_exp_f32_e32 v33, v33
	v_cvt_pk_bf16_f32 v32, v32, s0
	ds_write_b16 v128, v32 offset:20464
	ds_read_u16 v32, v128 offset:21824
	v_add_f32_e32 v33, 1.0, v33
	s_waitcnt lgkmcnt(0)
	v_lshlrev_b32_e32 v32, 16, v32
	v_rcp_f32_e32 v34, v33
	s_nop 0
	v_mul_f32_e32 v33, v40, v34
	v_mul_f32_e32 v32, v33, v32
	v_mul_f32_e32 v33, 0xbfb8aa3b, v41
	v_exp_f32_e32 v33, v33
	v_cvt_pk_bf16_f32 v32, v32, s0
	ds_write_b16 v128, v32 offset:21824
	ds_read_u16 v32, v128 offset:22096
	v_add_f32_e32 v33, 1.0, v33
	s_waitcnt lgkmcnt(0)
	v_lshlrev_b32_e32 v32, 16, v32
	v_rcp_f32_e32 v34, v33
	s_nop 0
	v_mul_f32_e32 v33, v41, v34
	v_mul_f32_e32 v32, v33, v32
	v_mul_f32_e32 v33, 0xbfb8aa3b, v42
	v_exp_f32_e32 v33, v33
	v_cvt_pk_bf16_f32 v32, v32, s0
	ds_write_b16 v128, v32 offset:22096
	ds_read_u16 v32, v128 offset:22368
	v_add_f32_e32 v33, 1.0, v33
	s_waitcnt lgkmcnt(0)
; DEV u16 f2bf(float f) { return (u16)(pk2bf(f, 0.f) & 0xffffu); }
; DEV float bf2f(u16 h) { return __uint_as_float(((unsigned)h) << 16); }
; DEV float siluf_(float x) { return x / (1.0f + __expf(-x)); }
; template <int MI>
; DEV void p4_tile(const Params& p, int l, int m0, int nt, unsigned char* smem) {
;     ...
;     zero_acc_t<MI>(acc);
;     gemm_mm<MI>(acc, H + (size_t)m0 * 1024, 1024, WL + WO_G + (size_t)(1024 + nt * 128) * 1024, 1024, 1024, smem);
;     tile_load_t<MI>(smem, Q + (size_t)m0 * 1536 + nt * 192, 1536);
;     acc_foreach_t<MI>([&](int mi, int ni, int r, int row, int col) __attribute__((always_inline)) {
;       sC[row * LDC + col] = f2bf(bf2f(sC[row * LDC + col]) * siluf_(acc[mi][ni][r]));
;     });
;     tile_store_t<MI>(smem, YB + (size_t)m0 * 1024 + nt * 128, 1024);
;   } else {
;     const int n0 = (nt - 8) * 128;
;     zero_acc_t<MI>(acc);
;     gemm_mm<MI>(acc, H + (size_t)m0 * 1024, 1024, WL + WO_G + (size_t)n0 * 1024, 1024, 1024, smem);
;     tile_load_t<MI>(smem, YA + (size_t)m0 * 1024 + n0, 1024);
;     acc_foreach_t<MI>([&](int mi, int ni, int r, int row, int col) __attribute__((always_inline)) {
;       sC[row * LDC + col] = f2bf(bf2f(sC[row * LDC + col]) * siluf_(acc[mi][ni][r]));
;     });
	v_lshlrev_b32_e32 v32, 16, v32
	v_rcp_f32_e32 v34, v33
	s_nop 0
	v_mul_f32_e32 v33, v42, v34
	v_mul_f32_e32 v32, v33, v32
	v_mul_f32_e32 v33, 0xbfb8aa3b, v43
	v_exp_f32_e32 v33, v33
	v_cvt_pk_bf16_f32 v32, v32, s0
	ds_write_b16 v128, v32 offset:22368
	ds_read_u16 v32, v128 offset:22640
	v_add_f32_e32 v33, 1.0, v33
	s_waitcnt lgkmcnt(0)
	v_lshlrev_b32_e32 v32, 16, v32
	v_rcp_f32_e32 v34, v33
	s_nop 0
	v_mul_f32_e32 v33, v43, v34
	v_mul_f32_e32 v32, v33, v32
	v_mul_f32_e32 v33, 0xbfb8aa3b, v44
	v_exp_f32_e32 v33, v33
	v_cvt_pk_bf16_f32 v32, v32, s0
	ds_write_b16 v128, v32 offset:22640
	ds_read_u16 v32, v128 offset:24000
	v_add_f32_e32 v33, 1.0, v33
	s_waitcnt lgkmcnt(0)
	v_lshlrev_b32_e32 v32, 16, v32
	v_rcp_f32_e32 v34, v33
	s_nop 0
	v_mul_f32_e32 v33, v44, v34
	v_mul_f32_e32 v32, v33, v32
	v_mul_f32_e32 v33, 0xbfb8aa3b, v45
	v_exp_f32_e32 v33, v33
	v_cvt_pk_bf16_f32 v32, v32, s0
	ds_write_b16 v128, v32 offset:24000
	ds_read_u16 v32, v128 offset:24272
	v_add_f32_e32 v33, 1.0, v33
	s_waitcnt lgkmcnt(0)
	v_lshlrev_b32_e32 v32, 16, v32
	v_rcp_f32_e32 v34, v33
	s_nop 0
	v_mul_f32_e32 v33, v45, v34
	v_mul_f32_e32 v32, v33, v32
	v_mul_f32_e32 v33, 0xbfb8aa3b, v46
	v_exp_f32_e32 v33, v33
	v_cvt_pk_bf16_f32 v32, v32, s0
	ds_write_b16 v128, v32 offset:24272
	ds_read_u16 v32, v128 offset:24544
	v_add_f32_e32 v33, 1.0, v33
	s_waitcnt lgkmcnt(0)
	v_lshlrev_b32_e32 v32, 16, v32
	v_rcp_f32_e32 v34, v33
	s_nop 0
	v_mul_f32_e32 v33, v46, v34
	v_mul_f32_e32 v32, v33, v32
	v_mul_f32_e32 v33, 0xbfb8aa3b, v47
	v_exp_f32_e32 v33, v33
	v_cvt_pk_bf16_f32 v32, v32, s0
	ds_write_b16 v128, v32 offset:24544
	ds_read_u16 v32, v128 offset:24816
	v_add_f32_e32 v33, 1.0, v33
	s_waitcnt lgkmcnt(0)
	v_lshlrev_b32_e32 v32, 16, v32
	v_rcp_f32_e32 v34, v33
	s_nop 0
	v_mul_f32_e32 v33, v47, v34
	v_mul_f32_e32 v32, v33, v32
	v_mul_f32_e32 v33, 0xbfb8aa3b, v16
	v_exp_f32_e32 v33, v33
	v_cvt_pk_bf16_f32 v32, v32, s0
	ds_write_b16 v128, v32 offset:24816
	ds_read_u16 v32, v128 offset:26112
	v_add_f32_e32 v33, 1.0, v33
	s_waitcnt lgkmcnt(0)
	v_lshlrev_b32_e32 v32, 16, v32
	v_rcp_f32_e32 v34, v33
	s_nop 0
	v_mul_f32_e32 v16, v16, v34
	v_mul_f32_e32 v16, v16, v32
	v_mul_f32_e32 v32, 0xbfb8aa3b, v17
	v_exp_f32_e32 v32, v32
	v_cvt_pk_bf16_f32 v16, v16, s0
	ds_write_b16 v128, v16 offset:26112
	ds_read_u16 v16, v128 offset:26384
	v_add_f32_e32 v32, 1.0, v32
	s_waitcnt lgkmcnt(0)
	v_lshlrev_b32_e32 v16, 16, v16
	v_rcp_f32_e32 v33, v32
	s_nop 0
	v_mul_f32_e32 v17, v17, v33
	v_mul_f32_e32 v16, v17, v16
	v_mul_f32_e32 v17, 0xbfb8aa3b, v18
	v_exp_f32_e32 v17, v17
	v_cvt_pk_bf16_f32 v16, v16, s0
	ds_write_b16 v128, v16 offset:26384
	ds_read_u16 v16, v128 offset:26656
	v_add_f32_e32 v17, 1.0, v17
	s_waitcnt lgkmcnt(0)
	v_lshlrev_b32_e32 v16, 16, v16
	v_rcp_f32_e32 v32, v17
	s_nop 0
	v_mul_f32_e32 v17, v18, v32
	v_mul_f32_e32 v16, v17, v16
	v_mul_f32_e32 v17, 0xbfb8aa3b, v19
	v_exp_f32_e32 v17, v17
	v_cvt_pk_bf16_f32 v16, v16, s0
	ds_write_b16 v128, v16 offset:26656
	ds_read_u16 v16, v128 offset:26928
	v_add_f32_e32 v17, 1.0, v17
	s_waitcnt lgkmcnt(0)
	v_lshlrev_b32_e32 v16, 16, v16
	v_rcp_f32_e32 v18, v17
	s_nop 0
	v_mul_f32_e32 v17, v19, v18
	v_mul_f32_e32 v16, v17, v16
	v_mul_f32_e32 v17, 0xbfb8aa3b, v20
	v_exp_f32_e32 v17, v17
	v_cvt_pk_bf16_f32 v16, v16, s0
	ds_write_b16 v128, v16 offset:26928
	ds_read_u16 v16, v128 offset:28288
	v_add_f32_e32 v17, 1.0, v17
	s_waitcnt lgkmcnt(0)
	v_lshlrev_b32_e32 v16, 16, v16
	v_rcp_f32_e32 v18, v17
	s_nop 0
	v_mul_f32_e32 v17, v20, v18
	v_mul_f32_e32 v16, v17, v16
	v_mul_f32_e32 v17, 0xbfb8aa3b, v21
	v_exp_f32_e32 v17, v17
	v_cvt_pk_bf16_f32 v16, v16, s0
	ds_write_b16 v128, v16 offset:28288
	ds_read_u16 v16, v128 offset:28560
	v_add_f32_e32 v17, 1.0, v17
	s_waitcnt lgkmcnt(0)
	v_lshlrev_b32_e32 v16, 16, v16
	v_rcp_f32_e32 v18, v17
	s_nop 0
	v_mul_f32_e32 v17, v21, v18
	v_mul_f32_e32 v16, v17, v16
	v_mul_f32_e32 v17, 0xbfb8aa3b, v22
	v_exp_f32_e32 v17, v17
	v_cvt_pk_bf16_f32 v16, v16, s0
	ds_write_b16 v128, v16 offset:28560
	ds_read_u16 v16, v128 offset:28832
	v_add_f32_e32 v17, 1.0, v17
	s_waitcnt lgkmcnt(0)
	v_lshlrev_b32_e32 v16, 16, v16
	v_rcp_f32_e32 v18, v17
	s_nop 0
	v_mul_f32_e32 v17, v22, v18
	v_mul_f32_e32 v16, v17, v16
	v_mul_f32_e32 v17, 0xbfb8aa3b, v23
	v_exp_f32_e32 v17, v17
	v_cvt_pk_bf16_f32 v16, v16, s0
	ds_write_b16 v128, v16 offset:28832
	ds_read_u16 v16, v128 offset:29104
	v_add_f32_e32 v17, 1.0, v17
	s_waitcnt lgkmcnt(0)
	v_lshlrev_b32_e32 v16, 16, v16
	v_rcp_f32_e32 v18, v17
	s_nop 0
	v_mul_f32_e32 v17, v23, v18
	v_mul_f32_e32 v16, v17, v16
	v_mul_f32_e32 v17, 0xbfb8aa3b, v24
	v_exp_f32_e32 v17, v17
	v_cvt_pk_bf16_f32 v16, v16, s0
	ds_write_b16 v128, v16 offset:29104
	ds_read_u16 v16, v128 offset:30464
	v_add_f32_e32 v17, 1.0, v17
	s_waitcnt lgkmcnt(0)
	v_lshlrev_b32_e32 v16, 16, v16
	v_rcp_f32_e32 v18, v17
	s_nop 0
	v_mul_f32_e32 v17, v24, v18
	v_mul_f32_e32 v16, v17, v16
	v_mul_f32_e32 v17, 0xbfb8aa3b, v25
	v_exp_f32_e32 v17, v17
	v_cvt_pk_bf16_f32 v16, v16, s0
	ds_write_b16 v128, v16 offset:30464
	ds_read_u16 v16, v128 offset:30736
	v_add_f32_e32 v17, 1.0, v17
	s_waitcnt lgkmcnt(0)
	v_lshlrev_b32_e32 v16, 16, v16
	v_rcp_f32_e32 v18, v17
	s_nop 0
	v_mul_f32_e32 v17, v25, v18
	v_mul_f32_e32 v16, v17, v16
	v_mul_f32_e32 v17, 0xbfb8aa3b, v26
	v_exp_f32_e32 v17, v17
	v_cvt_pk_bf16_f32 v16, v16, s0
	ds_write_b16 v128, v16 offset:30736
	ds_read_u16 v16, v128 offset:31008
	v_add_f32_e32 v17, 1.0, v17
	s_waitcnt lgkmcnt(0)
	v_lshlrev_b32_e32 v16, 16, v16
	v_rcp_f32_e32 v18, v17
	s_nop 0
	v_mul_f32_e32 v17, v26, v18
	v_mul_f32_e32 v16, v17, v16
	v_mul_f32_e32 v17, 0xbfb8aa3b, v27
	v_exp_f32_e32 v17, v17
	v_cvt_pk_bf16_f32 v16, v16, s0
	ds_write_b16 v128, v16 offset:31008
	ds_read_u16 v16, v128 offset:31280
	v_add_f32_e32 v17, 1.0, v17
	s_waitcnt lgkmcnt(0)
; DEV u16 f2bf(float f) { return (u16)(pk2bf(f, 0.f) & 0xffffu); }
; DEV float bf2f(u16 h) { return __uint_as_float(((unsigned)h) << 16); }
; DEV float siluf_(float x) { return x / (1.0f + __expf(-x)); }
; template <int MI>
; DEV void p4_tile(const Params& p, int l, int m0, int nt, unsigned char* smem) {
;     ...
;     zero_acc_t<MI>(acc);
;     gemm_mm<MI>(acc, H + (size_t)m0 * 1024, 1024, WL + WO_G + (size_t)(1024 + nt * 128) * 1024, 1024, 1024, smem);
;     tile_load_t<MI>(smem, Q + (size_t)m0 * 1536 + nt * 192, 1536);
;     acc_foreach_t<MI>([&](int mi, int ni, int r, int row, int col) __attribute__((always_inline)) {
;       sC[row * LDC + col] = f2bf(bf2f(sC[row * LDC + col]) * siluf_(acc[mi][ni][r]));
;     });
;     tile_store_t<MI>(smem, YB + (size_t)m0 * 1024 + nt * 128, 1024);
;   } else {
;     const int n0 = (nt - 8) * 128;
;     zero_acc_t<MI>(acc);
;     gemm_mm<MI>(acc, H + (size_t)m0 * 1024, 1024, WL + WO_G + (size_t)n0 * 1024, 1024, 1024, smem);
;     tile_load_t<MI>(smem, YA + (size_t)m0 * 1024 + n0, 1024);
;     acc_foreach_t<MI>([&](int mi, int ni, int r, int row, int col) __attribute__((always_inline)) {
;       sC[row * LDC + col] = f2bf(bf2f(sC[row * LDC + col]) * siluf_(acc[mi][ni][r]));
;     });
	v_lshlrev_b32_e32 v16, 16, v16
	v_rcp_f32_e32 v18, v17
	s_nop 0
	v_mul_f32_e32 v17, v27, v18
	v_mul_f32_e32 v16, v17, v16
	v_mul_f32_e32 v17, 0xbfb8aa3b, v28
	v_exp_f32_e32 v17, v17
	v_cvt_pk_bf16_f32 v16, v16, s0
	ds_write_b16 v128, v16 offset:31280
	ds_read_u16 v16, v128 offset:32640
	v_add_f32_e32 v17, 1.0, v17
	s_waitcnt lgkmcnt(0)
	v_lshlrev_b32_e32 v16, 16, v16
	v_rcp_f32_e32 v18, v17
	s_nop 0
	v_mul_f32_e32 v17, v28, v18
	v_mul_f32_e32 v16, v17, v16
	v_mul_f32_e32 v17, 0xbfb8aa3b, v29
	v_exp_f32_e32 v17, v17
	v_cvt_pk_bf16_f32 v16, v16, s0
	ds_write_b16 v128, v16 offset:32640
	ds_read_u16 v16, v128 offset:32912
	v_add_f32_e32 v17, 1.0, v17
	s_waitcnt lgkmcnt(0)
	v_lshlrev_b32_e32 v16, 16, v16
	v_rcp_f32_e32 v18, v17
	s_nop 0
	v_mul_f32_e32 v17, v29, v18
	v_mul_f32_e32 v16, v17, v16
	v_mul_f32_e32 v17, 0xbfb8aa3b, v30
	v_exp_f32_e32 v17, v17
	v_cvt_pk_bf16_f32 v16, v16, s0
	ds_write_b16 v128, v16 offset:32912
	ds_read_u16 v16, v128 offset:33184
	v_add_f32_e32 v17, 1.0, v17
	s_waitcnt lgkmcnt(0)
	v_lshlrev_b32_e32 v16, 16, v16
	v_rcp_f32_e32 v18, v17
	s_nop 0
	v_mul_f32_e32 v17, v30, v18
	v_mul_f32_e32 v16, v17, v16
	v_mul_f32_e32 v17, 0xbfb8aa3b, v31
	v_exp_f32_e32 v17, v17
	v_cvt_pk_bf16_f32 v16, v16, s0
	ds_write_b16 v128, v16 offset:33184
	ds_read_u16 v16, v128 offset:33456
	v_add_f32_e32 v17, 1.0, v17
	s_waitcnt lgkmcnt(0)
	v_lshlrev_b32_e32 v16, 16, v16
	v_rcp_f32_e32 v18, v17
	s_nop 0
	v_mul_f32_e32 v17, v31, v18
	v_mul_f32_e32 v16, v17, v16
	v_mul_f32_e32 v17, 0xbfb8aa3b, v0
	v_exp_f32_e32 v17, v17
	v_cvt_pk_bf16_f32 v16, v16, s0
	ds_write_b16 v128, v16 offset:33456
	ds_read_u16 v16, v128 offset:26176
	v_add_f32_e32 v17, 1.0, v17
	s_waitcnt lgkmcnt(0)
	v_lshlrev_b32_e32 v16, 16, v16
	v_rcp_f32_e32 v18, v17
	s_nop 0
	v_mul_f32_e32 v0, v0, v18
	v_mul_f32_e32 v0, v0, v16
	v_mul_f32_e32 v16, 0xbfb8aa3b, v1
	v_exp_f32_e32 v16, v16
	v_cvt_pk_bf16_f32 v0, v0, s0
	ds_write_b16 v128, v0 offset:26176
	ds_read_u16 v0, v128 offset:26448
	v_add_f32_e32 v16, 1.0, v16
	s_waitcnt lgkmcnt(0)
	v_lshlrev_b32_e32 v0, 16, v0
	v_rcp_f32_e32 v17, v16
	s_nop 0
	v_mul_f32_e32 v1, v1, v17
	v_mul_f32_e32 v0, v1, v0
	v_mul_f32_e32 v1, 0xbfb8aa3b, v2
	v_exp_f32_e32 v1, v1
	v_cvt_pk_bf16_f32 v0, v0, s0
	ds_write_b16 v128, v0 offset:26448
	ds_read_u16 v0, v128 offset:26720
	v_add_f32_e32 v1, 1.0, v1
	s_waitcnt lgkmcnt(0)
	v_lshlrev_b32_e32 v0, 16, v0
	v_rcp_f32_e32 v16, v1
	s_nop 0
	v_mul_f32_e32 v1, v2, v16
	v_mul_f32_e32 v0, v1, v0
	v_mul_f32_e32 v1, 0xbfb8aa3b, v3
	v_exp_f32_e32 v1, v1
	v_cvt_pk_bf16_f32 v0, v0, s0
	ds_write_b16 v128, v0 offset:26720
	ds_read_u16 v0, v128 offset:26992
	v_add_f32_e32 v1, 1.0, v1
	s_waitcnt lgkmcnt(0)
	v_lshlrev_b32_e32 v0, 16, v0
	v_rcp_f32_e32 v2, v1
	s_nop 0
	v_mul_f32_e32 v1, v3, v2
	v_mul_f32_e32 v0, v1, v0
	v_mul_f32_e32 v1, 0xbfb8aa3b, v4
	v_exp_f32_e32 v1, v1
	v_cvt_pk_bf16_f32 v0, v0, s0
	ds_write_b16 v128, v0 offset:26992
	ds_read_u16 v0, v128 offset:28352
	v_add_f32_e32 v1, 1.0, v1
	s_waitcnt lgkmcnt(0)
	v_lshlrev_b32_e32 v0, 16, v0
	v_rcp_f32_e32 v2, v1
	s_nop 0
	v_mul_f32_e32 v1, v4, v2
	v_mul_f32_e32 v0, v1, v0
	v_mul_f32_e32 v1, 0xbfb8aa3b, v5
	v_exp_f32_e32 v1, v1
	v_cvt_pk_bf16_f32 v0, v0, s0
	ds_write_b16 v128, v0 offset:28352
	ds_read_u16 v0, v128 offset:28624
	v_add_f32_e32 v1, 1.0, v1
	s_waitcnt lgkmcnt(0)
	v_lshlrev_b32_e32 v0, 16, v0
	v_rcp_f32_e32 v2, v1
	s_nop 0
	v_mul_f32_e32 v1, v5, v2
	v_mul_f32_e32 v0, v1, v0
	v_mul_f32_e32 v1, 0xbfb8aa3b, v6
	v_exp_f32_e32 v1, v1
	v_cvt_pk_bf16_f32 v0, v0, s0
	ds_write_b16 v128, v0 offset:28624
	ds_read_u16 v0, v128 offset:28896
	v_add_f32_e32 v1, 1.0, v1
	s_waitcnt lgkmcnt(0)
	v_lshlrev_b32_e32 v0, 16, v0
	v_rcp_f32_e32 v2, v1
	s_nop 0
	v_mul_f32_e32 v1, v6, v2
	v_mul_f32_e32 v0, v1, v0
	v_mul_f32_e32 v1, 0xbfb8aa3b, v7
	v_exp_f32_e32 v1, v1
	v_cvt_pk_bf16_f32 v0, v0, s0
	ds_write_b16 v128, v0 offset:28896
	ds_read_u16 v0, v128 offset:29168
	v_add_f32_e32 v1, 1.0, v1
	s_waitcnt lgkmcnt(0)
	v_lshlrev_b32_e32 v0, 16, v0
	v_rcp_f32_e32 v2, v1
	s_nop 0
	v_mul_f32_e32 v1, v7, v2
	v_mul_f32_e32 v0, v1, v0
	v_mul_f32_e32 v1, 0xbfb8aa3b, v8
	v_exp_f32_e32 v1, v1
	v_cvt_pk_bf16_f32 v0, v0, s0
	ds_write_b16 v128, v0 offset:29168
	ds_read_u16 v0, v128 offset:30528
	v_add_f32_e32 v1, 1.0, v1
	s_waitcnt lgkmcnt(0)
	v_lshlrev_b32_e32 v0, 16, v0
	v_rcp_f32_e32 v2, v1
	s_nop 0
	v_mul_f32_e32 v1, v8, v2
	v_mul_f32_e32 v0, v1, v0
	v_mul_f32_e32 v1, 0xbfb8aa3b, v9
	v_exp_f32_e32 v1, v1
	v_cvt_pk_bf16_f32 v0, v0, s0
	ds_write_b16 v128, v0 offset:30528
	ds_read_u16 v0, v128 offset:30800
	v_add_f32_e32 v1, 1.0, v1
	s_waitcnt lgkmcnt(0)
	v_lshlrev_b32_e32 v0, 16, v0
	v_rcp_f32_e32 v2, v1
	s_nop 0
	v_mul_f32_e32 v1, v9, v2
	v_mul_f32_e32 v0, v1, v0
	v_mul_f32_e32 v1, 0xbfb8aa3b, v10
	v_exp_f32_e32 v1, v1
	v_cvt_pk_bf16_f32 v0, v0, s0
	ds_write_b16 v128, v0 offset:30800
	ds_read_u16 v0, v128 offset:31072
	v_add_f32_e32 v1, 1.0, v1
	s_waitcnt lgkmcnt(0)
	v_lshlrev_b32_e32 v0, 16, v0
	v_rcp_f32_e32 v2, v1
	s_nop 0
	v_mul_f32_e32 v1, v10, v2
	v_mul_f32_e32 v0, v1, v0
	v_mul_f32_e32 v1, 0xbfb8aa3b, v11
	v_exp_f32_e32 v1, v1
	v_cvt_pk_bf16_f32 v0, v0, s0
	ds_write_b16 v128, v0 offset:31072
	ds_read_u16 v0, v128 offset:31344
	v_add_f32_e32 v1, 1.0, v1
	s_waitcnt lgkmcnt(0)
	v_lshlrev_b32_e32 v0, 16, v0
	v_rcp_f32_e32 v2, v1
	s_nop 0
	v_mul_f32_e32 v1, v11, v2
	v_mul_f32_e32 v0, v1, v0
	v_mul_f32_e32 v1, 0xbfb8aa3b, v12
	v_exp_f32_e32 v1, v1
	v_cvt_pk_bf16_f32 v0, v0, s0
	ds_write_b16 v128, v0 offset:31344
	ds_read_u16 v0, v128 offset:32704
	v_add_f32_e32 v1, 1.0, v1
	s_waitcnt lgkmcnt(0)
	v_lshlrev_b32_e32 v0, 16, v0
	v_rcp_f32_e32 v2, v1
	s_nop 0
	v_mul_f32_e32 v1, v12, v2
	v_mul_f32_e32 v0, v1, v0
	v_mul_f32_e32 v1, 0xbfb8aa3b, v13
	v_exp_f32_e32 v1, v1
	v_cvt_pk_bf16_f32 v0, v0, s0
	ds_write_b16 v128, v0 offset:32704
	ds_read_u16 v0, v128 offset:32976
	v_add_f32_e32 v1, 1.0, v1
	s_waitcnt lgkmcnt(0)
	v_lshlrev_b32_e32 v0, 16, v0
	v_rcp_f32_e32 v2, v1
	s_nop 0
	v_mul_f32_e32 v1, v13, v2
	v_mul_f32_e32 v0, v1, v0
	v_mul_f32_e32 v1, 0xbfb8aa3b, v14
	v_exp_f32_e32 v1, v1
	v_cvt_pk_bf16_f32 v0, v0, s0
	ds_write_b16 v128, v0 offset:32976
	ds_read_u16 v0, v128 offset:33248
	v_add_f32_e32 v1, 1.0, v1
	s_waitcnt lgkmcnt(0)
	v_lshlrev_b32_e32 v0, 16, v0
	v_rcp_f32_e32 v2, v1
	s_nop 0
	v_mul_f32_e32 v1, v14, v2
	v_mul_f32_e32 v0, v1, v0
	v_mul_f32_e32 v1, 0xbfb8aa3b, v15
	v_exp_f32_e32 v1, v1
	v_cvt_pk_bf16_f32 v0, v0, s0
	ds_write_b16 v128, v0 offset:33248
	ds_read_u16 v0, v128 offset:33520
	v_add_f32_e32 v1, 1.0, v1
	s_waitcnt lgkmcnt(0)
	v_lshlrev_b32_e32 v0, 16, v0
	s_mov_b64 s[6:7], 0
	v_rcp_f32_e32 v2, v1
	s_nop 0
	v_mul_f32_e32 v1, v15, v2
	v_mul_f32_e32 v0, v1, v0
	v_cvt_pk_bf16_f32 v0, v0, s0
	ds_write_b16 v128, v0 offset:33520
	v_mov_b32_e32 v0, v232
	s_waitcnt lgkmcnt(0)
	s_barrier

; DEV float sigmoidf_(float x) { return 1.0f / (1.0f + __expf(-x)); }
; DEV void phase_p5(const Params& p, int l, unsigned char* smem) {
;     ...
; #pragma unroll
;       for (int a_ = 0; a_ < 2; ++a_)
; #pragma unroll
;         for (int b_ = 0; b_ < 2; ++b_) {
; #pragma unroll
;           for (int r = 0; r < 8; ++r) ga[a_][b_][r] = pk2bf(sigmoidf_(g[a_][b_][2 * r]), sigmoidf_(g[a_][b_][2 * r + 1]));
;           __builtin_amdgcn_sched_barrier(0);
;         }
.LBB0_1304:
	v_mul_f32_e32 v48, 0xbfb8aa3b, v48
	v_mul_f32_e32 v49, 0xbfb8aa3b, v49
	v_exp_f32_e32 v48, v48
	v_exp_f32_e32 v49, v49
	v_mul_f32_e32 v32, 0xbfb8aa3b, v32
	v_mul_f32_e32 v33, 0xbfb8aa3b, v33
	v_exp_f32_e32 v32, v32
	v_pk_add_f32 v[48:49], v[48:49], 1.0 op_sel_hi:[1,0]
	v_exp_f32_e32 v33, v33
	s_waitcnt vmcnt(7)
	v_pk_add_f32 v[32:33], v[32:33], 1.0 op_sel_hi:[1,0]
	v_mul_f32_e32 v16, 0xbfb8aa3b, v16
	v_mul_f32_e32 v17, 0xbfb8aa3b, v17
	s_waitcnt vmcnt(6)
	v_rcp_f32_e32 v49, v49
	s_nop 0
	v_exp_f32_e32 v16, v16
	v_exp_f32_e32 v17, v17
	v_mul_f32_e32 v0, 0xbfb8aa3b, v0
	v_rcp_f32_e32 v48, v48
	s_nop 0
	v_cvt_pk_bf16_f32 v48, v48, v49
	v_mul_f32_e32 v49, 0xbfb8aa3b, v50
	v_exp_f32_e32 v50, v49
	v_mul_f32_e32 v49, 0xbfb8aa3b, v51
	v_exp_f32_e32 v51, v49
	v_pk_add_f32 v[16:17], v[16:17], 1.0 op_sel_hi:[1,0]
	v_mul_f32_e32 v1, 0xbfb8aa3b, v1
	v_exp_f32_e32 v0, v0
	v_pk_add_f32 v[50:51], v[50:51], 1.0 op_sel_hi:[1,0]
	v_exp_f32_e32 v1, v1
	s_nop 0
	v_pk_add_f32 v[0:1], v[0:1], 1.0 op_sel_hi:[1,0]
	s_barrier
	v_rcp_f32_e32 v49, v51
	s_nop 0
	v_mov_b32_e32 v230, 0x11410
	v_mov_b32_e32 v231, 0xfff
	v_rcp_f32_e32 v50, v50
	s_nop 0
	v_cvt_pk_bf16_f32 v49, v50, v49
	v_mul_f32_e32 v50, 0xbfb8aa3b, v52
	v_mul_f32_e32 v51, 0xbfb8aa3b, v53
	v_exp_f32_e32 v50, v50
	v_exp_f32_e32 v51, v51
	s_nop 0
	v_pk_add_f32 v[50:51], v[50:51], 1.0 op_sel_hi:[1,0]
	s_nop 0
	s_nop 0
	v_rcp_f32_e32 v51, v51
	s_nop 0
	s_nop 0
	v_rcp_f32_e32 v50, v50
	s_nop 0
	v_cvt_pk_bf16_f32 v50, v50, v51
	v_mul_f32_e32 v51, 0xbfb8aa3b, v54
	v_exp_f32_e32 v52, v51
	v_mul_f32_e32 v51, 0xbfb8aa3b, v55
	v_exp_f32_e32 v53, v51
	s_nop 0
	v_pk_add_f32 v[52:53], v[52:53], 1.0 op_sel_hi:[1,0]
	s_nop 0
	s_nop 0
	v_rcp_f32_e32 v51, v53
	s_nop 0
	s_nop 0
	v_rcp_f32_e32 v52, v52
	s_nop 0
	v_cvt_pk_bf16_f32 v51, v52, v51
	v_mul_f32_e32 v52, 0xbfb8aa3b, v56
	v_mul_f32_e32 v53, 0xbfb8aa3b, v57
	v_exp_f32_e32 v52, v52
	v_exp_f32_e32 v53, v53
	s_nop 0
	v_pk_add_f32 v[52:53], v[52:53], 1.0 op_sel_hi:[1,0]
	s_nop 0
	s_nop 0
	v_rcp_f32_e32 v53, v53
	s_nop 0
	s_nop 0
	v_rcp_f32_e32 v52, v52
	s_nop 0
	v_cvt_pk_bf16_f32 v52, v52, v53
	v_mul_f32_e32 v53, 0xbfb8aa3b, v58
	v_exp_f32_e32 v54, v53
	v_mul_f32_e32 v53, 0xbfb8aa3b, v59
	v_exp_f32_e32 v55, v53
	s_nop 0
	v_pk_add_f32 v[54:55], v[54:55], 1.0 op_sel_hi:[1,0]
	s_nop 0
	s_nop 0
	v_rcp_f32_e32 v53, v55
	s_nop 0
	s_nop 0
	v_rcp_f32_e32 v54, v54
	s_nop 0
	v_cvt_pk_bf16_f32 v53, v54, v53
	v_mul_f32_e32 v54, 0xbfb8aa3b, v60
	v_mul_f32_e32 v55, 0xbfb8aa3b, v61
	v_exp_f32_e32 v54, v54
	v_exp_f32_e32 v55, v55
	s_nop 0
	v_pk_add_f32 v[54:55], v[54:55], 1.0 op_sel_hi:[1,0]
	s_nop 0
	s_nop 0
	v_rcp_f32_e32 v55, v55
	s_nop 0
	s_nop 0
	v_rcp_f32_e32 v54, v54
	s_nop 0
	v_cvt_pk_bf16_f32 v54, v54, v55
	v_mul_f32_e32 v55, 0xbfb8aa3b, v62
	v_exp_f32_e32 v56, v55
	v_mul_f32_e32 v55, 0xbfb8aa3b, v63
	v_exp_f32_e32 v57, v55
	s_nop 0
	v_pk_add_f32 v[56:57], v[56:57], 1.0 op_sel_hi:[1,0]
	s_nop 0
	s_nop 0
	v_rcp_f32_e32 v55, v57
	s_nop 0
	s_nop 0
	v_rcp_f32_e32 v56, v56
	s_nop 0
	v_cvt_pk_bf16_f32 v55, v56, v55
	s_nop 0
	v_rcp_f32_e32 v33, v33
	s_nop 0
	s_nop 0
	v_rcp_f32_e32 v32, v32
	s_nop 0
	v_cvt_pk_bf16_f32 v32, v32, v33
	v_mul_f32_e32 v33, 0xbfb8aa3b, v34
	v_exp_f32_e32 v34, v33
	v_mul_f32_e32 v33, 0xbfb8aa3b, v35
	v_exp_f32_e32 v35, v33
	s_nop 0
	v_pk_add_f32 v[34:35], v[34:35], 1.0 op_sel_hi:[1,0]
	s_nop 0
	s_nop 0
	v_rcp_f32_e32 v33, v35
	s_nop 0
	s_nop 0
	v_rcp_f32_e32 v34, v34
	s_nop 0
	v_cvt_pk_bf16_f32 v33, v34, v33
	v_mul_f32_e32 v34, 0xbfb8aa3b, v36
	v_mul_f32_e32 v35, 0xbfb8aa3b, v37
	v_exp_f32_e32 v34, v34
	v_exp_f32_e32 v35, v35
	s_nop 0
	v_pk_add_f32 v[34:35], v[34:35], 1.0 op_sel_hi:[1,0]
	s_nop 0
	s_nop 0
	v_rcp_f32_e32 v35, v35
	s_nop 0
	s_nop 0
	v_rcp_f32_e32 v34, v34
	s_nop 0
	v_cvt_pk_bf16_f32 v34, v34, v35
	v_mul_f32_e32 v35, 0xbfb8aa3b, v38
	v_exp_f32_e32 v36, v35
	v_mul_f32_e32 v35, 0xbfb8aa3b, v39
	v_exp_f32_e32 v37, v35
	s_nop 0
	v_pk_add_f32 v[36:37], v[36:37], 1.0 op_sel_hi:[1,0]
	s_nop 0
	s_nop 0
	v_rcp_f32_e32 v35, v37
	s_nop 0
	s_nop 0
	v_rcp_f32_e32 v36, v36
	s_nop 0
	v_cvt_pk_bf16_f32 v35, v36, v35
	v_mul_f32_e32 v36, 0xbfb8aa3b, v40
	v_mul_f32_e32 v37, 0xbfb8aa3b, v41
	v_exp_f32_e32 v36, v36
	v_exp_f32_e32 v37, v37
	s_nop 0
	v_pk_add_f32 v[36:37], v[36:37], 1.0 op_sel_hi:[1,0]
	s_nop 0
	s_nop 0
	v_rcp_f32_e32 v37, v37
	s_nop 0
	s_nop 0
	v_rcp_f32_e32 v36, v36
	s_nop 0
	v_cvt_pk_bf16_f32 v36, v36, v37
	v_mul_f32_e32 v37, 0xbfb8aa3b, v42
	v_exp_f32_e32 v38, v37
	v_mul_f32_e32 v37, 0xbfb8aa3b, v43
	v_exp_f32_e32 v39, v37
	s_nop 0
	v_pk_add_f32 v[38:39], v[38:39], 1.0 op_sel_hi:[1,0]
	s_nop 0
	s_nop 0
	v_rcp_f32_e32 v37, v39
	s_nop 0
	s_nop 0
	v_rcp_f32_e32 v38, v38
	s_nop 0
	v_cvt_pk_bf16_f32 v37, v38, v37
	v_mul_f32_e32 v38, 0xbfb8aa3b, v44
	v_mul_f32_e32 v39, 0xbfb8aa3b, v45
	v_exp_f32_e32 v38, v38
	v_exp_f32_e32 v39, v39
	s_nop 0
	v_pk_add_f32 v[38:39], v[38:39], 1.0 op_sel_hi:[1,0]
	s_nop 0
	s_nop 0
	v_rcp_f32_e32 v39, v39
	s_nop 0
	s_nop 0
	v_rcp_f32_e32 v38, v38
	s_nop 0
	v_cvt_pk_bf16_f32 v38, v38, v39
	v_mul_f32_e32 v39, 0xbfb8aa3b, v46
	v_exp_f32_e32 v40, v39
	v_mul_f32_e32 v39, 0xbfb8aa3b, v47
	v_exp_f32_e32 v41, v39
	s_nop 0
	v_pk_add_f32 v[40:41], v[40:41], 1.0 op_sel_hi:[1,0]
	s_nop 0
	s_nop 0
	v_rcp_f32_e32 v39, v41
	s_nop 0
	s_nop 0
	v_rcp_f32_e32 v40, v40
	s_nop 0
	v_cvt_pk_bf16_f32 v39, v40, v39
	s_nop 0
	v_rcp_f32_e32 v17, v17
	s_nop 0
	s_nop 0
	v_rcp_f32_e32 v16, v16
	s_nop 0
	v_cvt_pk_bf16_f32 v16, v16, v17
	v_mul_f32_e32 v17, 0xbfb8aa3b, v18
	v_exp_f32_e32 v18, v17
	v_mul_f32_e32 v17, 0xbfb8aa3b, v19
	v_exp_f32_e32 v19, v17
	s_nop 0
	v_pk_add_f32 v[18:19], v[18:19], 1.0 op_sel_hi:[1,0]
	s_nop 0
	s_nop 0
; DEV float sigmoidf_(float x) { return 1.0f / (1.0f + __expf(-x)); }
; DEV void phase_p5(const Params& p, int l, unsigned char* smem) {
;     ...
; #pragma unroll
;       for (int a_ = 0; a_ < 2; ++a_)
; #pragma unroll
;         for (int b_ = 0; b_ < 2; ++b_) {
; #pragma unroll
;           for (int r = 0; r < 8; ++r) ga[a_][b_][r] = pk2bf(sigmoidf_(g[a_][b_][2 * r]), sigmoidf_(g[a_][b_][2 * r + 1]));
;           __builtin_amdgcn_sched_barrier(0);
;         }
;     ...
; #pragma unroll
;     for (int mi = 0; mi < 2; ++mi)
; #pragma unroll
;       for (int ni = 0; ni < 2; ++ni)
; #pragma unroll
;         for (int r = 0; r < 8; ++r)
;           res[mi][ni][r] = pk2bf(acc[mi][ni][2 * r] * gate_a(mi, ni, 2 * r), acc[mi][ni][2 * r + 1] * gate_a(mi, ni, 2 * r + 1));
	v_rcp_f32_e32 v17, v19
	s_nop 0
	s_nop 0
	v_rcp_f32_e32 v18, v18
	s_nop 0
	v_cvt_pk_bf16_f32 v17, v18, v17
	v_mul_f32_e32 v18, 0xbfb8aa3b, v20
	v_mul_f32_e32 v19, 0xbfb8aa3b, v21
	v_exp_f32_e32 v18, v18
	v_exp_f32_e32 v19, v19
	s_nop 0
	v_pk_add_f32 v[18:19], v[18:19], 1.0 op_sel_hi:[1,0]
	s_nop 0
	s_nop 0
	v_rcp_f32_e32 v19, v19
	s_nop 0
	s_nop 0
	v_rcp_f32_e32 v18, v18
	s_nop 0
	v_cvt_pk_bf16_f32 v18, v18, v19
	v_mul_f32_e32 v19, 0xbfb8aa3b, v22
	v_exp_f32_e32 v20, v19
	v_mul_f32_e32 v19, 0xbfb8aa3b, v23
	v_exp_f32_e32 v21, v19
	s_nop 0
	v_pk_add_f32 v[20:21], v[20:21], 1.0 op_sel_hi:[1,0]
	s_nop 0
	s_nop 0
	v_rcp_f32_e32 v19, v21
	s_nop 0
	s_nop 0
	v_rcp_f32_e32 v20, v20
	s_nop 0
	v_cvt_pk_bf16_f32 v19, v20, v19
	v_mul_f32_e32 v20, 0xbfb8aa3b, v24
	v_mul_f32_e32 v21, 0xbfb8aa3b, v25
	v_exp_f32_e32 v20, v20
	v_exp_f32_e32 v21, v21
	s_nop 0
	v_pk_add_f32 v[20:21], v[20:21], 1.0 op_sel_hi:[1,0]
	s_nop 0
	s_nop 0
	v_rcp_f32_e32 v21, v21
	s_nop 0
	s_nop 0
	v_rcp_f32_e32 v20, v20
	s_nop 0
	v_cvt_pk_bf16_f32 v20, v20, v21
	v_mul_f32_e32 v21, 0xbfb8aa3b, v26
	v_exp_f32_e32 v22, v21
	v_mul_f32_e32 v21, 0xbfb8aa3b, v27
	v_exp_f32_e32 v23, v21
	s_nop 0
	v_pk_add_f32 v[22:23], v[22:23], 1.0 op_sel_hi:[1,0]
	s_nop 0
	s_nop 0
	v_rcp_f32_e32 v21, v23
	s_nop 0
	s_nop 0
	v_rcp_f32_e32 v22, v22
	s_nop 0
	v_cvt_pk_bf16_f32 v21, v22, v21
	v_mul_f32_e32 v22, 0xbfb8aa3b, v28
	v_mul_f32_e32 v23, 0xbfb8aa3b, v29
	v_exp_f32_e32 v22, v22
	v_exp_f32_e32 v23, v23
	s_nop 0
	v_pk_add_f32 v[22:23], v[22:23], 1.0 op_sel_hi:[1,0]
	s_nop 0
	s_nop 0
	v_rcp_f32_e32 v23, v23
	s_nop 0
	s_nop 0
	v_rcp_f32_e32 v22, v22
	s_nop 0
	v_cvt_pk_bf16_f32 v22, v22, v23
	v_mul_f32_e32 v23, 0xbfb8aa3b, v30
	v_exp_f32_e32 v24, v23
	v_mul_f32_e32 v23, 0xbfb8aa3b, v31
	v_exp_f32_e32 v25, v23
	s_nop 0
	v_pk_add_f32 v[24:25], v[24:25], 1.0 op_sel_hi:[1,0]
	s_nop 0
	s_nop 0
	v_rcp_f32_e32 v23, v25
	s_nop 0
	s_nop 0
	v_rcp_f32_e32 v24, v24
	s_nop 0
	v_cvt_pk_bf16_f32 v23, v24, v23
	s_nop 0
	v_rcp_f32_e32 v1, v1
	s_nop 0
	s_nop 0
	v_rcp_f32_e32 v0, v0
	s_nop 0
	v_cvt_pk_bf16_f32 v0, v0, v1
	v_mul_f32_e32 v1, 0xbfb8aa3b, v2
	v_exp_f32_e32 v2, v1
	v_mul_f32_e32 v1, 0xbfb8aa3b, v3
	v_exp_f32_e32 v3, v1
	s_nop 0
	v_pk_add_f32 v[2:3], v[2:3], 1.0 op_sel_hi:[1,0]
	s_nop 0
	s_nop 0
	v_rcp_f32_e32 v1, v3
	s_nop 0
	s_nop 0
	v_rcp_f32_e32 v2, v2
	s_nop 0
	v_cvt_pk_bf16_f32 v1, v2, v1
	v_mul_f32_e32 v2, 0xbfb8aa3b, v4
	v_mul_f32_e32 v3, 0xbfb8aa3b, v5
	v_exp_f32_e32 v2, v2
	v_exp_f32_e32 v3, v3
	s_nop 0
	v_pk_add_f32 v[2:3], v[2:3], 1.0 op_sel_hi:[1,0]
	s_nop 0
	s_nop 0
	v_rcp_f32_e32 v3, v3
	s_nop 0
	s_nop 0
	v_rcp_f32_e32 v2, v2
	s_nop 0
	v_cvt_pk_bf16_f32 v2, v2, v3
	v_mul_f32_e32 v3, 0xbfb8aa3b, v6
	v_exp_f32_e32 v4, v3
	v_mul_f32_e32 v3, 0xbfb8aa3b, v7
	v_exp_f32_e32 v5, v3
	s_nop 0
	v_pk_add_f32 v[4:5], v[4:5], 1.0 op_sel_hi:[1,0]
	s_nop 0
	s_nop 0
	v_rcp_f32_e32 v3, v5
	s_nop 0
	s_nop 0
	v_rcp_f32_e32 v4, v4
	s_nop 0
	v_cvt_pk_bf16_f32 v3, v4, v3
	v_mul_f32_e32 v4, 0xbfb8aa3b, v8
	v_mul_f32_e32 v5, 0xbfb8aa3b, v9
	v_exp_f32_e32 v4, v4
	v_exp_f32_e32 v5, v5
	s_nop 0
	v_pk_add_f32 v[4:5], v[4:5], 1.0 op_sel_hi:[1,0]
	s_nop 0
	s_nop 0
	v_rcp_f32_e32 v5, v5
	s_nop 0
	s_nop 0
	v_rcp_f32_e32 v4, v4
	s_nop 0
	v_cvt_pk_bf16_f32 v4, v4, v5
	v_mul_f32_e32 v5, 0xbfb8aa3b, v10
	v_exp_f32_e32 v6, v5
	v_mul_f32_e32 v5, 0xbfb8aa3b, v11
	v_exp_f32_e32 v7, v5
	s_nop 0
	v_pk_add_f32 v[6:7], v[6:7], 1.0 op_sel_hi:[1,0]
	s_nop 0
	s_nop 0
	v_rcp_f32_e32 v5, v7
	s_nop 0
	s_nop 0
	v_rcp_f32_e32 v6, v6
	s_nop 0
	v_cvt_pk_bf16_f32 v28, v6, v5
	v_mul_f32_e32 v5, 0xbfb8aa3b, v12
	v_exp_f32_e32 v6, v5
	v_mul_f32_e32 v5, 0xbfb8aa3b, v13
	v_exp_f32_e32 v7, v5
	s_nop 0
	v_pk_add_f32 v[6:7], v[6:7], 1.0 op_sel_hi:[1,0]
	s_nop 0
	s_nop 0
	v_rcp_f32_e32 v5, v7
	s_nop 0
	s_nop 0
	v_rcp_f32_e32 v6, v6
	s_nop 0
	v_cvt_pk_bf16_f32 v29, v6, v5
	v_mul_f32_e32 v5, 0xbfb8aa3b, v14
	v_exp_f32_e32 v6, v5
	v_mul_f32_e32 v5, 0xbfb8aa3b, v15
	v_exp_f32_e32 v7, v5
	s_nop 0
	v_pk_add_f32 v[6:7], v[6:7], 1.0 op_sel_hi:[1,0]
	s_nop 0
	s_nop 0
	v_rcp_f32_e32 v5, v7
	s_nop 0
	s_nop 0
	v_rcp_f32_e32 v6, v6
	s_nop 0
	v_cvt_pk_bf16_f32 v30, v6, v5
	v_lshlrev_b32_e32 v6, 16, v48
	v_and_b32_e32 v7, 0xffff0000, v48
	v_pk_mul_f32 v[6:7], v[144:145], v[6:7]
	s_nop 0
	v_cvt_pk_bf16_f32 v31, v6, v7
	v_lshlrev_b32_e32 v6, 16, v49
	v_and_b32_e32 v7, 0xffff0000, v49
	v_pk_mul_f32 v[6:7], v[146:147], v[6:7]
	s_nop 0
	v_cvt_pk_bf16_f32 v40, v6, v7
	v_lshlrev_b32_e32 v6, 16, v50
	v_and_b32_e32 v7, 0xffff0000, v50
	v_pk_mul_f32 v[6:7], v[148:149], v[6:7]
	s_nop 0
	v_cvt_pk_bf16_f32 v41, v6, v7
	v_lshlrev_b32_e32 v6, 16, v51
	v_and_b32_e32 v7, 0xffff0000, v51
	v_pk_mul_f32 v[6:7], v[150:151], v[6:7]
	s_nop 0
	v_cvt_pk_bf16_f32 v42, v6, v7
	v_lshlrev_b32_e32 v6, 16, v52
	v_and_b32_e32 v7, 0xffff0000, v52
	v_pk_mul_f32 v[6:7], v[152:153], v[6:7]
	s_nop 0
	v_cvt_pk_bf16_f32 v43, v6, v7
	v_lshlrev_b32_e32 v6, 16, v53
	v_and_b32_e32 v7, 0xffff0000, v53
	v_pk_mul_f32 v[6:7], v[154:155], v[6:7]
	s_nop 0
	v_cvt_pk_bf16_f32 v44, v6, v7
	v_lshlrev_b32_e32 v6, 16, v54
	v_and_b32_e32 v7, 0xffff0000, v54
	v_pk_mul_f32 v[6:7], v[156:157], v[6:7]
	s_nop 0
	v_cvt_pk_bf16_f32 v45, v6, v7
	v_lshlrev_b32_e32 v6, 16, v55
	v_and_b32_e32 v7, 0xffff0000, v55
	v_pk_mul_f32 v[6:7], v[158:159], v[6:7]
	s_nop 0
	v_cvt_pk_bf16_f32 v46, v6, v7
	v_lshlrev_b32_e32 v6, 16, v32
	v_and_b32_e32 v7, 0xffff0000, v32
	v_pk_mul_f32 v[6:7], v[128:129], v[6:7]
	s_nop 0
	v_cvt_pk_bf16_f32 v32, v6, v7
	v_lshlrev_b32_e32 v6, 16, v33
	v_and_b32_e32 v7, 0xffff0000, v33
	v_pk_mul_f32 v[6:7], v[130:131], v[6:7]
	s_nop 0
	v_cvt_pk_bf16_f32 v33, v6, v7
	v_lshlrev_b32_e32 v6, 16, v34
	v_and_b32_e32 v7, 0xffff0000, v34
; DEV u16 f2bf(float f) { return (u16)(pk2bf(f, 0.f) & 0xffffu); }
; DEV void phase_p5(const Params& p, int l, unsigned char* smem) {
;     ...
; #pragma unroll
;     for (int mi = 0; mi < 2; ++mi)
; #pragma unroll
;       for (int ni = 0; ni < 2; ++ni)
; #pragma unroll
;         for (int r = 0; r < 8; ++r)
;           res[mi][ni][r] = pk2bf(acc[mi][ni][2 * r] * gate_a(mi, ni, 2 * r), acc[mi][ni][2 * r + 1] * gate_a(mi, ni, 2 * r + 1));
;     zero_acc(acc);
;     gemm_main<0>(acc, YB + (size_t)mt * 128 * 1024, 1024, WL + WO_BB + (size_t)nt * 128 * 1024, 1024, 1024, smem);
;     __syncthreads();
;     acc_foreach([&](int mi, int ni, int r, int row, int col) __attribute__((always_inline)) {
;       const unsigned rq = res[mi][ni][r >> 1];
;       const float rv = __uint_as_float((r & 1) ? (rq & 0xffff0000u) : (rq << 16));
;       sC[row * LDC + col] = f2bf(rv + acc[mi][ni][r] * gate_b(mi, ni, r));
;     });
	v_pk_mul_f32 v[6:7], v[132:133], v[6:7]
	s_nop 0
	v_cvt_pk_bf16_f32 v34, v6, v7
	v_lshlrev_b32_e32 v6, 16, v35
	v_and_b32_e32 v7, 0xffff0000, v35
	v_pk_mul_f32 v[6:7], v[134:135], v[6:7]
	s_nop 0
	v_cvt_pk_bf16_f32 v35, v6, v7
	v_lshlrev_b32_e32 v6, 16, v36
	v_and_b32_e32 v7, 0xffff0000, v36
	v_pk_mul_f32 v[6:7], v[136:137], v[6:7]
	s_nop 0
	v_cvt_pk_bf16_f32 v27, v6, v7
	v_lshlrev_b32_e32 v6, 16, v37
	v_and_b32_e32 v7, 0xffff0000, v37
	v_pk_mul_f32 v[6:7], v[138:139], v[6:7]
	s_nop 0
	v_cvt_pk_bf16_f32 v26, v6, v7
	v_lshlrev_b32_e32 v6, 16, v38
	v_and_b32_e32 v7, 0xffff0000, v38
	v_pk_mul_f32 v[6:7], v[140:141], v[6:7]
	s_nop 0
	v_cvt_pk_bf16_f32 v25, v6, v7
	v_lshlrev_b32_e32 v6, 16, v39
	v_and_b32_e32 v7, 0xffff0000, v39
	v_pk_mul_f32 v[6:7], v[142:143], v[6:7]
	s_nop 0
	v_cvt_pk_bf16_f32 v24, v6, v7
	v_lshlrev_b32_e32 v6, 16, v16
	v_and_b32_e32 v7, 0xffff0000, v16
	v_pk_mul_f32 v[6:7], v[112:113], v[6:7]
	s_nop 0
	v_cvt_pk_bf16_f32 v16, v6, v7
	v_lshlrev_b32_e32 v6, 16, v17
	v_and_b32_e32 v7, 0xffff0000, v17
	v_pk_mul_f32 v[6:7], v[114:115], v[6:7]
	s_nop 0
	v_cvt_pk_bf16_f32 v15, v6, v7
	v_lshlrev_b32_e32 v6, 16, v18
	v_and_b32_e32 v7, 0xffff0000, v18
	v_pk_mul_f32 v[6:7], v[116:117], v[6:7]
	s_nop 0
	v_cvt_pk_bf16_f32 v14, v6, v7
	v_lshlrev_b32_e32 v6, 16, v19
	v_and_b32_e32 v7, 0xffff0000, v19
	v_pk_mul_f32 v[6:7], v[118:119], v[6:7]
	s_nop 0
	v_cvt_pk_bf16_f32 v13, v6, v7
	v_lshlrev_b32_e32 v6, 16, v20
	v_and_b32_e32 v7, 0xffff0000, v20
	v_pk_mul_f32 v[6:7], v[120:121], v[6:7]
	v_lshlrev_b32_e32 v20, 16, v31
	v_cvt_pk_bf16_f32 v12, v6, v7
	v_lshlrev_b32_e32 v6, 16, v21
	v_and_b32_e32 v7, 0xffff0000, v21
	v_pk_mul_f32 v[6:7], v[122:123], v[6:7]
	s_nop 0
	v_cvt_pk_bf16_f32 v11, v6, v7
	v_lshlrev_b32_e32 v6, 16, v22
	v_and_b32_e32 v7, 0xffff0000, v22
	v_pk_mul_f32 v[6:7], v[124:125], v[6:7]
	s_nop 0
	v_cvt_pk_bf16_f32 v10, v6, v7
	v_lshlrev_b32_e32 v6, 16, v23
	v_and_b32_e32 v7, 0xffff0000, v23
	v_pk_mul_f32 v[6:7], v[126:127], v[6:7]
	s_nop 0
	v_cvt_pk_bf16_f32 v9, v6, v7
	v_lshlrev_b32_e32 v6, 16, v0
	v_and_b32_e32 v7, 0xffff0000, v0
	v_lshlrev_b32_e32 v0, 16, v1
	v_and_b32_e32 v1, 0xffff0000, v1
	v_pk_mul_f32 v[6:7], v[80:81], v[6:7]
	v_pk_mul_f32 v[0:1], v[82:83], v[0:1]
	v_cvt_pk_bf16_f32 v8, v6, v7
	v_cvt_pk_bf16_f32 v7, v0, v1
	v_lshlrev_b32_e32 v0, 16, v2
	v_and_b32_e32 v1, 0xffff0000, v2
	v_pk_mul_f32 v[0:1], v[84:85], v[0:1]
	s_nop 0
	v_cvt_pk_bf16_f32 v6, v0, v1
	v_lshlrev_b32_e32 v0, 16, v3
	v_and_b32_e32 v1, 0xffff0000, v3
	v_pk_mul_f32 v[0:1], v[86:87], v[0:1]
	s_nop 0
	v_cvt_pk_bf16_f32 v5, v0, v1
	v_lshlrev_b32_e32 v0, 16, v4
	v_and_b32_e32 v1, 0xffff0000, v4
	v_pk_mul_f32 v[0:1], v[88:89], v[0:1]
	s_nop 0
	v_cvt_pk_bf16_f32 v4, v0, v1
	v_lshlrev_b32_e32 v0, 16, v28
	v_and_b32_e32 v1, 0xffff0000, v28
	v_pk_mul_f32 v[0:1], v[90:91], v[0:1]
	s_nop 0
	v_cvt_pk_bf16_f32 v3, v0, v1
	v_lshlrev_b32_e32 v0, 16, v29
	v_and_b32_e32 v1, 0xffff0000, v29
	v_pk_mul_f32 v[0:1], v[92:93], v[0:1]
	s_nop 0
	v_cvt_pk_bf16_f32 v2, v0, v1
	v_lshlrev_b32_e32 v0, 16, v30
	v_and_b32_e32 v1, 0xffff0000, v30
	v_pk_mul_f32 v[0:1], v[94:95], v[0:1]
	s_nop 0
	v_cvt_pk_bf16_f32 v0, v0, v1
	v_mov_b32_e32 v1, v232
	s_nop 0
	v_lshrrev_b32_e32 v18, 3, v1
	v_lshrrev_b32_e32 v17, 1, v1
	v_and_b32_e32 v18, 4, v18
	v_and_or_b32 v17, v17, s72, v18
	ds_read2st64_b32 v[18:19], v248 offset0:148 offset1:152
	v_and_b32_e32 v1, 0x5f, v1
	v_mul_lo_u32 v17, v17, s42
	v_lshl_add_u32 v1, v1, 1, v17
	v_and_b32_e32 v17, 0xffff0000, v31
	s_waitcnt lgkmcnt(0)
	v_lshlrev_b32_e32 v21, 16, v18
	v_and_b32_e32 v18, 0xffff0000, v18
	v_fmac_f32_e32 v17, v177, v18
	v_cvt_pk_bf16_f32 v17, v17, s0
	ds_write_b16 v1, v17 offset:272
	v_lshlrev_b32_e32 v17, 16, v40
	v_lshlrev_b32_e32 v18, 16, v19
	v_fmac_f32_e32 v17, v178, v18
	v_cvt_pk_bf16_f32 v17, v17, s0
	ds_write_b16 v1, v17 offset:544
	v_and_b32_e32 v17, 0xffff0000, v40
	v_and_b32_e32 v18, 0xffff0000, v19
	v_fmac_f32_e32 v17, v179, v18
	ds_read2st64_b32 v[18:19], v248 offset0:156 offset1:160
	v_fmac_f32_e32 v20, v176, v21
	v_cvt_pk_bf16_f32 v20, v20, s0
	v_cvt_pk_bf16_f32 v17, v17, s0
	ds_write_b16 v1, v20
	ds_write_b16 v1, v17 offset:816
	v_lshlrev_b32_e32 v17, 16, v41
	s_waitcnt lgkmcnt(2)
	v_lshlrev_b32_e32 v20, 16, v18
	v_fmac_f32_e32 v17, v180, v20
	v_cvt_pk_bf16_f32 v17, v17, s0
	ds_write_b16 v1, v17 offset:2176
	v_and_b32_e32 v17, 0xffff0000, v41
	v_and_b32_e32 v18, 0xffff0000, v18
	v_fmac_f32_e32 v17, v181, v18
	v_cvt_pk_bf16_f32 v17, v17, s0
	ds_write_b16 v1, v17 offset:2448
	v_lshlrev_b32_e32 v17, 16, v42
	v_lshlrev_b32_e32 v18, 16, v19
	v_fmac_f32_e32 v17, v182, v18
	v_cvt_pk_bf16_f32 v17, v17, s0
	ds_write_b16 v1, v17 offset:2720
	v_and_b32_e32 v17, 0xffff0000, v42
	v_and_b32_e32 v18, 0xffff0000, v19
	v_fmac_f32_e32 v17, v183, v18
	ds_read2st64_b32 v[18:19], v248 offset0:164 offset1:168
	v_cvt_pk_bf16_f32 v17, v17, s0
	ds_write_b16 v1, v17 offset:2992
	v_lshlrev_b32_e32 v17, 16, v43
	s_waitcnt lgkmcnt(1)
	v_lshlrev_b32_e32 v20, 16, v18
	v_fmac_f32_e32 v17, v184, v20
	v_cvt_pk_bf16_f32 v17, v17, s0
	ds_write_b16 v1, v17 offset:4352
	v_and_b32_e32 v17, 0xffff0000, v43
	v_and_b32_e32 v18, 0xffff0000, v18
	v_fmac_f32_e32 v17, v185, v18
	v_cvt_pk_bf16_f32 v17, v17, s0
	ds_write_b16 v1, v17 offset:4624
	v_lshlrev_b32_e32 v17, 16, v44
	v_lshlrev_b32_e32 v18, 16, v19
	v_fmac_f32_e32 v17, v186, v18
	v_cvt_pk_bf16_f32 v17, v17, s0
	ds_write_b16 v1, v17 offset:4896
	v_and_b32_e32 v17, 0xffff0000, v44
	v_and_b32_e32 v18, 0xffff0000, v19
	v_fmac_f32_e32 v17, v187, v18
	ds_read2st64_b32 v[18:19], v248 offset0:172 offset1:176
	v_cvt_pk_bf16_f32 v17, v17, s0
	ds_write_b16 v1, v17 offset:5168
	v_lshlrev_b32_e32 v17, 16, v45
	s_waitcnt lgkmcnt(1)
; DEV u16 f2bf(float f) { return (u16)(pk2bf(f, 0.f) & 0xffffu); }
; DEV void phase_p5(const Params& p, int l, unsigned char* smem) {
;     ...
;     auto gate_a = [&](int mi, int ni, int r) __attribute__((always_inline)) -> float {
;       const unsigned gq = ga[mi][ni][r >> 1];
;       return __uint_as_float((r & 1) ? (gq & 0xffff0000u) : (gq << 16));
;     };
;     auto gate_b = [&](int mi, int ni, int r) __attribute__((always_inline)) -> float {
;       const unsigned gq = sG[((mi * 2 + ni) * 8 + (r >> 1)) * 256 + tid];
;       return __uint_as_float((r & 1) ? (gq & 0xffff0000u) : (gq << 16));
;     };
;     ...
;     acc_foreach([&](int mi, int ni, int r, int row, int col) __attribute__((always_inline)) {
;       const unsigned rq = res[mi][ni][r >> 1];
;       const float rv = __uint_as_float((r & 1) ? (rq & 0xffff0000u) : (rq << 16));
;       sC[row * LDC + col] = f2bf(rv + acc[mi][ni][r] * gate_b(mi, ni, r));
;     });
	v_lshlrev_b32_e32 v20, 16, v18
	v_fmac_f32_e32 v17, v188, v20
	v_cvt_pk_bf16_f32 v17, v17, s0
	ds_write_b16 v1, v17 offset:6528
	v_and_b32_e32 v17, 0xffff0000, v45
	v_and_b32_e32 v18, 0xffff0000, v18
	v_fmac_f32_e32 v17, v189, v18
	v_cvt_pk_bf16_f32 v17, v17, s0
	ds_write_b16 v1, v17 offset:6800
	v_lshlrev_b32_e32 v17, 16, v46
	v_lshlrev_b32_e32 v18, 16, v19
	v_fmac_f32_e32 v17, v190, v18
	v_cvt_pk_bf16_f32 v17, v17, s0
	ds_write_b16 v1, v17 offset:7072
	v_and_b32_e32 v17, 0xffff0000, v46
	v_and_b32_e32 v18, 0xffff0000, v19
	v_fmac_f32_e32 v17, v191, v18
	ds_read2st64_b32 v[18:19], v248 offset0:180 offset1:184
	v_cvt_pk_bf16_f32 v17, v17, s0
	ds_write_b16 v1, v17 offset:7344
	v_lshlrev_b32_e32 v17, 16, v32
	s_waitcnt lgkmcnt(1)
	v_lshlrev_b32_e32 v20, 16, v18
	v_fmac_f32_e32 v17, v160, v20
	v_cvt_pk_bf16_f32 v17, v17, s0
	ds_write_b16 v1, v17 offset:64
	v_and_b32_e32 v17, 0xffff0000, v32
	v_and_b32_e32 v18, 0xffff0000, v18
	v_fmac_f32_e32 v17, v161, v18
	v_cvt_pk_bf16_f32 v17, v17, s0
	ds_write_b16 v1, v17 offset:336
	v_lshlrev_b32_e32 v17, 16, v33
	v_lshlrev_b32_e32 v18, 16, v19
	v_fmac_f32_e32 v17, v162, v18
	v_cvt_pk_bf16_f32 v17, v17, s0
	ds_write_b16 v1, v17 offset:608
	v_and_b32_e32 v17, 0xffff0000, v33
	v_and_b32_e32 v18, 0xffff0000, v19
	v_fmac_f32_e32 v17, v163, v18
	ds_read2st64_b32 v[18:19], v248 offset0:188 offset1:192
	v_cvt_pk_bf16_f32 v17, v17, s0
	ds_write_b16 v1, v17 offset:880
	v_lshlrev_b32_e32 v17, 16, v34
	s_waitcnt lgkmcnt(1)
	v_lshlrev_b32_e32 v20, 16, v18
	v_fmac_f32_e32 v17, v164, v20
	v_cvt_pk_bf16_f32 v17, v17, s0
	ds_write_b16 v1, v17 offset:2240
	v_and_b32_e32 v17, 0xffff0000, v34
	v_and_b32_e32 v18, 0xffff0000, v18
	v_fmac_f32_e32 v17, v165, v18
	v_cvt_pk_bf16_f32 v17, v17, s0
	ds_write_b16 v1, v17 offset:2512
	v_lshlrev_b32_e32 v17, 16, v35
	v_lshlrev_b32_e32 v18, 16, v19
	v_fmac_f32_e32 v17, v166, v18
	v_cvt_pk_bf16_f32 v17, v17, s0
	ds_write_b16 v1, v17 offset:2784
	v_and_b32_e32 v17, 0xffff0000, v35
	v_and_b32_e32 v18, 0xffff0000, v19
	v_fmac_f32_e32 v17, v167, v18
	ds_read2st64_b32 v[18:19], v248 offset0:196 offset1:200
	v_cvt_pk_bf16_f32 v17, v17, s0
	ds_write_b16 v1, v17 offset:3056
	v_lshlrev_b32_e32 v17, 16, v27
	s_waitcnt lgkmcnt(1)
	v_lshlrev_b32_e32 v20, 16, v18
	v_fmac_f32_e32 v17, v168, v20
	v_cvt_pk_bf16_f32 v17, v17, s0
	ds_write_b16 v1, v17 offset:4416
	v_and_b32_e32 v17, 0xffff0000, v27
	v_and_b32_e32 v18, 0xffff0000, v18
	v_fmac_f32_e32 v17, v169, v18
	v_cvt_pk_bf16_f32 v17, v17, s0
	ds_write_b16 v1, v17 offset:4688
	v_lshlrev_b32_e32 v17, 16, v26
	v_lshlrev_b32_e32 v18, 16, v19
	v_fmac_f32_e32 v17, v170, v18
	v_cvt_pk_bf16_f32 v17, v17, s0
	ds_write_b16 v1, v17 offset:4960
	v_and_b32_e32 v17, 0xffff0000, v26
	v_and_b32_e32 v18, 0xffff0000, v19
	v_fmac_f32_e32 v17, v171, v18
	ds_read2st64_b32 v[18:19], v248 offset0:204 offset1:208
	v_cvt_pk_bf16_f32 v17, v17, s0
	ds_write_b16 v1, v17 offset:5232
	v_lshlrev_b32_e32 v17, 16, v25
	s_waitcnt lgkmcnt(1)
	v_lshlrev_b32_e32 v20, 16, v18
	v_fmac_f32_e32 v17, v172, v20
	v_cvt_pk_bf16_f32 v17, v17, s0
	ds_write_b16 v1, v17 offset:6592
	v_and_b32_e32 v17, 0xffff0000, v25
	v_and_b32_e32 v18, 0xffff0000, v18
	v_fmac_f32_e32 v17, v173, v18
	v_cvt_pk_bf16_f32 v17, v17, s0
	ds_write_b16 v1, v17 offset:6864
	v_lshlrev_b32_e32 v17, 16, v24
	v_lshlrev_b32_e32 v18, 16, v19
	v_fmac_f32_e32 v17, v174, v18
	v_cvt_pk_bf16_f32 v17, v17, s0
	ds_write_b16 v1, v17 offset:7136
	v_and_b32_e32 v17, 0xffff0000, v24
	v_and_b32_e32 v18, 0xffff0000, v19
	v_fmac_f32_e32 v17, v175, v18
	ds_read2st64_b32 v[18:19], v248 offset0:212 offset1:216
	v_cvt_pk_bf16_f32 v17, v17, s0
	ds_write_b16 v1, v17 offset:7408
	v_lshlrev_b32_e32 v17, 16, v16
	v_and_b32_e32 v16, 0xffff0000, v16
	s_waitcnt lgkmcnt(1)
	v_lshlrev_b32_e32 v20, 16, v18
	v_fmac_f32_e32 v17, v96, v20
	v_cvt_pk_bf16_f32 v17, v17, s0
	ds_write_b16 v1, v17 offset:8704
	v_and_b32_e32 v17, 0xffff0000, v18
	v_fmac_f32_e32 v16, v97, v17
	v_cvt_pk_bf16_f32 v16, v16, s0
	ds_write_b16 v1, v16 offset:8976
	v_lshlrev_b32_e32 v16, 16, v15
	v_lshlrev_b32_e32 v17, 16, v19
	v_fmac_f32_e32 v16, v98, v17
	v_cvt_pk_bf16_f32 v16, v16, s0
	ds_write_b16 v1, v16 offset:9248
	v_and_b32_e32 v15, 0xffff0000, v15
	v_and_b32_e32 v16, 0xffff0000, v19
	v_fmac_f32_e32 v15, v99, v16
	ds_read2st64_b32 v[16:17], v248 offset0:220 offset1:224
	v_cvt_pk_bf16_f32 v15, v15, s0
	ds_write_b16 v1, v15 offset:9520
	v_lshlrev_b32_e32 v15, 16, v14
	v_and_b32_e32 v14, 0xffff0000, v14
	s_waitcnt lgkmcnt(1)
	v_lshlrev_b32_e32 v18, 16, v16
	v_fmac_f32_e32 v15, v100, v18
	v_cvt_pk_bf16_f32 v15, v15, s0
	ds_write_b16 v1, v15 offset:10880
	v_and_b32_e32 v15, 0xffff0000, v16
	v_fmac_f32_e32 v14, v101, v15
	v_cvt_pk_bf16_f32 v14, v14, s0
	ds_write_b16 v1, v14 offset:11152
	v_lshlrev_b32_e32 v14, 16, v13
	v_lshlrev_b32_e32 v15, 16, v17
	v_fmac_f32_e32 v14, v102, v15
	v_cvt_pk_bf16_f32 v14, v14, s0
	ds_write_b16 v1, v14 offset:11424
	v_and_b32_e32 v13, 0xffff0000, v13
	v_and_b32_e32 v14, 0xffff0000, v17
	v_fmac_f32_e32 v13, v103, v14
	ds_read2st64_b32 v[14:15], v248 offset0:228 offset1:232
	v_cvt_pk_bf16_f32 v13, v13, s0
	ds_write_b16 v1, v13 offset:11696
	v_lshlrev_b32_e32 v13, 16, v12
	v_and_b32_e32 v12, 0xffff0000, v12
	s_waitcnt lgkmcnt(1)
	v_lshlrev_b32_e32 v16, 16, v14
	v_fmac_f32_e32 v13, v104, v16
	v_cvt_pk_bf16_f32 v13, v13, s0
	ds_write_b16 v1, v13 offset:13056
	v_and_b32_e32 v13, 0xffff0000, v14
	v_fmac_f32_e32 v12, v105, v13
	v_cvt_pk_bf16_f32 v12, v12, s0
	ds_write_b16 v1, v12 offset:13328
	v_lshlrev_b32_e32 v12, 16, v11
	v_lshlrev_b32_e32 v13, 16, v15
	v_fmac_f32_e32 v12, v106, v13
	v_cvt_pk_bf16_f32 v12, v12, s0
	ds_write_b16 v1, v12 offset:13600
	v_and_b32_e32 v11, 0xffff0000, v11
	v_and_b32_e32 v12, 0xffff0000, v15
	v_fmac_f32_e32 v11, v107, v12
	ds_read2st64_b32 v[12:13], v248 offset0:236 offset1:240
	v_cvt_pk_bf16_f32 v11, v11, s0
	ds_write_b16 v1, v11 offset:13872
	v_lshlrev_b32_e32 v11, 16, v10
	v_and_b32_e32 v10, 0xffff0000, v10
	s_waitcnt lgkmcnt(1)
; DEV u16 f2bf(float f) { return (u16)(pk2bf(f, 0.f) & 0xffffu); }
; DEV void tile_store(unsigned char* smem, u16* dst, size_t ldd) {
;   const u16* sC = (const u16*)smem;
;   __syncthreads();
;   const int tid_ = TIDX();
; #pragma unroll
;   for (int i = 0; i < 8; ++i) {
;     const int c = tid_ + 256 * i, row = c >> 4, cc = (c & 15) * 8;
;     __builtin_nontemporal_store(*(const bf16x8*)(sC + row * LDC + cc), (bf16x8*)(dst + (size_t)row * ldd + cc));
;   }
; }
; DEV void phase_p5(const Params& p, int l, unsigned char* smem) {
;     ...
;     acc_foreach([&](int mi, int ni, int r, int row, int col) __attribute__((always_inline)) {
;       const unsigned rq = res[mi][ni][r >> 1];
;       const float rv = __uint_as_float((r & 1) ? (rq & 0xffff0000u) : (rq << 16));
;       sC[row * LDC + col] = f2bf(rv + acc[mi][ni][r] * gate_b(mi, ni, r));
;     });
;     tile_store(smem, MRG + (size_t)mt * 128 * 1024 + nt * 128, 1024);
	v_lshlrev_b32_e32 v14, 16, v12
	v_fmac_f32_e32 v11, v108, v14
	v_cvt_pk_bf16_f32 v11, v11, s0
	ds_write_b16 v1, v11 offset:15232
	v_and_b32_e32 v11, 0xffff0000, v12
	v_fmac_f32_e32 v10, v109, v11
	v_cvt_pk_bf16_f32 v10, v10, s0
	ds_write_b16 v1, v10 offset:15504
	v_lshlrev_b32_e32 v10, 16, v9
	v_lshlrev_b32_e32 v11, 16, v13
	v_fmac_f32_e32 v10, v110, v11
	v_cvt_pk_bf16_f32 v10, v10, s0
	ds_write_b16 v1, v10 offset:15776
	v_and_b32_e32 v9, 0xffff0000, v9
	v_and_b32_e32 v10, 0xffff0000, v13
	v_fmac_f32_e32 v9, v111, v10
	ds_read2st64_b32 v[10:11], v248 offset0:244 offset1:248
	v_cvt_pk_bf16_f32 v9, v9, s0
	ds_write_b16 v1, v9 offset:16048
	v_lshlrev_b32_e32 v9, 16, v8
	v_and_b32_e32 v8, 0xffff0000, v8
	s_waitcnt lgkmcnt(1)
	v_lshlrev_b32_e32 v12, 16, v10
	v_fmac_f32_e32 v9, v64, v12
	v_cvt_pk_bf16_f32 v9, v9, s0
	ds_write_b16 v1, v9 offset:8768
	v_and_b32_e32 v9, 0xffff0000, v10
	v_fmac_f32_e32 v8, v65, v9
	v_cvt_pk_bf16_f32 v8, v8, s0
	ds_write_b16 v1, v8 offset:9040
	v_lshlrev_b32_e32 v8, 16, v7
	v_lshlrev_b32_e32 v9, 16, v11
	v_fmac_f32_e32 v8, v66, v9
	v_cvt_pk_bf16_f32 v8, v8, s0
	ds_write_b16 v1, v8 offset:9312
	v_and_b32_e32 v7, 0xffff0000, v7
	v_and_b32_e32 v8, 0xffff0000, v11
	v_fmac_f32_e32 v7, v67, v8
	ds_read_b32 v8, v248 offset:64512
	v_cvt_pk_bf16_f32 v7, v7, s0
	ds_write_b16 v1, v7 offset:9584
	v_lshlrev_b32_e32 v7, 16, v6
	v_and_b32_e32 v6, 0xffff0000, v6
	s_waitcnt lgkmcnt(1)
	v_lshlrev_b32_e32 v9, 16, v8
	v_fmac_f32_e32 v7, v68, v9
	v_cvt_pk_bf16_f32 v7, v7, s0
	ds_write_b16 v1, v7 offset:10944
	v_and_b32_e32 v7, 0xffff0000, v8
	v_fmac_f32_e32 v6, v69, v7
	v_cvt_pk_bf16_f32 v6, v6, s0
	ds_write_b16 v1, v6 offset:11216
	ds_read2st64_b32 v[6:7], v249 offset0:108 offset1:112
	v_lshlrev_b32_e32 v8, 16, v5
	v_and_b32_e32 v5, 0xffff0000, v5
	s_waitcnt lgkmcnt(0)
	v_lshlrev_b32_e32 v9, 16, v6
	v_and_b32_e32 v6, 0xffff0000, v6
	v_fmac_f32_e32 v5, v71, v6
	v_cvt_pk_bf16_f32 v5, v5, s0
	ds_write_b16 v1, v5 offset:11760
	v_lshlrev_b32_e32 v5, 16, v4
	v_lshlrev_b32_e32 v6, 16, v7
	v_fmac_f32_e32 v5, v72, v6
	v_cvt_pk_bf16_f32 v5, v5, s0
	ds_write_b16 v1, v5 offset:13120
	v_and_b32_e32 v4, 0xffff0000, v4
	v_and_b32_e32 v5, 0xffff0000, v7
	v_fmac_f32_e32 v4, v73, v5
	v_cvt_pk_bf16_f32 v4, v4, s0
	ds_write_b16 v1, v4 offset:13392
	ds_read2st64_b32 v[4:5], v249 offset0:116 offset1:120
	v_lshlrev_b32_e32 v6, 16, v3
	v_and_b32_e32 v3, 0xffff0000, v3
	v_fmac_f32_e32 v8, v70, v9
	v_cvt_pk_bf16_f32 v8, v8, s0
	s_waitcnt lgkmcnt(0)
	v_lshlrev_b32_e32 v7, 16, v4
	v_and_b32_e32 v4, 0xffff0000, v4
	v_fmac_f32_e32 v3, v75, v4
	v_cvt_pk_bf16_f32 v3, v3, s0
	ds_write_b16 v1, v3 offset:13936
	v_lshlrev_b32_e32 v3, 16, v2
	v_lshlrev_b32_e32 v4, 16, v5
	v_fmac_f32_e32 v3, v76, v4
	v_cvt_pk_bf16_f32 v3, v3, s0
	ds_write_b16 v1, v3 offset:15296
	v_and_b32_e32 v2, 0xffff0000, v2
	v_and_b32_e32 v3, 0xffff0000, v5
	v_fmac_f32_e32 v2, v77, v3
	ds_read_b32 v3, v249 offset:31744
	v_cvt_pk_bf16_f32 v2, v2, s0
	ds_write_b16 v1, v2 offset:15568
	v_lshlrev_b32_e32 v2, 16, v0
	v_and_b32_e32 v0, 0xffff0000, v0
	s_waitcnt lgkmcnt(1)
	v_lshlrev_b32_e32 v4, 16, v3
	v_fmac_f32_e32 v2, v78, v4
	v_cvt_pk_bf16_f32 v2, v2, s0
	ds_write_b16 v1, v2 offset:15840
	v_and_b32_e32 v2, 0xffff0000, v3
	v_fmac_f32_e32 v6, v74, v7
	v_fmac_f32_e32 v0, v79, v2
	v_cvt_pk_bf16_f32 v6, v6, s0
	v_cvt_pk_bf16_f32 v0, v0, s0
	s_add_u32 s0, s10, s0
	ds_write_b16 v1, v8 offset:11488
	s_addc_u32 s1, s11, s1
	s_lshl_b32 s19, s19, 8
	v_mov_b32_e32 v8, v232
	ds_write_b16 v1, v6 offset:13664
	ds_write_b16 v1, v0 offset:16112
	s_add_u32 s0, s0, s19
	s_waitcnt lgkmcnt(0)
	s_barrier
	s_addc_u32 s1, s1, 0
	v_lshlrev_b32_e32 v0, 4, v8
	v_and_b32_e32 v224, 0xf0, v0
	v_ashrrev_i32_e32 v6, 4, v8
	v_lshl_add_u64 v[4:5], s[0:1], 0, v[224:225]
	v_mad_u64_u32 v[0:1], s[0:1], v6, s42, v[224:225]
	ds_read_b128 v[0:3], v0
	v_ashrrev_i32_e32 v7, 31, v6
	v_lshlrev_b64 v[6:7], 11, v[6:7]
	v_lshl_add_u64 v[6:7], v[4:5], 0, v[6:7]
	s_add_i32 s18, s18, s34
	s_waitcnt lgkmcnt(0)
	global_store_dwordx4 v[6:7], v[0:3], off nt
	s_cmpk_lt_i32 s18, 0x1020
	s_nop 0
	v_add_u32_e32 v0, 0x100, v8
	v_ashrrev_i32_e32 v6, 4, v0
	v_mad_u64_u32 v[0:1], s[0:1], v6, s42, v[224:225]
	ds_read_b128 v[0:3], v0
	v_ashrrev_i32_e32 v7, 31, v6
	v_lshlrev_b64 v[6:7], 11, v[6:7]
	v_lshl_add_u64 v[6:7], v[4:5], 0, v[6:7]
	s_waitcnt lgkmcnt(0)
	global_store_dwordx4 v[6:7], v[0:3], off nt
	s_nop 1
	v_add_u32_e32 v0, 0x200, v8
	v_ashrrev_i32_e32 v6, 4, v0
	v_mad_u64_u32 v[0:1], s[0:1], v6, s42, v[224:225]
	ds_read_b128 v[0:3], v0
	v_ashrrev_i32_e32 v7, 31, v6
	v_lshlrev_b64 v[6:7], 11, v[6:7]
	v_lshl_add_u64 v[6:7], v[4:5], 0, v[6:7]
	s_waitcnt lgkmcnt(0)
	global_store_dwordx4 v[6:7], v[0:3], off nt
	s_nop 1
	v_add_u32_e32 v0, 0x300, v8
	v_ashrrev_i32_e32 v6, 4, v0
	v_mad_u64_u32 v[0:1], s[0:1], v6, s42, v[224:225]
	ds_read_b128 v[0:3], v0
	v_ashrrev_i32_e32 v7, 31, v6
	v_lshlrev_b64 v[6:7], 11, v[6:7]
	v_lshl_add_u64 v[6:7], v[4:5], 0, v[6:7]
	s_waitcnt lgkmcnt(0)
	global_store_dwordx4 v[6:7], v[0:3], off nt
	s_nop 1
	v_add_u32_e32 v0, 0x400, v8
	v_ashrrev_i32_e32 v6, 4, v0
	v_mad_u64_u32 v[0:1], s[0:1], v6, s42, v[224:225]
	ds_read_b128 v[0:3], v0
	v_ashrrev_i32_e32 v7, 31, v6
	v_lshlrev_b64 v[6:7], 11, v[6:7]
	v_lshl_add_u64 v[6:7], v[4:5], 0, v[6:7]
	s_waitcnt lgkmcnt(0)
	global_store_dwordx4 v[6:7], v[0:3], off nt
	s_nop 1
	v_add_u32_e32 v0, 0x500, v8
	v_ashrrev_i32_e32 v6, 4, v0
	v_mad_u64_u32 v[0:1], s[0:1], v6, s42, v[224:225]
	ds_read_b128 v[0:3], v0
	v_ashrrev_i32_e32 v7, 31, v6
	v_lshlrev_b64 v[6:7], 11, v[6:7]
	v_lshl_add_u64 v[6:7], v[4:5], 0, v[6:7]
	s_waitcnt lgkmcnt(0)
	global_store_dwordx4 v[6:7], v[0:3], off nt
	s_nop 1
	v_add_u32_e32 v0, 0x600, v8
	v_ashrrev_i32_e32 v6, 4, v0
	v_mad_u64_u32 v[0:1], s[0:1], v6, s42, v[224:225]
	ds_read_b128 v[0:3], v0
	v_ashrrev_i32_e32 v7, 31, v6
	v_lshlrev_b64 v[6:7], 11, v[6:7]
	v_lshl_add_u64 v[6:7], v[4:5], 0, v[6:7]
	s_waitcnt lgkmcnt(0)
	global_store_dwordx4 v[6:7], v[0:3], off nt
	s_nop 1
	v_add_u32_e32 v0, 0x700, v8
	v_ashrrev_i32_e32 v6, 4, v0
	v_mad_u64_u32 v[0:1], s[0:1], v6, s42, v[224:225]
	ds_read_b128 v[0:3], v0
	v_ashrrev_i32_e32 v7, 31, v6
	v_lshlrev_b64 v[6:7], 11, v[6:7]
	v_lshl_add_u64 v[4:5], v[4:5], 0, v[6:7]
	s_waitcnt lgkmcnt(0)
	global_store_dwordx4 v[4:5], v[0:3], off nt
	s_cbranch_scc0 .LBB0_1319

; DEV float sigmoidf_(float x) { return 1.0f / (1.0f + __expf(-x)); }
; DEV void gemm_gates(f32x16 (&acc)[2][4], const u16* __restrict__ A, const u16* __restrict__ B0, const u16* __restrict__ B1,
;                     unsigned char* smem) {
;     ...
;     for (int ks = 0; ks < 4; ++ks) {
;       bf16x8 af[2], bfr[4];
; #pragma unroll
;       for (int i = 0; i < 2; ++i) af[i] = *(const bf16x8*)(sA + (wm * 64 + i * 32) * LDT + fro + ks * 16);
; #pragma unroll
;       for (int i = 0; i < 4; ++i)
;         bfr[i] = *(const bf16x8*)(sB + ((i >> 1) * 128 + wn * 64 + (i & 1) * 32) * LDT + fro + ks * 16);
;       __builtin_amdgcn_s_setprio(1);
; #pragma unroll
;       for (int mi = 0; mi < 2; ++mi)
; #pragma unroll
;         for (int ni = 0; ni < 4; ++ni)
;           acc[mi][ni] = __builtin_amdgcn_mfma_f32_32x32x16_bf16(af[mi], bfr[ni], acc[mi][ni], 0, 0, 0);
;       __builtin_amdgcn_s_setprio(0);
;     }
;   }
; DEV void phase_p5(const Params& p, int l, unsigned char* smem) {
;     ...
;       for (int a_ = 0; a_ < 2; ++a_)
; #pragma unroll
;         for (int b_ = 0; b_ < 2; ++b_) {
; #pragma unroll
;           for (int r = 0; r < 8; ++r)
;             sG[((a_ * 2 + b_) * 8 + r) * 256 + tid] = pk2bf(sigmoidf_(g[a_][2 + b_][2 * r]), sigmoidf_(g[a_][2 + b_][2 * r + 1]));
;           __builtin_amdgcn_sched_barrier(0);
.LBB0_1309:
	v_add_u32_e32 v210, s36, v183
	v_add_u32_e32 v211, s36, v184
	ds_read_b128 v[186:189], v210
	ds_read_b128 v[190:193], v210 offset:4608
	ds_read_b128 v[194:197], v211
	ds_read_b128 v[198:201], v211 offset:4608
	ds_read_b128 v[202:205], v211 offset:18432
	ds_read_b128 v[206:209], v211 offset:23040
	s_setprio 1
	s_waitcnt lgkmcnt(3)
	v_mfma_f32_32x32x16_bf16 v[48:63], v[186:189], v[194:197], v[48:63]
	s_waitcnt lgkmcnt(2)
	v_mfma_f32_32x32x16_bf16 v[32:47], v[186:189], v[198:201], v[32:47]
	s_waitcnt lgkmcnt(1)
	v_mfma_f32_32x32x16_bf16 v[112:127], v[186:189], v[202:205], v[112:127]
	s_waitcnt lgkmcnt(0)
	v_mfma_f32_32x32x16_bf16 v[96:111], v[186:189], v[206:209], v[96:111]
	v_mfma_f32_32x32x16_bf16 v[16:31], v[190:193], v[194:197], v[16:31]
	v_mfma_f32_32x32x16_bf16 v[0:15], v[190:193], v[198:201], v[0:15]
	v_mfma_f32_32x32x16_bf16 v[80:95], v[190:193], v[202:205], v[80:95]
	v_mfma_f32_32x32x16_bf16 v[64:79], v[190:193], v[206:209], v[64:79]
	s_setprio 0
	ds_read_b128 v[186:189], v210 offset:32
	ds_read_b128 v[190:193], v210 offset:4640
	ds_read_b128 v[194:197], v211 offset:32
	ds_read_b128 v[198:201], v211 offset:4640
	ds_read_b128 v[202:205], v211 offset:18464
	ds_read_b128 v[206:209], v211 offset:23072
	s_setprio 1
	s_waitcnt lgkmcnt(3)
	v_mfma_f32_32x32x16_bf16 v[48:63], v[186:189], v[194:197], v[48:63]
	s_waitcnt lgkmcnt(2)
	v_mfma_f32_32x32x16_bf16 v[32:47], v[186:189], v[198:201], v[32:47]
	s_waitcnt lgkmcnt(1)
	v_mfma_f32_32x32x16_bf16 v[112:127], v[186:189], v[202:205], v[112:127]
	s_waitcnt lgkmcnt(0)
	v_mfma_f32_32x32x16_bf16 v[96:111], v[186:189], v[206:209], v[96:111]
	v_mfma_f32_32x32x16_bf16 v[16:31], v[190:193], v[194:197], v[16:31]
	v_mfma_f32_32x32x16_bf16 v[0:15], v[190:193], v[198:201], v[0:15]
	v_mfma_f32_32x32x16_bf16 v[80:95], v[190:193], v[202:205], v[80:95]
	v_mfma_f32_32x32x16_bf16 v[64:79], v[190:193], v[206:209], v[64:79]
	s_setprio 0
	s_add_i32 s36, s36, 64
	s_cmpk_eq_i32 s36, 0x80
	s_cbranch_scc0 .LBB0_1309
	s_add_i32 s21, s21, 1
	s_cmp_eq_u32 s21, 16
	s_cbranch_scc0 .LBB0_1306
	v_mul_f32_e32 v112, 0xbfb8aa3b, v112
	v_mul_f32_e32 v113, 0xbfb8aa3b, v113
	v_exp_f32_e32 v112, v112
	v_exp_f32_e32 v113, v113
	v_lshlrev_b32_e32 v248, 2, v182
	s_barrier
	s_lshl_b64 s[36:37], s[0:1], 1
	s_add_u32 s36, s8, s36
	s_addc_u32 s37, s9, s37
	s_lshl_b32 s38, s20, 1
	s_add_u32 s38, s14, s38
	s_addc_u32 s39, s15, 0
	v_ashrrev_i32_e32 v216, 3, v232
	v_ashrrev_i32_e32 v217, 31, v216
	v_lshlrev_b64 v[216:217], 11, v[216:217]
	v_lshlrev_b32_e32 v218, 4, v232
	v_and_b32_e32 v218, 0x70, v218
	v_mov_b32_e32 v219, 0
	v_lshl_add_u64 v[220:221], s[36:37], 0, v[216:217]
	v_lshl_add_u64 v[220:221], v[220:221], 0, v[218:219]
	v_lshl_add_u64 v[222:223], s[38:39], 0, v[216:217]
	v_lshl_add_u64 v[222:223], v[222:223], 0, v[218:219]
	global_load_dwordx4 v[184:187], v[220:221], off
	global_load_dwordx4 v[188:191], v[222:223], off
	v_add_co_u32_e32 v216, vcc, s35, v220
	s_nop 1
	v_addc_co_u32_e32 v217, vcc, 0, v221, vcc
	global_load_dwordx4 v[192:195], v[216:217], off
	v_add_co_u32_e32 v218, vcc, s35, v222
	s_nop 1
	v_addc_co_u32_e32 v219, vcc, 0, v223, vcc
	global_load_dwordx4 v[196:199], v[218:219], off
	v_add_co_u32_e32 v216, vcc, s33, v220
	s_nop 1
	v_addc_co_u32_e32 v217, vcc, 0, v221, vcc
	global_load_dwordx4 v[200:203], v[216:217], off
	v_add_co_u32_e32 v218, vcc, s33, v222
	s_nop 1
	v_addc_co_u32_e32 v219, vcc, 0, v223, vcc
	global_load_dwordx4 v[204:207], v[218:219], off
	v_add_co_u32_e32 v216, vcc, s40, v220
	s_nop 1
	v_addc_co_u32_e32 v217, vcc, 0, v221, vcc
	global_load_dwordx4 v[208:211], v[216:217], off
	v_add_co_u32_e32 v218, vcc, s40, v222
	s_nop 1
	v_addc_co_u32_e32 v219, vcc, 0, v223, vcc
	global_load_dwordx4 v[212:215], v[218:219], off
	v_pk_add_f32 v[112:113], v[112:113], 1.0 op_sel_hi:[1,0]
	s_waitcnt vmcnt(10)
	v_add_u32_e32 v249, 0x9400, v248
	s_waitcnt vmcnt(9)
	v_rcp_f32_e32 v113, v113
	s_nop 0
	s_nop 0
	v_rcp_f32_e32 v112, v112
	s_nop 0
	v_cvt_pk_bf16_f32 v128, v112, v113
	v_mul_f32_e32 v112, 0xbfb8aa3b, v114
	v_mul_f32_e32 v113, 0xbfb8aa3b, v115
	v_exp_f32_e32 v112, v112
	v_exp_f32_e32 v113, v113
	s_nop 0
	v_pk_add_f32 v[112:113], v[112:113], 1.0 op_sel_hi:[1,0]
	s_nop 0
	s_nop 0
	v_rcp_f32_e32 v113, v113
	s_nop 0
	s_nop 0
	v_rcp_f32_e32 v112, v112
	s_nop 0
	v_cvt_pk_bf16_f32 v112, v112, v113
	ds_write2st64_b32 v248, v128, v112 offset0:148 offset1:152
	v_mul_f32_e32 v112, 0xbfb8aa3b, v116
	v_mul_f32_e32 v113, 0xbfb8aa3b, v117
	v_exp_f32_e32 v112, v112
	v_exp_f32_e32 v113, v113
	s_nop 0
	v_pk_add_f32 v[112:113], v[112:113], 1.0 op_sel_hi:[1,0]
	s_nop 0
	s_nop 0
	v_rcp_f32_e32 v113, v113
	s_nop 0
	s_nop 0
	v_rcp_f32_e32 v112, v112
	s_nop 0
	v_cvt_pk_bf16_f32 v114, v112, v113
	v_mul_f32_e32 v112, 0xbfb8aa3b, v118
	v_mul_f32_e32 v113, 0xbfb8aa3b, v119
	v_exp_f32_e32 v112, v112
	v_exp_f32_e32 v113, v113
	s_nop 0
	v_pk_add_f32 v[112:113], v[112:113], 1.0 op_sel_hi:[1,0]
	s_nop 0
	s_nop 0
	v_rcp_f32_e32 v113, v113
	s_nop 0
	s_nop 0
	v_rcp_f32_e32 v112, v112
	s_nop 0
	v_cvt_pk_bf16_f32 v112, v112, v113
	ds_write2st64_b32 v248, v114, v112 offset0:156 offset1:160
	v_mul_f32_e32 v112, 0xbfb8aa3b, v120
	v_mul_f32_e32 v113, 0xbfb8aa3b, v121
	v_exp_f32_e32 v112, v112
	v_exp_f32_e32 v113, v113
	s_nop 0
	v_pk_add_f32 v[112:113], v[112:113], 1.0 op_sel_hi:[1,0]
	s_nop 0
	s_nop 0
	v_rcp_f32_e32 v113, v113
	s_nop 0
	s_nop 0
	v_rcp_f32_e32 v112, v112
	s_nop 0
	v_cvt_pk_bf16_f32 v114, v112, v113
	v_mul_f32_e32 v112, 0xbfb8aa3b, v122
	v_mul_f32_e32 v113, 0xbfb8aa3b, v123
	v_exp_f32_e32 v112, v112
	v_exp_f32_e32 v113, v113
	s_nop 0
	v_pk_add_f32 v[112:113], v[112:113], 1.0 op_sel_hi:[1,0]
	s_nop 0
	s_nop 0
	v_rcp_f32_e32 v113, v113
; DEV float sigmoidf_(float x) { return 1.0f / (1.0f + __expf(-x)); }
; DEV void phase_p5(const Params& p, int l, unsigned char* smem) {
;     ...
;       for (int a_ = 0; a_ < 2; ++a_)
; #pragma unroll
;         for (int b_ = 0; b_ < 2; ++b_) {
; #pragma unroll
;           for (int r = 0; r < 8; ++r)
;             sG[((a_ * 2 + b_) * 8 + r) * 256 + tid] = pk2bf(sigmoidf_(g[a_][2 + b_][2 * r]), sigmoidf_(g[a_][2 + b_][2 * r + 1]));
;           __builtin_amdgcn_sched_barrier(0);
	s_nop 0
	s_nop 0
	v_rcp_f32_e32 v112, v112
	s_nop 0
	v_cvt_pk_bf16_f32 v112, v112, v113
	ds_write2st64_b32 v248, v114, v112 offset0:164 offset1:168
	v_mul_f32_e32 v112, 0xbfb8aa3b, v124
	v_mul_f32_e32 v113, 0xbfb8aa3b, v125
	v_exp_f32_e32 v112, v112
	v_exp_f32_e32 v113, v113
	s_nop 0
	v_pk_add_f32 v[112:113], v[112:113], 1.0 op_sel_hi:[1,0]
	s_nop 0
	s_nop 0
	v_rcp_f32_e32 v113, v113
	s_nop 0
	s_nop 0
	v_rcp_f32_e32 v112, v112
	s_nop 0
	v_cvt_pk_bf16_f32 v114, v112, v113
	v_mul_f32_e32 v112, 0xbfb8aa3b, v126
	v_mul_f32_e32 v113, 0xbfb8aa3b, v127
	v_exp_f32_e32 v112, v112
	v_exp_f32_e32 v113, v113
	s_nop 0
	v_pk_add_f32 v[112:113], v[112:113], 1.0 op_sel_hi:[1,0]
	s_nop 0
	s_nop 0
	v_rcp_f32_e32 v113, v113
	s_nop 0
	s_nop 0
	v_rcp_f32_e32 v112, v112
	s_nop 0
	v_cvt_pk_bf16_f32 v112, v112, v113
	ds_write2st64_b32 v248, v114, v112 offset0:172 offset1:176
	v_mul_f32_e32 v96, 0xbfb8aa3b, v96
	v_mul_f32_e32 v97, 0xbfb8aa3b, v97
	v_exp_f32_e32 v96, v96
	v_exp_f32_e32 v97, v97
	s_nop 0
	v_pk_add_f32 v[96:97], v[96:97], 1.0 op_sel_hi:[1,0]
	s_nop 0
	s_nop 0
	v_rcp_f32_e32 v97, v97
	s_nop 0
	s_nop 0
	v_rcp_f32_e32 v96, v96
	s_nop 0
	v_cvt_pk_bf16_f32 v112, v96, v97
	v_mul_f32_e32 v96, 0xbfb8aa3b, v98
	v_mul_f32_e32 v97, 0xbfb8aa3b, v99
	v_exp_f32_e32 v96, v96
	v_exp_f32_e32 v97, v97
	s_nop 0
	v_pk_add_f32 v[96:97], v[96:97], 1.0 op_sel_hi:[1,0]
	s_nop 0
	s_nop 0
	v_rcp_f32_e32 v97, v97
	s_nop 0
	s_nop 0
	v_rcp_f32_e32 v96, v96
	s_nop 0
	v_cvt_pk_bf16_f32 v96, v96, v97
	ds_write2st64_b32 v248, v112, v96 offset0:180 offset1:184
	v_mul_f32_e32 v96, 0xbfb8aa3b, v100
	v_mul_f32_e32 v97, 0xbfb8aa3b, v101
	v_exp_f32_e32 v96, v96
	v_exp_f32_e32 v97, v97
	s_nop 0
	v_pk_add_f32 v[96:97], v[96:97], 1.0 op_sel_hi:[1,0]
	s_nop 0
	s_nop 0
	v_rcp_f32_e32 v97, v97
	s_nop 0
	s_nop 0
	v_rcp_f32_e32 v96, v96
	s_nop 0
	v_cvt_pk_bf16_f32 v98, v96, v97
	v_mul_f32_e32 v96, 0xbfb8aa3b, v102
	v_mul_f32_e32 v97, 0xbfb8aa3b, v103
	v_exp_f32_e32 v96, v96
	v_exp_f32_e32 v97, v97
	s_nop 0
	v_pk_add_f32 v[96:97], v[96:97], 1.0 op_sel_hi:[1,0]
	s_nop 0
	s_nop 0
	v_rcp_f32_e32 v97, v97
	s_nop 0
	s_nop 0
	v_rcp_f32_e32 v96, v96
	s_nop 0
	v_cvt_pk_bf16_f32 v96, v96, v97
	ds_write2st64_b32 v248, v98, v96 offset0:188 offset1:192
	v_mul_f32_e32 v96, 0xbfb8aa3b, v104
	v_mul_f32_e32 v97, 0xbfb8aa3b, v105
	v_exp_f32_e32 v96, v96
	v_exp_f32_e32 v97, v97
	s_nop 0
	v_pk_add_f32 v[96:97], v[96:97], 1.0 op_sel_hi:[1,0]
	s_nop 0
	s_nop 0
	v_rcp_f32_e32 v97, v97
	s_nop 0
	s_nop 0
	v_rcp_f32_e32 v96, v96
	s_nop 0
	v_cvt_pk_bf16_f32 v98, v96, v97
	v_mul_f32_e32 v96, 0xbfb8aa3b, v106
	v_mul_f32_e32 v97, 0xbfb8aa3b, v107
	v_exp_f32_e32 v96, v96
	v_exp_f32_e32 v97, v97
	s_nop 0
	v_pk_add_f32 v[96:97], v[96:97], 1.0 op_sel_hi:[1,0]
	s_nop 0
	s_nop 0
	v_rcp_f32_e32 v97, v97
	s_nop 0
	s_nop 0
	v_rcp_f32_e32 v96, v96
	s_nop 0
	v_cvt_pk_bf16_f32 v96, v96, v97
	ds_write2st64_b32 v248, v98, v96 offset0:196 offset1:200
	v_mul_f32_e32 v96, 0xbfb8aa3b, v108
	v_mul_f32_e32 v97, 0xbfb8aa3b, v109
	v_exp_f32_e32 v96, v96
	v_exp_f32_e32 v97, v97
	s_nop 0
	v_pk_add_f32 v[96:97], v[96:97], 1.0 op_sel_hi:[1,0]
	s_nop 0
	s_nop 0
	v_rcp_f32_e32 v97, v97
	s_nop 0
	s_nop 0
	v_rcp_f32_e32 v96, v96
	s_nop 0
	v_cvt_pk_bf16_f32 v98, v96, v97
	v_mul_f32_e32 v96, 0xbfb8aa3b, v110
	v_mul_f32_e32 v97, 0xbfb8aa3b, v111
	v_exp_f32_e32 v96, v96
	v_exp_f32_e32 v97, v97
	s_nop 0
	v_pk_add_f32 v[96:97], v[96:97], 1.0 op_sel_hi:[1,0]
	s_nop 0
	s_nop 0
	v_rcp_f32_e32 v97, v97
	s_nop 0
	s_nop 0
	v_rcp_f32_e32 v96, v96
	s_nop 0
	v_cvt_pk_bf16_f32 v96, v96, v97
	ds_write2st64_b32 v248, v98, v96 offset0:204 offset1:208
	v_mul_f32_e32 v80, 0xbfb8aa3b, v80
	v_mul_f32_e32 v81, 0xbfb8aa3b, v81
	v_exp_f32_e32 v80, v80
	v_exp_f32_e32 v81, v81
	s_nop 0
	v_pk_add_f32 v[80:81], v[80:81], 1.0 op_sel_hi:[1,0]
	s_nop 0
	s_nop 0
	v_rcp_f32_e32 v81, v81
	s_nop 0
	s_nop 0
	v_rcp_f32_e32 v80, v80
	s_nop 0
	v_cvt_pk_bf16_f32 v96, v80, v81
	v_mul_f32_e32 v80, 0xbfb8aa3b, v82
	v_mul_f32_e32 v81, 0xbfb8aa3b, v83
	v_exp_f32_e32 v80, v80
	v_exp_f32_e32 v81, v81
	s_nop 0
	v_pk_add_f32 v[80:81], v[80:81], 1.0 op_sel_hi:[1,0]
	s_nop 0
	s_nop 0
	v_rcp_f32_e32 v81, v81
	s_nop 0
	s_nop 0
	v_rcp_f32_e32 v80, v80
	s_nop 0
	v_cvt_pk_bf16_f32 v80, v80, v81
	ds_write2st64_b32 v248, v96, v80 offset0:212 offset1:216
	v_mul_f32_e32 v80, 0xbfb8aa3b, v84
	v_mul_f32_e32 v81, 0xbfb8aa3b, v85
	v_exp_f32_e32 v80, v80
	v_exp_f32_e32 v81, v81
	s_nop 0
	v_pk_add_f32 v[80:81], v[80:81], 1.0 op_sel_hi:[1,0]
	s_nop 0
	s_nop 0
	v_rcp_f32_e32 v81, v81
	s_nop 0
	s_nop 0
	v_rcp_f32_e32 v80, v80
	s_nop 0
	v_cvt_pk_bf16_f32 v82, v80, v81
	v_mul_f32_e32 v80, 0xbfb8aa3b, v86
	v_mul_f32_e32 v81, 0xbfb8aa3b, v87
	v_exp_f32_e32 v80, v80
	v_exp_f32_e32 v81, v81
	s_nop 0
	v_pk_add_f32 v[80:81], v[80:81], 1.0 op_sel_hi:[1,0]
	s_nop 0
	s_nop 0
	v_rcp_f32_e32 v81, v81
	s_nop 0
	s_nop 0
	v_rcp_f32_e32 v80, v80
	s_nop 0
	v_cvt_pk_bf16_f32 v80, v80, v81
	ds_write2st64_b32 v248, v82, v80 offset0:220 offset1:224
	v_mul_f32_e32 v80, 0xbfb8aa3b, v88
	v_mul_f32_e32 v81, 0xbfb8aa3b, v89
	v_exp_f32_e32 v80, v80
	v_exp_f32_e32 v81, v81
	s_nop 0
	v_pk_add_f32 v[80:81], v[80:81], 1.0 op_sel_hi:[1,0]
	s_nop 0
	s_nop 0
	v_rcp_f32_e32 v81, v81
	s_nop 0
	s_nop 0
	v_rcp_f32_e32 v80, v80
	s_nop 0
	v_cvt_pk_bf16_f32 v82, v80, v81
	v_mul_f32_e32 v80, 0xbfb8aa3b, v90
	v_mul_f32_e32 v81, 0xbfb8aa3b, v91
	v_exp_f32_e32 v80, v80
	v_exp_f32_e32 v81, v81
	s_nop 0
	v_pk_add_f32 v[80:81], v[80:81], 1.0 op_sel_hi:[1,0]
	s_nop 0
	s_nop 0
	v_rcp_f32_e32 v81, v81
	s_nop 0
	s_nop 0
	v_rcp_f32_e32 v80, v80
	s_nop 0
	v_cvt_pk_bf16_f32 v80, v80, v81
	ds_write2st64_b32 v248, v82, v80 offset0:228 offset1:232
	v_mul_f32_e32 v80, 0xbfb8aa3b, v92
; DEV float sigmoidf_(float x) { return 1.0f / (1.0f + __expf(-x)); }
;     ...
;   const int tid = TIDX(), lane = tid & 63, w = tid >> 6, wm = w >> 1, wn = w & 1;
;   const int srow = tid >> 3, scol = (tid & 7) * 8;
;   const u16* ap = A + (size_t)srow * lda + scol;
;   const u16* bp = B + (size_t)srow * ldb + scol;
; DEV void phase_p5(const Params& p, int l, unsigned char* smem) {
;     ...
; #pragma unroll
;       for (int a_ = 0; a_ < 2; ++a_)
; #pragma unroll
;         for (int b_ = 0; b_ < 2; ++b_) {
; #pragma unroll
;           for (int r = 0; r < 8; ++r)
;             sG[((a_ * 2 + b_) * 8 + r) * 256 + tid] = pk2bf(sigmoidf_(g[a_][2 + b_][2 * r]), sigmoidf_(g[a_][2 + b_][2 * r + 1]));
;           __builtin_amdgcn_sched_barrier(0);
;         }
	v_mul_f32_e32 v81, 0xbfb8aa3b, v93
	v_exp_f32_e32 v80, v80
	v_exp_f32_e32 v81, v81
	s_nop 0
	v_pk_add_f32 v[80:81], v[80:81], 1.0 op_sel_hi:[1,0]
	s_nop 0
	s_nop 0
	v_rcp_f32_e32 v81, v81
	s_nop 0
	s_nop 0
	v_rcp_f32_e32 v80, v80
	s_nop 0
	v_cvt_pk_bf16_f32 v82, v80, v81
	v_mul_f32_e32 v80, 0xbfb8aa3b, v94
	v_mul_f32_e32 v81, 0xbfb8aa3b, v95
	v_exp_f32_e32 v80, v80
	v_exp_f32_e32 v81, v81
	s_nop 0
	v_pk_add_f32 v[80:81], v[80:81], 1.0 op_sel_hi:[1,0]
	s_nop 0
	s_nop 0
	v_rcp_f32_e32 v81, v81
	s_nop 0
	s_nop 0
	v_rcp_f32_e32 v80, v80
	s_nop 0
	v_cvt_pk_bf16_f32 v80, v80, v81
	ds_write2st64_b32 v248, v82, v80 offset0:236 offset1:240
	v_mul_f32_e32 v64, 0xbfb8aa3b, v64
	v_mul_f32_e32 v65, 0xbfb8aa3b, v65
	v_exp_f32_e32 v64, v64
	v_exp_f32_e32 v65, v65
	s_nop 0
	v_pk_add_f32 v[64:65], v[64:65], 1.0 op_sel_hi:[1,0]
	s_nop 0
	s_nop 0
	v_rcp_f32_e32 v65, v65
	s_nop 0
	s_nop 0
	v_rcp_f32_e32 v64, v64
	s_nop 0
	v_cvt_pk_bf16_f32 v80, v64, v65
	v_mul_f32_e32 v64, 0xbfb8aa3b, v66
	v_mul_f32_e32 v65, 0xbfb8aa3b, v67
	v_exp_f32_e32 v64, v64
	v_exp_f32_e32 v65, v65
	s_nop 0
	v_pk_add_f32 v[64:65], v[64:65], 1.0 op_sel_hi:[1,0]
	s_nop 0
	s_nop 0
	v_rcp_f32_e32 v65, v65
	s_nop 0
	s_nop 0
	v_rcp_f32_e32 v64, v64
	s_nop 0
	v_cvt_pk_bf16_f32 v64, v64, v65
	ds_write2st64_b32 v248, v80, v64 offset0:244 offset1:248
	v_mul_f32_e32 v64, 0xbfb8aa3b, v68
	v_mul_f32_e32 v65, 0xbfb8aa3b, v69
	v_exp_f32_e32 v64, v64
	v_exp_f32_e32 v65, v65
	s_nop 0
	v_pk_add_f32 v[64:65], v[64:65], 1.0 op_sel_hi:[1,0]
	s_nop 0
	s_nop 0
	v_rcp_f32_e32 v65, v65
	s_nop 0
	s_nop 0
	v_rcp_f32_e32 v64, v64
	s_nop 0
	v_cvt_pk_bf16_f32 v64, v64, v65
	ds_write_b32 v248, v64 offset:64512
	v_mul_f32_e32 v64, 0xbfb8aa3b, v70
	v_mul_f32_e32 v65, 0xbfb8aa3b, v71
	v_exp_f32_e32 v64, v64
	v_exp_f32_e32 v65, v65
	s_nop 0
	v_pk_add_f32 v[64:65], v[64:65], 1.0 op_sel_hi:[1,0]
	s_nop 0
	s_nop 0
	v_rcp_f32_e32 v65, v65
	s_nop 0
	s_nop 0
	v_rcp_f32_e32 v64, v64
	s_nop 0
	v_cvt_pk_bf16_f32 v66, v64, v65
	v_mul_f32_e32 v64, 0xbfb8aa3b, v72
	v_mul_f32_e32 v65, 0xbfb8aa3b, v73
	v_exp_f32_e32 v64, v64
	v_exp_f32_e32 v65, v65
	s_nop 0
	v_pk_add_f32 v[64:65], v[64:65], 1.0 op_sel_hi:[1,0]
	s_nop 0
	s_nop 0
	v_rcp_f32_e32 v65, v65
	s_nop 0
	s_nop 0
	v_rcp_f32_e32 v64, v64
	s_nop 0
	v_cvt_pk_bf16_f32 v64, v64, v65
	ds_write2st64_b32 v249, v66, v64 offset0:108 offset1:112
	v_mul_f32_e32 v64, 0xbfb8aa3b, v74
	v_mul_f32_e32 v65, 0xbfb8aa3b, v75
	v_exp_f32_e32 v64, v64
	v_exp_f32_e32 v65, v65
	s_nop 0
	v_pk_add_f32 v[64:65], v[64:65], 1.0 op_sel_hi:[1,0]
	s_nop 0
	s_nop 0
	v_rcp_f32_e32 v65, v65
	s_nop 0
	s_nop 0
	v_rcp_f32_e32 v64, v64
	s_nop 0
	v_cvt_pk_bf16_f32 v66, v64, v65
	v_mul_f32_e32 v64, 0xbfb8aa3b, v76
	v_mul_f32_e32 v65, 0xbfb8aa3b, v77
	v_exp_f32_e32 v64, v64
	v_exp_f32_e32 v65, v65
	s_nop 0
	v_pk_add_f32 v[64:65], v[64:65], 1.0 op_sel_hi:[1,0]
	s_nop 0
	s_nop 0
	v_rcp_f32_e32 v65, v65
	s_nop 0
	s_nop 0
	v_rcp_f32_e32 v64, v64
	s_nop 0
	v_cvt_pk_bf16_f32 v64, v64, v65
	ds_write2st64_b32 v249, v66, v64 offset0:116 offset1:120
	v_mul_f32_e32 v64, 0xbfb8aa3b, v78
	v_mul_f32_e32 v65, 0xbfb8aa3b, v79
	v_exp_f32_e32 v64, v64
	v_exp_f32_e32 v65, v65
	s_nop 0
	v_pk_add_f32 v[64:65], v[64:65], 1.0 op_sel_hi:[1,0]
	s_nop 0
	s_nop 0
	v_rcp_f32_e32 v65, v65
	s_nop 0
	s_nop 0
	v_rcp_f32_e32 v64, v64
	s_nop 0
	v_cvt_pk_bf16_f32 v64, v64, v65
	ds_write_b32 v249, v64 offset:31744
	v_mov_b32_e32 v90, v232
	s_lshl_b64 s[0:1], s[0:1], 1
	s_add_u32 s36, s8, s0
	v_ashrrev_i32_e32 v80, 3, v90
	v_ashrrev_i32_e32 v81, 31, v80
	s_addc_u32 s37, s9, s1
	s_lshl_b32 s20, s20, 1
	v_lshlrev_b64 v[64:65], 11, v[80:81]
	v_lshlrev_b32_e32 v68, 4, v90
	s_add_u32 s38, s14, s20
	v_lshl_add_u64 v[66:67], s[36:37], 0, v[64:65]
	v_and_b32_e32 v224, 0x70, v68
	s_addc_u32 s39, s15, 0
	v_lshl_add_u64 v[82:83], v[66:67], 0, v[224:225]
	v_lshl_add_u64 v[64:65], s[38:39], 0, v[64:65]
	v_add_co_u32_e32 v72, vcc, s35, v82
	v_lshl_add_u64 v[84:85], v[64:65], 0, v[224:225]
	s_nop 0
	v_addc_co_u32_e32 v73, vcc, 0, v83, vcc
	v_add_co_u32_e32 v76, vcc, s35, v84
	s_waitcnt vmcnt(0)
;     ...
;   const int tid = TIDX(), lane = tid & 63, w = tid >> 6, wm = w >> 1, wn = w & 1;
;   const int srow = tid >> 3, scol = (tid & 7) * 8;
;   const u16* ap = A + (size_t)srow * lda + scol;
;   const u16* bp = B + (size_t)srow * ldb + scol;
;   bf16x8 ra[DEPTH][4], rb[DEPTH][4];
;   float ssq[4] = {0.f, 0.f, 0.f, 0.f};
;   const int nk = K >> 6;
; #pragma unroll
;   for (int d = 0; d < DEPTH; ++d)
; #pragma unroll
;     for (int i = 0; i < 4; ++i) {
;       ra[d][i] = *(const bf16x8*)(ap + d * 64 + (size_t)(32 * i) * lda);
;       rb[d][i] = *(const bf16x8*)(bp + d * 64 + (size_t)(32 * i) * ldb);
;     }
;   ap += DEPTH * 64;
;   bp += DEPTH * 64;
;   const int fro = (lane & 31) * LDT + (lane >> 5) * 8;
; DEV void zero_acc(f32x16 (&acc)[2][2]) {
; #pragma unroll
;   for (int a = 0; a < 2; ++a)
; #pragma unroll
;     for (int b = 0; b < 2; ++b)
; #pragma unroll
;       for (int r = 0; r < 16; ++r) acc[a][b][r] = 0.f;
; }
	v_mov_b32_e32 v64, v184
	v_mov_b32_e32 v65, v185
	v_mov_b32_e32 v66, v186
	v_mov_b32_e32 v67, v187
	v_mov_b32_e32 v68, v188
	v_mov_b32_e32 v69, v189
	v_mov_b32_e32 v70, v190
	v_mov_b32_e32 v71, v191
	v_addc_co_u32_e32 v77, vcc, 0, v85, vcc
	v_add_co_u32_e32 v86, vcc, s33, v82
	v_mov_b32_e32 v72, v192
	v_mov_b32_e32 v73, v193
	v_mov_b32_e32 v74, v194
	v_mov_b32_e32 v75, v195
	s_nop 0
	v_mov_b32_e32 v76, v196
	v_mov_b32_e32 v77, v197
	v_mov_b32_e32 v78, v198
	v_mov_b32_e32 v79, v199
	v_addc_co_u32_e32 v87, vcc, 0, v83, vcc
	v_add_co_u32_e32 v88, vcc, s33, v84
	s_waitcnt vmcnt(7)
	v_lshl_add_u64 v[160:161], v[82:83], 0, s[82:83]
	v_addc_co_u32_e32 v89, vcc, 0, v85, vcc
	v_mov_b32_e32 v96, v200
	v_mov_b32_e32 v97, v201
	v_mov_b32_e32 v98, v202
	v_mov_b32_e32 v99, v203
	v_mov_b32_e32 v100, v204
	v_mov_b32_e32 v101, v205
	v_mov_b32_e32 v102, v206
	v_mov_b32_e32 v103, v207
	v_add_co_u32_e32 v86, vcc, s40, v82
	v_lshl_add_u64 v[162:163], v[84:85], 0, s[82:83]
	s_nop 0
	v_addc_co_u32_e32 v87, vcc, 0, v83, vcc
	v_add_co_u32_e32 v88, vcc, s40, v84
	v_and_b32_e32 v82, 31, v90
	s_nop 0
	v_addc_co_u32_e32 v89, vcc, 0, v85, vcc
	v_mov_b32_e32 v104, v208
	v_mov_b32_e32 v105, v209
	v_mov_b32_e32 v106, v210
	v_mov_b32_e32 v107, v211
	v_mov_b32_e32 v108, v212
	v_mov_b32_e32 v109, v213
	v_mov_b32_e32 v110, v214
	v_mov_b32_e32 v111, v215
	v_lshrrev_b32_e32 v83, 2, v90
	v_lshrrev_b32_e32 v84, 1, v90
	v_and_b32_e32 v81, 64, v90
	v_mul_u32_u24_e32 v82, 0x48, v82
	v_and_b32_e32 v83, 8, v83
	v_and_b32_e32 v84, 0xfffffc0, v84
	v_add_lshl_u32 v82, v82, v83, 1
	s_waitcnt vmcnt(10)
	v_mad_u64_u32 v[164:165], s[36:37], v80, s49, v[224:225]
	v_mul_lo_u32 v83, v84, s49
	v_mul_u32_u24_e32 v81, 0x90, v81
	v_mov_b32_e32 v80, 0
	s_mov_b32 s21, 16
	v_add_u32_e32 v165, v82, v83
	v_add_u32_e32 v166, v82, v81
	v_mov_b32_e32 v81, v80
	v_mov_b32_e32 v82, v80
	v_mov_b32_e32 v83, v80
	v_mov_b32_e32 v84, v80
	v_mov_b32_e32 v85, v80
	v_mov_b32_e32 v86, v80
	v_mov_b32_e32 v87, v80
	v_mov_b32_e32 v88, v80
	v_mov_b32_e32 v89, v80
	v_mov_b32_e32 v90, v80
	v_mov_b32_e32 v91, v80
	v_mov_b32_e32 v92, v80
	v_mov_b32_e32 v93, v80
	v_mov_b32_e32 v94, v80
	v_mov_b32_e32 v95, v80
	v_mov_b32_e32 v112, v80
	v_mov_b32_e32 v113, v80
	v_mov_b32_e32 v114, v80
	v_mov_b32_e32 v115, v80
	v_mov_b32_e32 v116, v80
	v_mov_b32_e32 v117, v80
	v_mov_b32_e32 v118, v80
	v_mov_b32_e32 v119, v80
	v_mov_b32_e32 v120, v80
	v_mov_b32_e32 v121, v80
	v_mov_b32_e32 v122, v80
	v_mov_b32_e32 v123, v80
	v_mov_b32_e32 v124, v80
	v_mov_b32_e32 v125, v80
	v_mov_b32_e32 v126, v80
	v_mov_b32_e32 v127, v80
	v_mov_b32_e32 v128, v80
	v_mov_b32_e32 v129, v80
	v_mov_b32_e32 v130, v80
	v_mov_b32_e32 v131, v80
	v_mov_b32_e32 v132, v80
	v_mov_b32_e32 v133, v80
	v_mov_b32_e32 v134, v80
	v_mov_b32_e32 v135, v80
	v_mov_b32_e32 v136, v80
	v_mov_b32_e32 v137, v80
	v_mov_b32_e32 v138, v80
	v_mov_b32_e32 v139, v80
	v_mov_b32_e32 v140, v80
	v_mov_b32_e32 v141, v80
	v_mov_b32_e32 v142, v80
	v_mov_b32_e32 v143, v80
	v_mov_b32_e32 v144, v80
	v_mov_b32_e32 v145, v80
	v_mov_b32_e32 v146, v80
	v_mov_b32_e32 v147, v80
	v_mov_b32_e32 v148, v80
	v_mov_b32_e32 v149, v80
	v_mov_b32_e32 v150, v80
	v_mov_b32_e32 v151, v80
	v_mov_b32_e32 v152, v80
	v_mov_b32_e32 v153, v80
	v_mov_b32_e32 v154, v80
	v_mov_b32_e32 v155, v80
	v_mov_b32_e32 v156, v80
	v_mov_b32_e32 v157, v80
	v_mov_b32_e32 v158, v80
	v_mov_b32_e32 v159, v80
	s_branch .LBB0_1313
